# GEMM K-loops: no-op s_setprio 0/1 pair between the two MFMA clusters of each compute segment and the duplicate lgkmcnt(0) after the segment's opening barrier removed (13 loops)
# speedup vs baseline: 1.0049x; 1.0049x over previous
.LBB0_338:
	v_add_u32_e32 v138, s61, v1
	ds_read_b128 v[148:151], v138
	ds_read_b128 v[152:155], v138 offset:1024
	ds_read_b128 v[156:159], v138 offset:2048
	ds_read_b128 v[160:163], v138 offset:3072
	v_add_u32_e32 v138, s62, v1
	ds_read_b128 v[164:167], v138
	ds_read_b128 v[170:173], v138 offset:1024
	ds_read_b128 v[174:177], v138 offset:2048
	ds_read_b128 v[178:181], v138 offset:3072
	s_add_i32 s44, s4, 2
	s_add_u32 s45, s2, 0x80
	s_addc_u32 s5, s3, 0
	s_cmp_eq_u32 s54, s4
	s_cselect_b32 s4, s36, s45
	s_cselect_b32 s5, s37, s5
	s_cselect_b32 s49, s39, s43
	s_cselect_b32 s48, s38, s42
	v_lshl_add_u64 v[198:199], s[2:3], 0, v[140:141]
	s_add_i32 m0, s81, 0xc000
	ds_read_b128 v[182:185], v169
	ds_read_b128 v[186:189], v169 offset:1024
	ds_read_b128 v[190:193], v169 offset:2048
	ds_read_b128 v[194:197], v169 offset:3072
	ds_read_b128 v[202:205], v169 offset:4096
	ds_read_b128 v[206:209], v169 offset:5120
	ds_read_b128 v[210:213], v169 offset:6144
	ds_read_b128 v[214:217], v169 offset:7168
	global_load_lds_dwordx4 v[198:199], off
	v_lshl_add_u64 v[198:199], s[2:3], 0, v[142:143]
	s_add_i32 m0, s81, 0xe000
	s_nop 0
	global_load_lds_dwordx4 v[198:199], off
	s_waitcnt vmcnt(8)
	s_waitcnt lgkmcnt(0)
	s_barrier
	s_setprio 1
	v_mfma_i32_16x16x64_i8 v[126:129], v[148:151], v[182:185], v[126:129]
	v_mfma_i32_16x16x64_i8 v[122:125], v[156:159], v[182:185], v[122:125]
	v_mfma_i32_16x16x64_i8 v[118:121], v[148:151], v[190:193], v[118:121]
	v_mfma_i32_16x16x64_i8 v[114:117], v[156:159], v[190:193], v[114:117]
	v_mfma_i32_16x16x64_i8 v[106:109], v[148:151], v[202:205], v[106:109]
	v_mfma_i32_16x16x64_i8 v[98:101], v[156:159], v[202:205], v[98:101]
	v_mfma_i32_16x16x64_i8 v[90:93], v[148:151], v[210:213], v[90:93]
	v_mfma_i32_16x16x64_i8 v[82:85], v[156:159], v[210:213], v[82:85]
	v_mfma_i32_16x16x64_i8 v[126:129], v[152:155], v[186:189], v[126:129]
	v_mfma_i32_16x16x64_i8 v[122:125], v[160:163], v[186:189], v[122:125]
	v_mfma_i32_16x16x64_i8 v[118:121], v[152:155], v[194:197], v[118:121]
	v_mfma_i32_16x16x64_i8 v[114:117], v[160:163], v[194:197], v[114:117]
	v_mfma_i32_16x16x64_i8 v[106:109], v[152:155], v[206:209], v[106:109]
	v_mfma_i32_16x16x64_i8 v[98:101], v[160:163], v[206:209], v[98:101]
	v_mfma_i32_16x16x64_i8 v[90:93], v[152:155], v[214:217], v[90:93]
	v_mfma_i32_16x16x64_i8 v[82:85], v[160:163], v[214:217], v[82:85]
	v_mfma_i32_16x16x64_i8 v[110:113], v[164:167], v[182:185], v[110:113]
	v_mfma_i32_16x16x64_i8 v[102:105], v[174:177], v[182:185], v[102:105]
	v_mfma_i32_16x16x64_i8 v[94:97], v[164:167], v[190:193], v[94:97]
	v_mfma_i32_16x16x64_i8 v[86:89], v[174:177], v[190:193], v[86:89]
	v_mfma_i32_16x16x64_i8 v[78:81], v[164:167], v[202:205], v[78:81]
	v_mfma_i32_16x16x64_i8 v[74:77], v[174:177], v[202:205], v[74:77]
	v_mfma_i32_16x16x64_i8 v[70:73], v[164:167], v[210:213], v[70:73]
	v_mfma_i32_16x16x64_i8 v[66:69], v[174:177], v[210:213], v[66:69]
	v_mfma_i32_16x16x64_i8 v[110:113], v[170:173], v[186:189], v[110:113]
	v_mfma_i32_16x16x64_i8 v[102:105], v[178:181], v[186:189], v[102:105]
	v_mfma_i32_16x16x64_i8 v[94:97], v[170:173], v[194:197], v[94:97]
	v_mfma_i32_16x16x64_i8 v[86:89], v[178:181], v[194:197], v[86:89]
	v_mfma_i32_16x16x64_i8 v[78:81], v[170:173], v[206:209], v[78:81]
	v_mfma_i32_16x16x64_i8 v[74:77], v[178:181], v[206:209], v[74:77]
	v_mfma_i32_16x16x64_i8 v[70:73], v[170:173], v[214:217], v[70:73]
	v_mfma_i32_16x16x64_i8 v[66:69], v[178:181], v[214:217], v[66:69]
	s_setprio 0
	s_barrier
	s_add_i32 s45, s61, s67
	v_lshl_add_u64 v[198:199], s[48:49], 0, v[132:133]
	s_mov_b32 m0, s45
	ds_read_b128 v[182:185], v169 offset:16384
	ds_read_b128 v[186:189], v169 offset:17408
	ds_read_b128 v[190:193], v169 offset:18432
	ds_read_b128 v[194:197], v169 offset:19456
	ds_read_b128 v[202:205], v169 offset:20480
	ds_read_b128 v[206:209], v169 offset:21504
	ds_read_b128 v[210:213], v169 offset:22528
	ds_read_b128 v[214:217], v169 offset:23552
	global_load_lds_dwordx4 v[198:199], off
	s_add_i32 m0, s45, 0x2000
	v_lshl_add_u64 v[218:219], s[48:49], 0, v[136:137]
	s_add_u32 s48, s48, s16
	s_addc_u32 s49, s49, s17
	s_add_i32 s45, s62, s67
	global_load_lds_dwordx4 v[218:219], off
	v_lshl_add_u64 v[220:221], s[48:49], 0, v[132:133]
	s_mov_b32 m0, s45
	v_lshl_add_u64 v[222:223], s[48:49], 0, v[136:137]
	global_load_lds_dwordx4 v[220:221], off
	s_add_i32 m0, s45, 0x2000
	v_lshl_add_u64 v[224:225], s[4:5], 0, v[130:131]
	global_load_lds_dwordx4 v[222:223], off
	s_mov_b32 m0, s81
	v_lshl_add_u64 v[226:227], s[4:5], 0, v[134:135]
	global_load_lds_dwordx4 v[224:225], off
	s_mov_b32 m0, s90
	s_nop 0
	global_load_lds_dwordx4 v[226:227], off
	s_waitcnt vmcnt(8)
	s_waitcnt lgkmcnt(0)
	s_barrier
	s_setprio 1
	v_mfma_i32_16x16x64_i8 v[62:65], v[148:151], v[182:185], v[62:65]
	v_mfma_i32_16x16x64_i8 v[58:61], v[156:159], v[182:185], v[58:61]
	v_mfma_i32_16x16x64_i8 v[54:57], v[148:151], v[190:193], v[54:57]
	v_mfma_i32_16x16x64_i8 v[50:53], v[156:159], v[190:193], v[50:53]
	v_mfma_i32_16x16x64_i8 v[42:45], v[148:151], v[202:205], v[42:45]
	v_mfma_i32_16x16x64_i8 v[34:37], v[156:159], v[202:205], v[34:37]
	v_mfma_i32_16x16x64_i8 v[26:29], v[148:151], v[210:213], v[26:29]
	v_mfma_i32_16x16x64_i8 v[18:21], v[156:159], v[210:213], v[18:21]
	v_mfma_i32_16x16x64_i8 v[62:65], v[152:155], v[186:189], v[62:65]
	v_mfma_i32_16x16x64_i8 v[58:61], v[160:163], v[186:189], v[58:61]
	v_mfma_i32_16x16x64_i8 v[54:57], v[152:155], v[194:197], v[54:57]
	v_mfma_i32_16x16x64_i8 v[50:53], v[160:163], v[194:197], v[50:53]
	v_mfma_i32_16x16x64_i8 v[42:45], v[152:155], v[206:209], v[42:45]
	v_mfma_i32_16x16x64_i8 v[34:37], v[160:163], v[206:209], v[34:37]
	v_mfma_i32_16x16x64_i8 v[26:29], v[152:155], v[214:217], v[26:29]
	v_mfma_i32_16x16x64_i8 v[18:21], v[160:163], v[214:217], v[18:21]
	v_mfma_i32_16x16x64_i8 v[46:49], v[164:167], v[182:185], v[46:49]
	v_mfma_i32_16x16x64_i8 v[38:41], v[174:177], v[182:185], v[38:41]
	v_mfma_i32_16x16x64_i8 v[30:33], v[164:167], v[190:193], v[30:33]
	v_mfma_i32_16x16x64_i8 v[22:25], v[174:177], v[190:193], v[22:25]
	v_mfma_i32_16x16x64_i8 v[14:17], v[164:167], v[202:205], v[14:17]
	v_mfma_i32_16x16x64_i8 v[10:13], v[174:177], v[202:205], v[10:13]
	v_mfma_i32_16x16x64_i8 v[6:9], v[164:167], v[210:213], v[6:9]
	v_mfma_i32_16x16x64_i8 v[2:5], v[174:177], v[210:213], v[2:5]
	v_mfma_i32_16x16x64_i8 v[46:49], v[170:173], v[186:189], v[46:49]
	v_mfma_i32_16x16x64_i8 v[38:41], v[178:181], v[186:189], v[38:41]
	v_mfma_i32_16x16x64_i8 v[30:33], v[170:173], v[194:197], v[30:33]
	v_mfma_i32_16x16x64_i8 v[22:25], v[178:181], v[194:197], v[22:25]
	v_mfma_i32_16x16x64_i8 v[14:17], v[170:173], v[206:209], v[14:17]
	v_mfma_i32_16x16x64_i8 v[10:13], v[178:181], v[206:209], v[10:13]
	v_mfma_i32_16x16x64_i8 v[6:9], v[170:173], v[214:217], v[6:9]
	v_mfma_i32_16x16x64_i8 v[2:5], v[178:181], v[214:217], v[2:5]
	s_setprio 0
	s_barrier
	s_add_i32 s45, 0, 0x18000
	v_add_u32_e32 v138, s45, v1
	s_add_i32 s47, 0, 0x1c000
	ds_read_b128 v[148:151], v138
	ds_read_b128 v[152:155], v138 offset:1024
	ds_read_b128 v[156:159], v138 offset:2048
	ds_read_b128 v[160:163], v138 offset:3072
	v_add_u32_e32 v138, s47, v1
	ds_read_b128 v[164:167], v138
	ds_read_b128 v[170:173], v138 offset:1024
	ds_read_b128 v[174:177], v138 offset:2048
	ds_read_b128 v[178:181], v138 offset:3072
	s_add_u32 s4, s4, s16
	s_addc_u32 s5, s5, s17
	s_mov_b32 m0, s91
	v_lshl_add_u64 v[228:229], s[4:5], 0, v[130:131]
	ds_read_b128 v[182:185], v169 offset:32768
	ds_read_b128 v[186:189], v169 offset:33792
	ds_read_b128 v[190:193], v169 offset:34816
	ds_read_b128 v[194:197], v169 offset:35840
	ds_read_b128 v[202:205], v169 offset:36864
	ds_read_b128 v[206:209], v169 offset:37888
	ds_read_b128 v[210:213], v169 offset:38912
	ds_read_b128 v[214:217], v169 offset:39936
	global_load_lds_dwordx4 v[228:229], off
	v_lshl_add_u64 v[228:229], s[4:5], 0, v[134:135]
	s_mov_b32 m0, s92
	s_nop 0
	global_load_lds_dwordx4 v[228:229], off
	s_waitcnt vmcnt(8)
	s_waitcnt lgkmcnt(0)
	s_barrier
	s_setprio 1
	v_mfma_i32_16x16x64_i8 v[126:129], v[148:151], v[182:185], v[126:129]
	v_mfma_i32_16x16x64_i8 v[122:125], v[156:159], v[182:185], v[122:125]
	v_mfma_i32_16x16x64_i8 v[118:121], v[148:151], v[190:193], v[118:121]
	v_mfma_i32_16x16x64_i8 v[114:117], v[156:159], v[190:193], v[114:117]
	v_mfma_i32_16x16x64_i8 v[106:109], v[148:151], v[202:205], v[106:109]
	v_mfma_i32_16x16x64_i8 v[98:101], v[156:159], v[202:205], v[98:101]
	v_mfma_i32_16x16x64_i8 v[90:93], v[148:151], v[210:213], v[90:93]
	v_mfma_i32_16x16x64_i8 v[82:85], v[156:159], v[210:213], v[82:85]
	v_mfma_i32_16x16x64_i8 v[126:129], v[152:155], v[186:189], v[126:129]
	v_mfma_i32_16x16x64_i8 v[122:125], v[160:163], v[186:189], v[122:125]
	v_mfma_i32_16x16x64_i8 v[118:121], v[152:155], v[194:197], v[118:121]
	v_mfma_i32_16x16x64_i8 v[114:117], v[160:163], v[194:197], v[114:117]
	v_mfma_i32_16x16x64_i8 v[106:109], v[152:155], v[206:209], v[106:109]
	v_mfma_i32_16x16x64_i8 v[98:101], v[160:163], v[206:209], v[98:101]
	v_mfma_i32_16x16x64_i8 v[90:93], v[152:155], v[214:217], v[90:93]
	v_mfma_i32_16x16x64_i8 v[82:85], v[160:163], v[214:217], v[82:85]
	v_mfma_i32_16x16x64_i8 v[110:113], v[164:167], v[182:185], v[110:113]
	v_mfma_i32_16x16x64_i8 v[102:105], v[174:177], v[182:185], v[102:105]
	v_mfma_i32_16x16x64_i8 v[94:97], v[164:167], v[190:193], v[94:97]
	v_mfma_i32_16x16x64_i8 v[86:89], v[174:177], v[190:193], v[86:89]
	v_mfma_i32_16x16x64_i8 v[78:81], v[164:167], v[202:205], v[78:81]
	v_mfma_i32_16x16x64_i8 v[74:77], v[174:177], v[202:205], v[74:77]
	v_mfma_i32_16x16x64_i8 v[70:73], v[164:167], v[210:213], v[70:73]
	v_mfma_i32_16x16x64_i8 v[66:69], v[174:177], v[210:213], v[66:69]
	v_mfma_i32_16x16x64_i8 v[110:113], v[170:173], v[186:189], v[110:113]
	v_mfma_i32_16x16x64_i8 v[102:105], v[178:181], v[186:189], v[102:105]
	v_mfma_i32_16x16x64_i8 v[94:97], v[170:173], v[194:197], v[94:97]
	v_mfma_i32_16x16x64_i8 v[86:89], v[178:181], v[194:197], v[86:89]
	v_mfma_i32_16x16x64_i8 v[78:81], v[170:173], v[206:209], v[78:81]
	v_mfma_i32_16x16x64_i8 v[74:77], v[178:181], v[206:209], v[74:77]
	v_mfma_i32_16x16x64_i8 v[70:73], v[170:173], v[214:217], v[70:73]
	v_mfma_i32_16x16x64_i8 v[66:69], v[178:181], v[214:217], v[66:69]
	s_setprio 0
	s_barrier
	s_add_i32 s4, s45, s67
	v_lshl_add_u64 v[198:199], v[198:199], 0, s[26:27]
	s_mov_b32 m0, s4
	ds_read_b128 v[182:185], v169 offset:49152
	ds_read_b128 v[186:189], v169 offset:50176
	ds_read_b128 v[190:193], v169 offset:51200
	ds_read_b128 v[194:197], v169 offset:52224
	ds_read_b128 v[202:205], v169 offset:53248
	ds_read_b128 v[206:209], v169 offset:54272
	ds_read_b128 v[210:213], v169 offset:55296
	ds_read_b128 v[214:217], v169 offset:56320
	global_load_lds_dwordx4 v[198:199], off
	v_lshl_add_u64 v[198:199], v[218:219], 0, s[26:27]
	s_add_i32 m0, s4, 0x2000
	s_add_i32 s4, s47, s67
	global_load_lds_dwordx4 v[198:199], off
	v_lshl_add_u64 v[198:199], v[220:221], 0, s[26:27]
	s_mov_b32 m0, s4
	s_nop 0
	global_load_lds_dwordx4 v[198:199], off
	v_lshl_add_u64 v[198:199], v[222:223], 0, s[26:27]
	s_add_i32 m0, s4, 0x2000
	s_nop 0
	global_load_lds_dwordx4 v[198:199], off
	v_lshl_add_u64 v[198:199], v[224:225], 0, s[26:27]
	s_mov_b32 m0, s97
	s_nop 0
	global_load_lds_dwordx4 v[198:199], off
	v_lshl_add_u64 v[198:199], v[226:227], 0, s[26:27]
	s_mov_b32 m0, s6
	s_nop 0
	global_load_lds_dwordx4 v[198:199], off
	s_waitcnt vmcnt(8)
	s_waitcnt lgkmcnt(0)
	s_barrier
	s_setprio 1
	v_mfma_i32_16x16x64_i8 v[62:65], v[148:151], v[182:185], v[62:65]
	v_mfma_i32_16x16x64_i8 v[58:61], v[156:159], v[182:185], v[58:61]
	v_mfma_i32_16x16x64_i8 v[54:57], v[148:151], v[190:193], v[54:57]
	v_mfma_i32_16x16x64_i8 v[50:53], v[156:159], v[190:193], v[50:53]
	v_mfma_i32_16x16x64_i8 v[42:45], v[148:151], v[202:205], v[42:45]
	v_mfma_i32_16x16x64_i8 v[34:37], v[156:159], v[202:205], v[34:37]
	v_mfma_i32_16x16x64_i8 v[26:29], v[148:151], v[210:213], v[26:29]
	v_mfma_i32_16x16x64_i8 v[18:21], v[156:159], v[210:213], v[18:21]
	v_mfma_i32_16x16x64_i8 v[62:65], v[152:155], v[186:189], v[62:65]
	v_mfma_i32_16x16x64_i8 v[58:61], v[160:163], v[186:189], v[58:61]
	v_mfma_i32_16x16x64_i8 v[54:57], v[152:155], v[194:197], v[54:57]
	v_mfma_i32_16x16x64_i8 v[50:53], v[160:163], v[194:197], v[50:53]
	v_mfma_i32_16x16x64_i8 v[42:45], v[152:155], v[206:209], v[42:45]
	v_mfma_i32_16x16x64_i8 v[34:37], v[160:163], v[206:209], v[34:37]
	v_mfma_i32_16x16x64_i8 v[26:29], v[152:155], v[214:217], v[26:29]
	v_mfma_i32_16x16x64_i8 v[18:21], v[160:163], v[214:217], v[18:21]
	v_mfma_i32_16x16x64_i8 v[46:49], v[164:167], v[182:185], v[46:49]
	v_mfma_i32_16x16x64_i8 v[38:41], v[174:177], v[182:185], v[38:41]
	v_mfma_i32_16x16x64_i8 v[30:33], v[164:167], v[190:193], v[30:33]
	v_mfma_i32_16x16x64_i8 v[22:25], v[174:177], v[190:193], v[22:25]
	v_mfma_i32_16x16x64_i8 v[14:17], v[164:167], v[202:205], v[14:17]
	v_mfma_i32_16x16x64_i8 v[10:13], v[174:177], v[202:205], v[10:13]
	v_mfma_i32_16x16x64_i8 v[6:9], v[164:167], v[210:213], v[6:9]
	v_mfma_i32_16x16x64_i8 v[2:5], v[174:177], v[210:213], v[2:5]
	v_mfma_i32_16x16x64_i8 v[46:49], v[170:173], v[186:189], v[46:49]
	v_mfma_i32_16x16x64_i8 v[38:41], v[178:181], v[186:189], v[38:41]
	v_mfma_i32_16x16x64_i8 v[30:33], v[170:173], v[194:197], v[30:33]
	v_mfma_i32_16x16x64_i8 v[22:25], v[178:181], v[194:197], v[22:25]
	v_mfma_i32_16x16x64_i8 v[14:17], v[170:173], v[206:209], v[14:17]
	v_mfma_i32_16x16x64_i8 v[10:13], v[178:181], v[206:209], v[10:13]
	v_mfma_i32_16x16x64_i8 v[6:9], v[170:173], v[214:217], v[6:9]
	v_mfma_i32_16x16x64_i8 v[2:5], v[178:181], v[214:217], v[2:5]
	s_setprio 0
	s_barrier
	s_add_u32 s2, s2, 0x100
	s_addc_u32 s3, s3, 0
	s_add_u32 s42, s42, 0x100
	s_addc_u32 s43, s43, 0
	s_cmp_ge_i32 s44, s7
	s_mov_b32 s4, s44
	s_cbranch_scc0 .LBB0_338
	v_cvt_f32_i32_e32 v182, v126
	v_cvt_f32_i32_e32 v183, v127
	v_cvt_f32_i32_e32 v180, v128
	v_cvt_f32_i32_e32 v181, v129
	v_cvt_f32_i32_e32 v184, v122
	v_cvt_f32_i32_e32 v185, v123
	v_cvt_f32_i32_e32 v186, v124
	v_cvt_f32_i32_e32 v187, v125
	v_cvt_f32_i32_e32 v170, v110
	v_cvt_f32_i32_e32 v171, v111
	v_cvt_f32_i32_e32 v174, v112
	v_cvt_f32_i32_e32 v175, v113
	v_cvt_f32_i32_e32 v172, v102
	v_cvt_f32_i32_e32 v173, v103
	v_cvt_f32_i32_e32 v166, v104
	v_cvt_f32_i32_e32 v167, v105
	v_cvt_f32_i32_e32 v162, v118
	v_cvt_f32_i32_e32 v163, v119
	v_cvt_f32_i32_e32 v164, v120
	v_cvt_f32_i32_e32 v165, v121
	v_cvt_f32_i32_e32 v158, v114
	v_cvt_f32_i32_e32 v159, v115
	v_cvt_f32_i32_e32 v160, v116
	v_cvt_f32_i32_e32 v161, v117
	v_cvt_f32_i32_e32 v150, v94
	v_cvt_f32_i32_e32 v151, v95
	v_cvt_f32_i32_e32 v154, v96
	v_cvt_f32_i32_e32 v155, v97
	v_cvt_f32_i32_e32 v128, v86
	v_cvt_f32_i32_e32 v129, v87
	v_cvt_f32_i32_e32 v148, v88
	v_cvt_f32_i32_e32 v149, v89
	v_cvt_f32_i32_e32 v124, v106
	v_cvt_f32_i32_e32 v125, v107
	v_cvt_f32_i32_e32 v126, v108
	v_cvt_f32_i32_e32 v127, v109
	v_cvt_f32_i32_e32 v120, v98
	v_cvt_f32_i32_e32 v121, v99
	v_cvt_f32_i32_e32 v122, v100
	v_cvt_f32_i32_e32 v123, v101
	v_cvt_f32_i32_e32 v114, v78
	v_cvt_f32_i32_e32 v115, v79
	v_cvt_f32_i32_e32 v116, v80
	v_cvt_f32_i32_e32 v117, v81
	v_cvt_f32_i32_e32 v110, v74
	v_cvt_f32_i32_e32 v111, v75
	v_cvt_f32_i32_e32 v112, v76
	v_cvt_f32_i32_e32 v113, v77
	v_cvt_f32_i32_e32 v104, v90
	v_cvt_f32_i32_e32 v105, v91
	v_cvt_f32_i32_e32 v106, v92
	v_cvt_f32_i32_e32 v107, v93
	v_cvt_f32_i32_e32 v100, v82
	v_cvt_f32_i32_e32 v101, v83
	v_cvt_f32_i32_e32 v102, v84
	v_cvt_f32_i32_e32 v103, v85
	v_cvt_f32_i32_e32 v96, v70
	v_cvt_f32_i32_e32 v97, v71
	v_cvt_f32_i32_e32 v98, v72
	v_cvt_f32_i32_e32 v99, v73
	v_cvt_f32_i32_e32 v92, v66
	v_cvt_f32_i32_e32 v93, v67
	v_cvt_f32_i32_e32 v94, v68
	v_cvt_f32_i32_e32 v95, v69
	v_cvt_f32_i32_e32 v86, v62
	v_cvt_f32_i32_e32 v87, v63
	v_cvt_f32_i32_e32 v88, v64
	v_cvt_f32_i32_e32 v89, v65
	v_cvt_f32_i32_e32 v82, v58
	v_cvt_f32_i32_e32 v83, v59
	v_cvt_f32_i32_e32 v84, v60
	v_cvt_f32_i32_e32 v85, v61
	v_cvt_f32_i32_e32 v78, v46
	v_cvt_f32_i32_e32 v79, v47
	v_cvt_f32_i32_e32 v80, v48
	v_cvt_f32_i32_e32 v81, v49
	v_cvt_f32_i32_e32 v74, v38
	v_cvt_f32_i32_e32 v75, v39
	v_cvt_f32_i32_e32 v76, v40
	v_cvt_f32_i32_e32 v77, v41
	v_cvt_f32_i32_e32 v68, v54
	v_cvt_f32_i32_e32 v69, v55
	v_cvt_f32_i32_e32 v70, v56
	v_cvt_f32_i32_e32 v71, v57
	v_cvt_f32_i32_e32 v64, v50
	v_cvt_f32_i32_e32 v65, v51
	v_cvt_f32_i32_e32 v66, v52
	v_cvt_f32_i32_e32 v67, v53
	v_cvt_f32_i32_e32 v60, v30
	v_cvt_f32_i32_e32 v61, v31
	v_cvt_f32_i32_e32 v62, v32
	v_cvt_f32_i32_e32 v63, v33
	v_cvt_f32_i32_e32 v56, v22
	v_cvt_f32_i32_e32 v57, v23
	v_cvt_f32_i32_e32 v58, v24
	v_cvt_f32_i32_e32 v59, v25
	v_cvt_f32_i32_e32 v50, v42
	v_cvt_f32_i32_e32 v51, v43
	v_cvt_f32_i32_e32 v52, v44
	v_cvt_f32_i32_e32 v53, v45
	v_cvt_f32_i32_e32 v46, v34
	v_cvt_f32_i32_e32 v47, v35
	v_cvt_f32_i32_e32 v48, v36
	v_cvt_f32_i32_e32 v49, v37
	v_cvt_f32_i32_e32 v34, v14
	v_cvt_f32_i32_e32 v35, v15
	v_cvt_f32_i32_e32 v36, v16
	v_cvt_f32_i32_e32 v37, v17
	v_cvt_f32_i32_e32 v30, v10
	v_cvt_f32_i32_e32 v31, v11
	v_cvt_f32_i32_e32 v32, v12
	v_cvt_f32_i32_e32 v33, v13
	v_cvt_f32_i32_e32 v22, v26
	v_cvt_f32_i32_e32 v23, v27
	v_cvt_f32_i32_e32 v24, v28
	v_cvt_f32_i32_e32 v25, v29
	v_cvt_f32_i32_e32 v18, v18
	v_cvt_f32_i32_e32 v19, v19
	v_cvt_f32_i32_e32 v20, v20
	v_cvt_f32_i32_e32 v21, v21
	v_cvt_f32_i32_e32 v14, v6
	v_cvt_f32_i32_e32 v15, v7
	v_cvt_f32_i32_e32 v16, v8
	v_cvt_f32_i32_e32 v17, v9
	v_cvt_f32_i32_e32 v10, v2
	v_cvt_f32_i32_e32 v11, v3
	v_cvt_f32_i32_e32 v12, v4
	v_cvt_f32_i32_e32 v13, v5

.LBB0_549:
	ds_read_b128 v[148:151], v154
	ds_read_b128 v[158:161], v154 offset:1024
	ds_read_b128 v[162:165], v154 offset:2048
	ds_read_b128 v[170:173], v154 offset:3072
	ds_read_b128 v[174:177], v155
	ds_read_b128 v[178:181], v155 offset:1024
	ds_read_b128 v[182:185], v155 offset:2048
	ds_read_b128 v[186:189], v155 offset:3072
	s_add_u32 s64, s56, 0xfff00080
	s_addc_u32 s65, s57, -1
	s_cmp_eq_u32 s93, 60
	s_cselect_b32 s67, s45, s65
	s_cselect_b32 s66, s51, s64
	s_cselect_b32 s65, s43, s83
	s_cselect_b32 s64, s79, s82
	v_lshl_add_u64 v[152:153], s[56:57], 0, v[140:141]
	s_add_i32 m0, s7, 0xc000
	ds_read_b128 v[190:193], v156
	ds_read_b128 v[194:197], v156 offset:1024
	ds_read_b128 v[198:201], v156 offset:2048
	ds_read_b128 v[202:205], v156 offset:3072
	ds_read_b128 v[206:209], v156 offset:4096
	ds_read_b128 v[210:213], v156 offset:5120
	ds_read_b128 v[214:217], v156 offset:6144
	ds_read_b128 v[218:221], v156 offset:7168
	global_load_lds_dwordx4 v[152:153], off
	v_lshl_add_u64 v[152:153], s[56:57], 0, v[142:143]
	s_add_i32 m0, s7, 0xe000
	s_nop 0
	global_load_lds_dwordx4 v[152:153], off
	s_waitcnt vmcnt(8)
	s_waitcnt lgkmcnt(0)
	s_barrier
	s_setprio 1
	v_mfma_f32_16x16x32_bf16 v[126:129], v[148:151], v[190:193], v[126:129]
	v_mfma_f32_16x16x32_bf16 v[122:125], v[162:165], v[190:193], v[122:125]
	v_mfma_f32_16x16x32_bf16 v[118:121], v[148:151], v[198:201], v[118:121]
	v_mfma_f32_16x16x32_bf16 v[114:117], v[162:165], v[198:201], v[114:117]
	v_mfma_f32_16x16x32_bf16 v[102:105], v[148:151], v[206:209], v[102:105]
	v_mfma_f32_16x16x32_bf16 v[98:101], v[162:165], v[206:209], v[98:101]
	v_mfma_f32_16x16x32_bf16 v[86:89], v[148:151], v[214:217], v[86:89]
	v_mfma_f32_16x16x32_bf16 v[82:85], v[162:165], v[214:217], v[82:85]
	v_mfma_f32_16x16x32_bf16 v[126:129], v[158:161], v[194:197], v[126:129]
	v_mfma_f32_16x16x32_bf16 v[122:125], v[170:173], v[194:197], v[122:125]
	v_mfma_f32_16x16x32_bf16 v[118:121], v[158:161], v[202:205], v[118:121]
	v_mfma_f32_16x16x32_bf16 v[114:117], v[170:173], v[202:205], v[114:117]
	v_mfma_f32_16x16x32_bf16 v[102:105], v[158:161], v[210:213], v[102:105]
	v_mfma_f32_16x16x32_bf16 v[98:101], v[170:173], v[210:213], v[98:101]
	v_mfma_f32_16x16x32_bf16 v[86:89], v[158:161], v[218:221], v[86:89]
	v_mfma_f32_16x16x32_bf16 v[82:85], v[170:173], v[218:221], v[82:85]
	v_mfma_f32_16x16x32_bf16 v[110:113], v[174:177], v[190:193], v[110:113]
	v_mfma_f32_16x16x32_bf16 v[106:109], v[182:185], v[190:193], v[106:109]
	v_mfma_f32_16x16x32_bf16 v[94:97], v[174:177], v[198:201], v[94:97]
	v_mfma_f32_16x16x32_bf16 v[90:93], v[182:185], v[198:201], v[90:93]
	v_mfma_f32_16x16x32_bf16 v[78:81], v[174:177], v[206:209], v[78:81]
	v_mfma_f32_16x16x32_bf16 v[74:77], v[182:185], v[206:209], v[74:77]
	v_mfma_f32_16x16x32_bf16 v[70:73], v[174:177], v[214:217], v[70:73]
	v_mfma_f32_16x16x32_bf16 v[66:69], v[182:185], v[214:217], v[66:69]
	v_mfma_f32_16x16x32_bf16 v[110:113], v[178:181], v[194:197], v[110:113]
	v_mfma_f32_16x16x32_bf16 v[106:109], v[186:189], v[194:197], v[106:109]
	v_mfma_f32_16x16x32_bf16 v[94:97], v[178:181], v[202:205], v[94:97]
	v_mfma_f32_16x16x32_bf16 v[90:93], v[186:189], v[202:205], v[90:93]
	v_mfma_f32_16x16x32_bf16 v[78:81], v[178:181], v[210:213], v[78:81]
	v_mfma_f32_16x16x32_bf16 v[74:77], v[186:189], v[210:213], v[74:77]
	v_mfma_f32_16x16x32_bf16 v[70:73], v[178:181], v[218:221], v[70:73]
	v_mfma_f32_16x16x32_bf16 v[66:69], v[186:189], v[218:221], v[66:69]
	s_setprio 0
	s_barrier
	s_add_i32 s95, s71, s6
	v_lshl_add_u64 v[152:153], s[64:65], 0, v[132:133]
	s_mov_b32 m0, s95
	ds_read_b128 v[190:193], v156 offset:16384
	ds_read_b128 v[194:197], v156 offset:17408
	ds_read_b128 v[198:201], v156 offset:18432
	ds_read_b128 v[202:205], v156 offset:19456
	ds_read_b128 v[206:209], v156 offset:20480
	ds_read_b128 v[210:213], v156 offset:21504
	ds_read_b128 v[214:217], v156 offset:22528
	ds_read_b128 v[218:221], v156 offset:23552
	global_load_lds_dwordx4 v[152:153], off
	s_add_i32 m0, s95, 0x2000
	s_add_u32 vcc_lo, s64, 0x100000
	v_lshl_add_u64 v[166:167], s[64:65], 0, v[136:137]
	s_addc_u32 vcc_hi, s65, 0
	s_add_i32 s95, s72, s6
	global_load_lds_dwordx4 v[166:167], off
	v_lshl_add_u64 v[222:223], vcc, 0, v[132:133]
	s_mov_b32 m0, s95
	v_lshl_add_u64 v[224:225], s[66:67], 0, v[134:135]
	global_load_lds_dwordx4 v[222:223], off
	v_lshl_add_u64 v[222:223], vcc, 0, v[136:137]
	s_add_i32 m0, s95, 0x2000
	s_nop 0
	global_load_lds_dwordx4 v[222:223], off
	v_lshl_add_u64 v[222:223], s[66:67], 0, v[130:131]
	s_mov_b32 m0, s7
	s_nop 0
	global_load_lds_dwordx4 v[222:223], off
	s_mov_b32 m0, s52
	s_nop 0
	global_load_lds_dwordx4 v[224:225], off
	s_waitcnt vmcnt(8)
	s_waitcnt lgkmcnt(0)
	s_barrier
	s_setprio 1
	v_mfma_f32_16x16x32_bf16 v[62:65], v[148:151], v[190:193], v[62:65]
	v_mfma_f32_16x16x32_bf16 v[58:61], v[162:165], v[190:193], v[58:61]
	v_mfma_f32_16x16x32_bf16 v[54:57], v[148:151], v[198:201], v[54:57]
	v_mfma_f32_16x16x32_bf16 v[50:53], v[162:165], v[198:201], v[50:53]
	v_mfma_f32_16x16x32_bf16 v[38:41], v[148:151], v[206:209], v[38:41]
	v_mfma_f32_16x16x32_bf16 v[34:37], v[162:165], v[206:209], v[34:37]
	v_mfma_f32_16x16x32_bf16 v[22:25], v[148:151], v[214:217], v[22:25]
	v_mfma_f32_16x16x32_bf16 v[18:21], v[162:165], v[214:217], v[18:21]
	v_mfma_f32_16x16x32_bf16 v[62:65], v[158:161], v[194:197], v[62:65]
	v_mfma_f32_16x16x32_bf16 v[58:61], v[170:173], v[194:197], v[58:61]
	v_mfma_f32_16x16x32_bf16 v[54:57], v[158:161], v[202:205], v[54:57]
	v_mfma_f32_16x16x32_bf16 v[50:53], v[170:173], v[202:205], v[50:53]
	v_mfma_f32_16x16x32_bf16 v[38:41], v[158:161], v[210:213], v[38:41]
	v_mfma_f32_16x16x32_bf16 v[34:37], v[170:173], v[210:213], v[34:37]
	v_mfma_f32_16x16x32_bf16 v[22:25], v[158:161], v[218:221], v[22:25]
	v_mfma_f32_16x16x32_bf16 v[18:21], v[170:173], v[218:221], v[18:21]
	v_mfma_f32_16x16x32_bf16 v[46:49], v[174:177], v[190:193], v[46:49]
	v_mfma_f32_16x16x32_bf16 v[42:45], v[182:185], v[190:193], v[42:45]
	v_mfma_f32_16x16x32_bf16 v[30:33], v[174:177], v[198:201], v[30:33]
	v_mfma_f32_16x16x32_bf16 v[26:29], v[182:185], v[198:201], v[26:29]
	v_mfma_f32_16x16x32_bf16 v[14:17], v[174:177], v[206:209], v[14:17]
	v_mfma_f32_16x16x32_bf16 v[10:13], v[182:185], v[206:209], v[10:13]
	v_mfma_f32_16x16x32_bf16 v[6:9], v[174:177], v[214:217], v[6:9]
	v_mfma_f32_16x16x32_bf16 v[2:5], v[182:185], v[214:217], v[2:5]
	v_mfma_f32_16x16x32_bf16 v[46:49], v[178:181], v[194:197], v[46:49]
	v_mfma_f32_16x16x32_bf16 v[42:45], v[186:189], v[194:197], v[42:45]
	v_mfma_f32_16x16x32_bf16 v[30:33], v[178:181], v[202:205], v[30:33]
	v_mfma_f32_16x16x32_bf16 v[26:29], v[186:189], v[202:205], v[26:29]
	v_mfma_f32_16x16x32_bf16 v[14:17], v[178:181], v[210:213], v[14:17]
	v_mfma_f32_16x16x32_bf16 v[10:13], v[186:189], v[210:213], v[10:13]
	v_mfma_f32_16x16x32_bf16 v[6:9], v[178:181], v[218:221], v[6:9]
	v_mfma_f32_16x16x32_bf16 v[2:5], v[186:189], v[218:221], v[2:5]
	s_setprio 0
	s_barrier
	s_add_i32 s95, 0, 0x18000
	v_add_u32_e32 v138, s95, v1
	s_add_i32 s97, 0, 0x1c000
	ds_read_b128 v[148:151], v138
	ds_read_b128 v[158:161], v138 offset:1024
	ds_read_b128 v[162:165], v138 offset:2048
	ds_read_b128 v[170:173], v138 offset:3072
	v_add_u32_e32 v138, s97, v1
	ds_read_b128 v[174:177], v138
	ds_read_b128 v[178:181], v138 offset:1024
	ds_read_b128 v[182:185], v138 offset:2048
	ds_read_b128 v[186:189], v138 offset:3072
	s_add_u32 s66, s66, 0x100000
	s_addc_u32 s67, s67, 0
	s_mov_b32 m0, s53
	v_lshl_add_u64 v[226:227], s[66:67], 0, v[130:131]
	ds_read_b128 v[190:193], v156 offset:32768
	ds_read_b128 v[194:197], v156 offset:33792
	ds_read_b128 v[198:201], v156 offset:34816
	ds_read_b128 v[202:205], v156 offset:35840
	ds_read_b128 v[206:209], v156 offset:36864
	ds_read_b128 v[210:213], v156 offset:37888
	ds_read_b128 v[214:217], v156 offset:38912
	ds_read_b128 v[218:221], v156 offset:39936
	global_load_lds_dwordx4 v[226:227], off
	v_lshl_add_u64 v[226:227], s[66:67], 0, v[134:135]
	s_mov_b32 m0, s54
	s_nop 0
	global_load_lds_dwordx4 v[226:227], off
	s_waitcnt vmcnt(8)
	s_waitcnt lgkmcnt(0)
	s_barrier
	s_setprio 1
	v_mfma_f32_16x16x32_bf16 v[126:129], v[148:151], v[190:193], v[126:129]
	v_mfma_f32_16x16x32_bf16 v[122:125], v[162:165], v[190:193], v[122:125]
	v_mfma_f32_16x16x32_bf16 v[118:121], v[148:151], v[198:201], v[118:121]
	v_mfma_f32_16x16x32_bf16 v[114:117], v[162:165], v[198:201], v[114:117]
	v_mfma_f32_16x16x32_bf16 v[102:105], v[148:151], v[206:209], v[102:105]
	v_mfma_f32_16x16x32_bf16 v[98:101], v[162:165], v[206:209], v[98:101]
	v_mfma_f32_16x16x32_bf16 v[86:89], v[148:151], v[214:217], v[86:89]
	v_mfma_f32_16x16x32_bf16 v[82:85], v[162:165], v[214:217], v[82:85]
	v_mfma_f32_16x16x32_bf16 v[126:129], v[158:161], v[194:197], v[126:129]
	v_mfma_f32_16x16x32_bf16 v[122:125], v[170:173], v[194:197], v[122:125]
	v_mfma_f32_16x16x32_bf16 v[118:121], v[158:161], v[202:205], v[118:121]
	v_mfma_f32_16x16x32_bf16 v[114:117], v[170:173], v[202:205], v[114:117]
	v_mfma_f32_16x16x32_bf16 v[102:105], v[158:161], v[210:213], v[102:105]
	v_mfma_f32_16x16x32_bf16 v[98:101], v[170:173], v[210:213], v[98:101]
	v_mfma_f32_16x16x32_bf16 v[86:89], v[158:161], v[218:221], v[86:89]
	v_mfma_f32_16x16x32_bf16 v[82:85], v[170:173], v[218:221], v[82:85]
	v_mfma_f32_16x16x32_bf16 v[110:113], v[174:177], v[190:193], v[110:113]
	v_mfma_f32_16x16x32_bf16 v[106:109], v[182:185], v[190:193], v[106:109]
	v_mfma_f32_16x16x32_bf16 v[94:97], v[174:177], v[198:201], v[94:97]
	v_mfma_f32_16x16x32_bf16 v[90:93], v[182:185], v[198:201], v[90:93]
	v_mfma_f32_16x16x32_bf16 v[78:81], v[174:177], v[206:209], v[78:81]
	v_mfma_f32_16x16x32_bf16 v[74:77], v[182:185], v[206:209], v[74:77]
	v_mfma_f32_16x16x32_bf16 v[70:73], v[174:177], v[214:217], v[70:73]
	v_mfma_f32_16x16x32_bf16 v[66:69], v[182:185], v[214:217], v[66:69]
	v_mfma_f32_16x16x32_bf16 v[110:113], v[178:181], v[194:197], v[110:113]
	v_mfma_f32_16x16x32_bf16 v[106:109], v[186:189], v[194:197], v[106:109]
	v_mfma_f32_16x16x32_bf16 v[94:97], v[178:181], v[202:205], v[94:97]
	v_mfma_f32_16x16x32_bf16 v[90:93], v[186:189], v[202:205], v[90:93]
	v_mfma_f32_16x16x32_bf16 v[78:81], v[178:181], v[210:213], v[78:81]
	v_mfma_f32_16x16x32_bf16 v[74:77], v[186:189], v[210:213], v[74:77]
	v_mfma_f32_16x16x32_bf16 v[70:73], v[178:181], v[218:221], v[70:73]
	v_mfma_f32_16x16x32_bf16 v[66:69], v[186:189], v[218:221], v[66:69]
	s_setprio 0
	s_barrier
	s_add_i32 s66, s95, s6
	v_lshl_add_u64 v[152:153], v[152:153], 0, s[24:25]
	s_mov_b32 m0, s66
	ds_read_b128 v[190:193], v156 offset:49152
	ds_read_b128 v[194:197], v156 offset:50176
	ds_read_b128 v[198:201], v156 offset:51200
	ds_read_b128 v[202:205], v156 offset:52224
	ds_read_b128 v[206:209], v156 offset:53248
	ds_read_b128 v[210:213], v156 offset:54272
	ds_read_b128 v[214:217], v156 offset:55296
	ds_read_b128 v[218:221], v156 offset:56320
	global_load_lds_dwordx4 v[152:153], off
	s_add_i32 m0, s66, 0x2000
	s_add_u32 s64, s64, 0x100080
	v_lshl_add_u64 v[152:153], v[166:167], 0, s[24:25]
	s_addc_u32 s65, s65, 0
	s_add_i32 s66, s97, s6
	global_load_lds_dwordx4 v[152:153], off
	v_lshl_add_u64 v[152:153], s[64:65], 0, v[132:133]
	s_mov_b32 m0, s66
	s_nop 0
	global_load_lds_dwordx4 v[152:153], off
	v_lshl_add_u64 v[152:153], s[64:65], 0, v[136:137]
	s_add_i32 m0, s66, 0x2000
	s_nop 0
	global_load_lds_dwordx4 v[152:153], off
	v_lshl_add_u64 v[152:153], v[222:223], 0, s[24:25]
	s_mov_b32 m0, s63
	s_nop 0
	global_load_lds_dwordx4 v[152:153], off
	v_lshl_add_u64 v[152:153], v[224:225], 0, s[24:25]
	s_mov_b32 m0, s68
	s_nop 0
	global_load_lds_dwordx4 v[152:153], off
	s_waitcnt vmcnt(8)
	s_waitcnt lgkmcnt(0)
	s_barrier
	s_setprio 1
	v_mfma_f32_16x16x32_bf16 v[62:65], v[148:151], v[190:193], v[62:65]
	v_mfma_f32_16x16x32_bf16 v[58:61], v[162:165], v[190:193], v[58:61]
	v_mfma_f32_16x16x32_bf16 v[54:57], v[148:151], v[198:201], v[54:57]
	v_mfma_f32_16x16x32_bf16 v[50:53], v[162:165], v[198:201], v[50:53]
	v_mfma_f32_16x16x32_bf16 v[38:41], v[148:151], v[206:209], v[38:41]
	v_mfma_f32_16x16x32_bf16 v[34:37], v[162:165], v[206:209], v[34:37]
	v_mfma_f32_16x16x32_bf16 v[22:25], v[148:151], v[214:217], v[22:25]
	v_mfma_f32_16x16x32_bf16 v[18:21], v[162:165], v[214:217], v[18:21]
	v_mfma_f32_16x16x32_bf16 v[62:65], v[158:161], v[194:197], v[62:65]
	v_mfma_f32_16x16x32_bf16 v[58:61], v[170:173], v[194:197], v[58:61]
	v_mfma_f32_16x16x32_bf16 v[54:57], v[158:161], v[202:205], v[54:57]
	v_mfma_f32_16x16x32_bf16 v[50:53], v[170:173], v[202:205], v[50:53]
	v_mfma_f32_16x16x32_bf16 v[38:41], v[158:161], v[210:213], v[38:41]
	v_mfma_f32_16x16x32_bf16 v[34:37], v[170:173], v[210:213], v[34:37]
	v_mfma_f32_16x16x32_bf16 v[22:25], v[158:161], v[218:221], v[22:25]
	v_mfma_f32_16x16x32_bf16 v[18:21], v[170:173], v[218:221], v[18:21]
	v_mfma_f32_16x16x32_bf16 v[46:49], v[174:177], v[190:193], v[46:49]
	v_mfma_f32_16x16x32_bf16 v[42:45], v[182:185], v[190:193], v[42:45]
	v_mfma_f32_16x16x32_bf16 v[30:33], v[174:177], v[198:201], v[30:33]
	v_mfma_f32_16x16x32_bf16 v[26:29], v[182:185], v[198:201], v[26:29]
	v_mfma_f32_16x16x32_bf16 v[14:17], v[174:177], v[206:209], v[14:17]
	v_mfma_f32_16x16x32_bf16 v[10:13], v[182:185], v[206:209], v[10:13]
	v_mfma_f32_16x16x32_bf16 v[6:9], v[174:177], v[214:217], v[6:9]
	v_mfma_f32_16x16x32_bf16 v[2:5], v[182:185], v[214:217], v[2:5]
	v_mfma_f32_16x16x32_bf16 v[46:49], v[178:181], v[194:197], v[46:49]
	v_mfma_f32_16x16x32_bf16 v[42:45], v[186:189], v[194:197], v[42:45]
	v_mfma_f32_16x16x32_bf16 v[30:33], v[178:181], v[202:205], v[30:33]
	v_mfma_f32_16x16x32_bf16 v[26:29], v[186:189], v[202:205], v[26:29]
	v_mfma_f32_16x16x32_bf16 v[14:17], v[178:181], v[210:213], v[14:17]
	v_mfma_f32_16x16x32_bf16 v[10:13], v[186:189], v[210:213], v[10:13]
	v_mfma_f32_16x16x32_bf16 v[6:9], v[178:181], v[218:221], v[6:9]
	v_mfma_f32_16x16x32_bf16 v[2:5], v[186:189], v[218:221], v[2:5]
	s_setprio 0
	s_barrier
	s_add_i32 s93, s93, 2
	s_add_u32 s56, s56, 0x100
	s_addc_u32 s57, s57, 0
	s_add_u32 s82, s82, 0x100
	s_addc_u32 s83, s83, 0
	s_cmp_gt_u32 s93, 61
	s_cbranch_scc0 .LBB0_549
	s_and_b64 vcc, exec, s[26:27]
	s_cbranch_vccz .LBB0_552
	s_barrier

.LBB0_736:
	ds_read_b128 v[118:121], v164
	ds_read_b128 v[122:125], v164 offset:1024
	ds_read_b128 v[138:141], v164 offset:2048
	ds_read_b128 v[142:145], v164 offset:3072
	ds_read_b128 v[160:163], v165
	ds_read_b128 v[170:173], v165 offset:1024
	ds_read_b128 v[174:177], v165 offset:2048
	ds_read_b128 v[178:181], v165 offset:3072
	s_add_i32 s58, s22, 2
	s_add_u32 s59, s20, 0x80
	s_addc_u32 s23, s21, 0
	s_cmp_eq_u32 s47, s22
	s_cselect_b32 s22, s16, s59
	s_cselect_b32 s23, s17, s23
	s_cselect_b32 s61, s19, s57
	s_cselect_b32 s60, s18, s56
	v_lshl_add_u64 v[214:215], s[20:21], 0, v[156:157]
	s_add_i32 m0, s29, 0xc000
	ds_read_b128 v[182:185], v166
	ds_read_b128 v[186:189], v166 offset:1024
	ds_read_b128 v[190:193], v166 offset:2048
	ds_read_b128 v[194:197], v166 offset:3072
	ds_read_b128 v[198:201], v166 offset:4096
	ds_read_b128 v[202:205], v166 offset:5120
	ds_read_b128 v[206:209], v166 offset:6144
	ds_read_b128 v[210:213], v166 offset:7168
	global_load_lds_dwordx4 v[214:215], off
	v_lshl_add_u64 v[214:215], s[20:21], 0, v[158:159]
	s_add_i32 m0, s29, 0xe000
	s_nop 0
	global_load_lds_dwordx4 v[214:215], off
	s_waitcnt vmcnt(8)
	s_waitcnt lgkmcnt(0)
	s_barrier
	s_setprio 1
	v_mfma_f32_16x16x32_bf16 v[134:137], v[118:121], v[182:185], v[134:137]
	v_mfma_f32_16x16x32_bf16 v[130:133], v[138:141], v[182:185], v[130:133]
	v_mfma_f32_16x16x32_bf16 v[110:113], v[118:121], v[190:193], v[110:113]
	v_mfma_f32_16x16x32_bf16 v[106:109], v[138:141], v[190:193], v[106:109]
	v_mfma_f32_16x16x32_bf16 v[94:97], v[118:121], v[198:201], v[94:97]
	v_mfma_f32_16x16x32_bf16 v[90:93], v[138:141], v[198:201], v[90:93]
	v_mfma_f32_16x16x32_bf16 v[78:81], v[118:121], v[206:209], v[78:81]
	v_mfma_f32_16x16x32_bf16 v[74:77], v[138:141], v[206:209], v[74:77]
	v_mfma_f32_16x16x32_bf16 v[134:137], v[122:125], v[186:189], v[134:137]
	v_mfma_f32_16x16x32_bf16 v[130:133], v[142:145], v[186:189], v[130:133]
	v_mfma_f32_16x16x32_bf16 v[110:113], v[122:125], v[194:197], v[110:113]
	v_mfma_f32_16x16x32_bf16 v[106:109], v[142:145], v[194:197], v[106:109]
	v_mfma_f32_16x16x32_bf16 v[94:97], v[122:125], v[202:205], v[94:97]
	v_mfma_f32_16x16x32_bf16 v[90:93], v[142:145], v[202:205], v[90:93]
	v_mfma_f32_16x16x32_bf16 v[78:81], v[122:125], v[210:213], v[78:81]
	v_mfma_f32_16x16x32_bf16 v[74:77], v[142:145], v[210:213], v[74:77]
	v_mfma_f32_16x16x32_bf16 v[126:129], v[160:163], v[182:185], v[126:129]
	v_mfma_f32_16x16x32_bf16 v[114:117], v[174:177], v[182:185], v[114:117]
	v_mfma_f32_16x16x32_bf16 v[102:105], v[160:163], v[190:193], v[102:105]
	v_mfma_f32_16x16x32_bf16 v[98:101], v[174:177], v[190:193], v[98:101]
	v_mfma_f32_16x16x32_bf16 v[86:89], v[160:163], v[198:201], v[86:89]
	v_mfma_f32_16x16x32_bf16 v[82:85], v[174:177], v[198:201], v[82:85]
	v_mfma_f32_16x16x32_bf16 v[70:73], v[160:163], v[206:209], v[70:73]
	v_mfma_f32_16x16x32_bf16 v[66:69], v[174:177], v[206:209], v[66:69]
	v_mfma_f32_16x16x32_bf16 v[126:129], v[170:173], v[186:189], v[126:129]
	v_mfma_f32_16x16x32_bf16 v[114:117], v[178:181], v[186:189], v[114:117]
	v_mfma_f32_16x16x32_bf16 v[102:105], v[170:173], v[194:197], v[102:105]
	v_mfma_f32_16x16x32_bf16 v[98:101], v[178:181], v[194:197], v[98:101]
	v_mfma_f32_16x16x32_bf16 v[86:89], v[170:173], v[202:205], v[86:89]
	v_mfma_f32_16x16x32_bf16 v[82:85], v[178:181], v[202:205], v[82:85]
	v_mfma_f32_16x16x32_bf16 v[70:73], v[170:173], v[210:213], v[70:73]
	v_mfma_f32_16x16x32_bf16 v[66:69], v[178:181], v[210:213], v[66:69]
	s_setprio 0
	s_barrier
	s_add_i32 s59, s48, s28
	v_lshl_add_u64 v[214:215], s[60:61], 0, v[150:151]
	s_mov_b32 m0, s59
	ds_read_b128 v[182:185], v166 offset:16384
	ds_read_b128 v[186:189], v166 offset:17408
	ds_read_b128 v[190:193], v166 offset:18432
	ds_read_b128 v[194:197], v166 offset:19456
	ds_read_b128 v[198:201], v166 offset:20480
	ds_read_b128 v[202:205], v166 offset:21504
	ds_read_b128 v[206:209], v166 offset:22528
	ds_read_b128 v[210:213], v166 offset:23552
	global_load_lds_dwordx4 v[214:215], off
	s_add_i32 m0, s59, 0x2000
	v_lshl_add_u64 v[216:217], s[60:61], 0, v[146:147]
	s_add_u32 s60, s60, s6
	s_addc_u32 s61, s61, s7
	s_add_i32 s59, s49, s28
	global_load_lds_dwordx4 v[216:217], off
	v_lshl_add_u64 v[218:219], s[60:61], 0, v[150:151]
	s_mov_b32 m0, s59
	v_lshl_add_u64 v[220:221], s[60:61], 0, v[146:147]
	global_load_lds_dwordx4 v[218:219], off
	s_add_i32 m0, s59, 0x2000
	v_lshl_add_u64 v[222:223], s[22:23], 0, v[152:153]
	global_load_lds_dwordx4 v[220:221], off
	s_mov_b32 m0, s29
	v_lshl_add_u64 v[224:225], s[22:23], 0, v[148:149]
	global_load_lds_dwordx4 v[222:223], off
	s_mov_b32 m0, s30
	s_nop 0
	global_load_lds_dwordx4 v[224:225], off
	s_waitcnt vmcnt(8)
	s_waitcnt lgkmcnt(0)
	s_barrier
	s_setprio 1
	v_mfma_f32_16x16x32_bf16 v[62:65], v[118:121], v[182:185], v[62:65]
	v_mfma_f32_16x16x32_bf16 v[58:61], v[138:141], v[182:185], v[58:61]
	v_mfma_f32_16x16x32_bf16 v[46:49], v[118:121], v[190:193], v[46:49]
	v_mfma_f32_16x16x32_bf16 v[42:45], v[138:141], v[190:193], v[42:45]
	v_mfma_f32_16x16x32_bf16 v[30:33], v[118:121], v[198:201], v[30:33]
	v_mfma_f32_16x16x32_bf16 v[26:29], v[138:141], v[198:201], v[26:29]
	v_mfma_f32_16x16x32_bf16 v[14:17], v[118:121], v[206:209], v[14:17]
	v_mfma_f32_16x16x32_bf16 v[10:13], v[138:141], v[206:209], v[10:13]
	v_mfma_f32_16x16x32_bf16 v[62:65], v[122:125], v[186:189], v[62:65]
	v_mfma_f32_16x16x32_bf16 v[58:61], v[142:145], v[186:189], v[58:61]
	v_mfma_f32_16x16x32_bf16 v[46:49], v[122:125], v[194:197], v[46:49]
	v_mfma_f32_16x16x32_bf16 v[42:45], v[142:145], v[194:197], v[42:45]
	v_mfma_f32_16x16x32_bf16 v[30:33], v[122:125], v[202:205], v[30:33]
	v_mfma_f32_16x16x32_bf16 v[26:29], v[142:145], v[202:205], v[26:29]
	v_mfma_f32_16x16x32_bf16 v[14:17], v[122:125], v[210:213], v[14:17]
	v_mfma_f32_16x16x32_bf16 v[10:13], v[142:145], v[210:213], v[10:13]
	v_mfma_f32_16x16x32_bf16 v[54:57], v[160:163], v[182:185], v[54:57]
	v_mfma_f32_16x16x32_bf16 v[50:53], v[174:177], v[182:185], v[50:53]
	v_mfma_f32_16x16x32_bf16 v[38:41], v[160:163], v[190:193], v[38:41]
	v_mfma_f32_16x16x32_bf16 v[34:37], v[174:177], v[190:193], v[34:37]
	v_mfma_f32_16x16x32_bf16 v[22:25], v[160:163], v[198:201], v[22:25]
	v_mfma_f32_16x16x32_bf16 v[18:21], v[174:177], v[198:201], v[18:21]
	v_mfma_f32_16x16x32_bf16 v[6:9], v[160:163], v[206:209], v[6:9]
	v_mfma_f32_16x16x32_bf16 v[2:5], v[174:177], v[206:209], v[2:5]
	v_mfma_f32_16x16x32_bf16 v[54:57], v[170:173], v[186:189], v[54:57]
	v_mfma_f32_16x16x32_bf16 v[50:53], v[178:181], v[186:189], v[50:53]
	v_mfma_f32_16x16x32_bf16 v[38:41], v[170:173], v[194:197], v[38:41]
	v_mfma_f32_16x16x32_bf16 v[34:37], v[178:181], v[194:197], v[34:37]
	v_mfma_f32_16x16x32_bf16 v[22:25], v[170:173], v[202:205], v[22:25]
	v_mfma_f32_16x16x32_bf16 v[18:21], v[178:181], v[202:205], v[18:21]
	v_mfma_f32_16x16x32_bf16 v[6:9], v[170:173], v[210:213], v[6:9]
	v_mfma_f32_16x16x32_bf16 v[2:5], v[178:181], v[210:213], v[2:5]
	s_setprio 0
	s_barrier
	s_add_i32 s59, 0, 0x18000
	s_add_i32 s60, 0, 0x1c000
	v_add_u32_e32 v142, s59, v1
	v_add_u32_e32 v154, s60, v1
	ds_read_b128 v[118:121], v142
	ds_read_b128 v[122:125], v142 offset:1024
	ds_read_b128 v[138:141], v142 offset:2048
	ds_read_b128 v[142:145], v142 offset:3072
	ds_read_b128 v[160:163], v154
	ds_read_b128 v[170:173], v154 offset:1024
	ds_read_b128 v[174:177], v154 offset:2048
	ds_read_b128 v[178:181], v154 offset:3072
	s_add_u32 s22, s22, s6
	s_addc_u32 s23, s23, s7
	s_mov_b32 m0, s31
	v_lshl_add_u64 v[226:227], s[22:23], 0, v[152:153]
	ds_read_b128 v[182:185], v166 offset:32768
	ds_read_b128 v[186:189], v166 offset:33792
	ds_read_b128 v[190:193], v166 offset:34816
	ds_read_b128 v[194:197], v166 offset:35840
	ds_read_b128 v[198:201], v166 offset:36864
	ds_read_b128 v[202:205], v166 offset:37888
	ds_read_b128 v[206:209], v166 offset:38912
	ds_read_b128 v[210:213], v166 offset:39936
	global_load_lds_dwordx4 v[226:227], off
	v_lshl_add_u64 v[226:227], s[22:23], 0, v[148:149]
	s_mov_b32 m0, s34
	s_nop 0
	global_load_lds_dwordx4 v[226:227], off
	s_waitcnt vmcnt(8)
	s_waitcnt lgkmcnt(0)
	s_barrier
	s_setprio 1
	v_mfma_f32_16x16x32_bf16 v[134:137], v[118:121], v[182:185], v[134:137]
	v_mfma_f32_16x16x32_bf16 v[130:133], v[138:141], v[182:185], v[130:133]
	v_mfma_f32_16x16x32_bf16 v[110:113], v[118:121], v[190:193], v[110:113]
	v_mfma_f32_16x16x32_bf16 v[106:109], v[138:141], v[190:193], v[106:109]
	v_mfma_f32_16x16x32_bf16 v[94:97], v[118:121], v[198:201], v[94:97]
	v_mfma_f32_16x16x32_bf16 v[90:93], v[138:141], v[198:201], v[90:93]
	v_mfma_f32_16x16x32_bf16 v[78:81], v[118:121], v[206:209], v[78:81]
	v_mfma_f32_16x16x32_bf16 v[74:77], v[138:141], v[206:209], v[74:77]
	v_mfma_f32_16x16x32_bf16 v[134:137], v[122:125], v[186:189], v[134:137]
	v_mfma_f32_16x16x32_bf16 v[130:133], v[142:145], v[186:189], v[130:133]
	v_mfma_f32_16x16x32_bf16 v[110:113], v[122:125], v[194:197], v[110:113]
	v_mfma_f32_16x16x32_bf16 v[106:109], v[142:145], v[194:197], v[106:109]
	v_mfma_f32_16x16x32_bf16 v[94:97], v[122:125], v[202:205], v[94:97]
	v_mfma_f32_16x16x32_bf16 v[90:93], v[142:145], v[202:205], v[90:93]
	v_mfma_f32_16x16x32_bf16 v[78:81], v[122:125], v[210:213], v[78:81]
	v_mfma_f32_16x16x32_bf16 v[74:77], v[142:145], v[210:213], v[74:77]
	v_mfma_f32_16x16x32_bf16 v[126:129], v[160:163], v[182:185], v[126:129]
	v_mfma_f32_16x16x32_bf16 v[114:117], v[174:177], v[182:185], v[114:117]
	v_mfma_f32_16x16x32_bf16 v[102:105], v[160:163], v[190:193], v[102:105]
	v_mfma_f32_16x16x32_bf16 v[98:101], v[174:177], v[190:193], v[98:101]
	v_mfma_f32_16x16x32_bf16 v[86:89], v[160:163], v[198:201], v[86:89]
	v_mfma_f32_16x16x32_bf16 v[82:85], v[174:177], v[198:201], v[82:85]
	v_mfma_f32_16x16x32_bf16 v[70:73], v[160:163], v[206:209], v[70:73]
	v_mfma_f32_16x16x32_bf16 v[66:69], v[174:177], v[206:209], v[66:69]
	v_mfma_f32_16x16x32_bf16 v[126:129], v[170:173], v[186:189], v[126:129]
	v_mfma_f32_16x16x32_bf16 v[114:117], v[178:181], v[186:189], v[114:117]
	v_mfma_f32_16x16x32_bf16 v[102:105], v[170:173], v[194:197], v[102:105]
	v_mfma_f32_16x16x32_bf16 v[98:101], v[178:181], v[194:197], v[98:101]
	v_mfma_f32_16x16x32_bf16 v[86:89], v[170:173], v[202:205], v[86:89]
	v_mfma_f32_16x16x32_bf16 v[82:85], v[178:181], v[202:205], v[82:85]
	v_mfma_f32_16x16x32_bf16 v[70:73], v[170:173], v[210:213], v[70:73]
	v_mfma_f32_16x16x32_bf16 v[66:69], v[178:181], v[210:213], v[66:69]
	s_setprio 0
	s_barrier
	s_add_i32 s22, s59, s28
	v_lshl_add_u64 v[214:215], v[214:215], 0, s[12:13]
	s_mov_b32 m0, s22
	ds_read_b128 v[182:185], v166 offset:49152
	ds_read_b128 v[186:189], v166 offset:50176
	ds_read_b128 v[190:193], v166 offset:51200
	ds_read_b128 v[194:197], v166 offset:52224
	ds_read_b128 v[198:201], v166 offset:53248
	ds_read_b128 v[202:205], v166 offset:54272
	ds_read_b128 v[206:209], v166 offset:55296
	ds_read_b128 v[210:213], v166 offset:56320
	global_load_lds_dwordx4 v[214:215], off
	v_lshl_add_u64 v[214:215], v[216:217], 0, s[12:13]
	s_add_i32 m0, s22, 0x2000
	s_add_i32 s22, s60, s28
	global_load_lds_dwordx4 v[214:215], off
	v_lshl_add_u64 v[214:215], v[218:219], 0, s[12:13]
	s_mov_b32 m0, s22
	s_nop 0
	global_load_lds_dwordx4 v[214:215], off
	v_lshl_add_u64 v[214:215], v[220:221], 0, s[12:13]
	s_add_i32 m0, s22, 0x2000
	s_nop 0
	global_load_lds_dwordx4 v[214:215], off
	v_lshl_add_u64 v[214:215], v[222:223], 0, s[12:13]
	s_mov_b32 m0, s45
	s_nop 0
	global_load_lds_dwordx4 v[214:215], off
	v_lshl_add_u64 v[214:215], v[224:225], 0, s[12:13]
	s_mov_b32 m0, s46
	s_nop 0
	global_load_lds_dwordx4 v[214:215], off
	s_waitcnt vmcnt(8)
	s_waitcnt lgkmcnt(0)
	s_barrier
	s_setprio 1
	v_mfma_f32_16x16x32_bf16 v[62:65], v[118:121], v[182:185], v[62:65]
	v_mfma_f32_16x16x32_bf16 v[58:61], v[138:141], v[182:185], v[58:61]
	v_mfma_f32_16x16x32_bf16 v[46:49], v[118:121], v[190:193], v[46:49]
	v_mfma_f32_16x16x32_bf16 v[42:45], v[138:141], v[190:193], v[42:45]
	v_mfma_f32_16x16x32_bf16 v[30:33], v[118:121], v[198:201], v[30:33]
	v_mfma_f32_16x16x32_bf16 v[26:29], v[138:141], v[198:201], v[26:29]
	v_mfma_f32_16x16x32_bf16 v[14:17], v[118:121], v[206:209], v[14:17]
	v_mfma_f32_16x16x32_bf16 v[10:13], v[138:141], v[206:209], v[10:13]
	v_mfma_f32_16x16x32_bf16 v[62:65], v[122:125], v[186:189], v[62:65]
	v_mfma_f32_16x16x32_bf16 v[58:61], v[142:145], v[186:189], v[58:61]
	v_mfma_f32_16x16x32_bf16 v[46:49], v[122:125], v[194:197], v[46:49]
	v_mfma_f32_16x16x32_bf16 v[42:45], v[142:145], v[194:197], v[42:45]
	v_mfma_f32_16x16x32_bf16 v[30:33], v[122:125], v[202:205], v[30:33]
	v_mfma_f32_16x16x32_bf16 v[26:29], v[142:145], v[202:205], v[26:29]
	v_mfma_f32_16x16x32_bf16 v[14:17], v[122:125], v[210:213], v[14:17]
	v_mfma_f32_16x16x32_bf16 v[10:13], v[142:145], v[210:213], v[10:13]
	v_mfma_f32_16x16x32_bf16 v[54:57], v[160:163], v[182:185], v[54:57]
	v_mfma_f32_16x16x32_bf16 v[50:53], v[174:177], v[182:185], v[50:53]
	v_mfma_f32_16x16x32_bf16 v[38:41], v[160:163], v[190:193], v[38:41]
	v_mfma_f32_16x16x32_bf16 v[34:37], v[174:177], v[190:193], v[34:37]
	v_mfma_f32_16x16x32_bf16 v[22:25], v[160:163], v[198:201], v[22:25]
	v_mfma_f32_16x16x32_bf16 v[18:21], v[174:177], v[198:201], v[18:21]
	v_mfma_f32_16x16x32_bf16 v[6:9], v[160:163], v[206:209], v[6:9]
	v_mfma_f32_16x16x32_bf16 v[2:5], v[174:177], v[206:209], v[2:5]
	v_mfma_f32_16x16x32_bf16 v[54:57], v[170:173], v[186:189], v[54:57]
	v_mfma_f32_16x16x32_bf16 v[50:53], v[178:181], v[186:189], v[50:53]
	v_mfma_f32_16x16x32_bf16 v[38:41], v[170:173], v[194:197], v[38:41]
	v_mfma_f32_16x16x32_bf16 v[34:37], v[178:181], v[194:197], v[34:37]
	v_mfma_f32_16x16x32_bf16 v[22:25], v[170:173], v[202:205], v[22:25]
	v_mfma_f32_16x16x32_bf16 v[18:21], v[178:181], v[202:205], v[18:21]
	v_mfma_f32_16x16x32_bf16 v[6:9], v[170:173], v[210:213], v[6:9]
	v_mfma_f32_16x16x32_bf16 v[2:5], v[178:181], v[210:213], v[2:5]
	s_setprio 0
	s_barrier
	s_add_u32 s20, s20, 0x100
	s_addc_u32 s21, s21, 0
	s_add_u32 s56, s56, 0x100
	s_addc_u32 s57, s57, 0
	s_cmp_ge_i32 s58, s42
	s_mov_b32 s22, s58
	s_cbranch_scc0 .LBB0_736

.LBB0_757:
	ds_read_b128 v[152:155], v148
	ds_read_b128 v[156:159], v148 offset:1024
	ds_read_b128 v[160:163], v148 offset:2048
	ds_read_b128 v[164:167], v148 offset:3072
	ds_read_b128 v[170:173], v149
	ds_read_b128 v[174:177], v149 offset:1024
	ds_read_b128 v[178:181], v149 offset:2048
	ds_read_b128 v[182:185], v149 offset:3072
	s_add_i32 s60, s26, 2
	s_add_u32 s61, s24, 0x80
	s_addc_u32 s27, s25, 0
	s_cmp_eq_u32 s51, s26
	s_cselect_b32 s26, s2, s61
	s_cselect_b32 s27, s3, s27
	s_cselect_b32 s63, s23, s59
	s_cselect_b32 s62, s22, s58
	v_lshl_add_u64 v[218:219], s[24:25], 0, v[140:141]
	s_add_i32 m0, s38, 0xc000
	ds_read_b128 v[186:189], v150
	ds_read_b128 v[190:193], v150 offset:1024
	ds_read_b128 v[194:197], v150 offset:2048
	ds_read_b128 v[198:201], v150 offset:3072
	ds_read_b128 v[202:205], v150 offset:4096
	ds_read_b128 v[206:209], v150 offset:5120
	ds_read_b128 v[210:213], v150 offset:6144
	ds_read_b128 v[214:217], v150 offset:7168
	global_load_lds_dwordx4 v[218:219], off
	v_lshl_add_u64 v[218:219], s[24:25], 0, v[142:143]
	s_add_i32 m0, s38, 0xe000
	s_nop 0
	global_load_lds_dwordx4 v[218:219], off
	s_waitcnt vmcnt(8)
	s_waitcnt lgkmcnt(0)
	s_barrier
	s_setprio 1
	v_mfma_f32_16x16x32_bf16 v[122:125], v[152:155], v[186:189], v[122:125]
	v_mfma_f32_16x16x32_bf16 v[126:129], v[160:163], v[186:189], v[126:129]
	v_mfma_f32_16x16x32_bf16 v[110:113], v[152:155], v[194:197], v[110:113]
	v_mfma_f32_16x16x32_bf16 v[106:109], v[160:163], v[194:197], v[106:109]
	v_mfma_f32_16x16x32_bf16 v[94:97], v[152:155], v[202:205], v[94:97]
	v_mfma_f32_16x16x32_bf16 v[90:93], v[160:163], v[202:205], v[90:93]
	v_mfma_f32_16x16x32_bf16 v[78:81], v[152:155], v[210:213], v[78:81]
	v_mfma_f32_16x16x32_bf16 v[74:77], v[160:163], v[210:213], v[74:77]
	v_mfma_f32_16x16x32_bf16 v[122:125], v[156:159], v[190:193], v[122:125]
	v_mfma_f32_16x16x32_bf16 v[126:129], v[164:167], v[190:193], v[126:129]
	v_mfma_f32_16x16x32_bf16 v[110:113], v[156:159], v[198:201], v[110:113]
	v_mfma_f32_16x16x32_bf16 v[106:109], v[164:167], v[198:201], v[106:109]
	v_mfma_f32_16x16x32_bf16 v[94:97], v[156:159], v[206:209], v[94:97]
	v_mfma_f32_16x16x32_bf16 v[90:93], v[164:167], v[206:209], v[90:93]
	v_mfma_f32_16x16x32_bf16 v[78:81], v[156:159], v[214:217], v[78:81]
	v_mfma_f32_16x16x32_bf16 v[74:77], v[164:167], v[214:217], v[74:77]
	v_mfma_f32_16x16x32_bf16 v[118:121], v[170:173], v[186:189], v[118:121]
	v_mfma_f32_16x16x32_bf16 v[114:117], v[178:181], v[186:189], v[114:117]
	v_mfma_f32_16x16x32_bf16 v[102:105], v[170:173], v[194:197], v[102:105]
	v_mfma_f32_16x16x32_bf16 v[98:101], v[178:181], v[194:197], v[98:101]
	v_mfma_f32_16x16x32_bf16 v[86:89], v[170:173], v[202:205], v[86:89]
	v_mfma_f32_16x16x32_bf16 v[82:85], v[178:181], v[202:205], v[82:85]
	v_mfma_f32_16x16x32_bf16 v[70:73], v[170:173], v[210:213], v[70:73]
	v_mfma_f32_16x16x32_bf16 v[66:69], v[178:181], v[210:213], v[66:69]
	v_mfma_f32_16x16x32_bf16 v[118:121], v[174:177], v[190:193], v[118:121]
	v_mfma_f32_16x16x32_bf16 v[114:117], v[182:185], v[190:193], v[114:117]
	v_mfma_f32_16x16x32_bf16 v[102:105], v[174:177], v[198:201], v[102:105]
	v_mfma_f32_16x16x32_bf16 v[98:101], v[182:185], v[198:201], v[98:101]
	v_mfma_f32_16x16x32_bf16 v[86:89], v[174:177], v[206:209], v[86:89]
	v_mfma_f32_16x16x32_bf16 v[82:85], v[182:185], v[206:209], v[82:85]
	v_mfma_f32_16x16x32_bf16 v[70:73], v[174:177], v[214:217], v[70:73]
	v_mfma_f32_16x16x32_bf16 v[66:69], v[182:185], v[214:217], v[66:69]
	s_setprio 0
	s_barrier
	s_add_i32 s61, s53, s36
	v_lshl_add_u64 v[218:219], s[62:63], 0, v[134:135]
	s_mov_b32 m0, s61
	ds_read_b128 v[186:189], v150 offset:16384
	ds_read_b128 v[190:193], v150 offset:17408
	ds_read_b128 v[194:197], v150 offset:18432
	ds_read_b128 v[198:201], v150 offset:19456
	ds_read_b128 v[202:205], v150 offset:20480
	ds_read_b128 v[206:209], v150 offset:21504
	ds_read_b128 v[210:213], v150 offset:22528
	ds_read_b128 v[214:217], v150 offset:23552
	global_load_lds_dwordx4 v[218:219], off
	s_add_i32 m0, s61, 0x2000
	v_lshl_add_u64 v[220:221], s[62:63], 0, v[130:131]
	s_add_u32 s62, s62, s6
	s_addc_u32 s63, s63, s7
	s_add_i32 s61, s54, s36
	global_load_lds_dwordx4 v[220:221], off
	v_lshl_add_u64 v[222:223], s[62:63], 0, v[134:135]
	s_mov_b32 m0, s61
	v_lshl_add_u64 v[224:225], s[62:63], 0, v[130:131]
	global_load_lds_dwordx4 v[222:223], off
	s_add_i32 m0, s61, 0x2000
	v_lshl_add_u64 v[226:227], s[26:27], 0, v[136:137]
	global_load_lds_dwordx4 v[224:225], off
	s_mov_b32 m0, s38
	v_lshl_add_u64 v[228:229], s[26:27], 0, v[132:133]
	global_load_lds_dwordx4 v[226:227], off
	s_mov_b32 m0, s39
	s_nop 0
	global_load_lds_dwordx4 v[228:229], off
	s_waitcnt vmcnt(8)
	s_waitcnt lgkmcnt(0)
	s_barrier
	s_setprio 1
	v_mfma_f32_16x16x32_bf16 v[62:65], v[152:155], v[186:189], v[62:65]
	v_mfma_f32_16x16x32_bf16 v[58:61], v[160:163], v[186:189], v[58:61]
	v_mfma_f32_16x16x32_bf16 v[46:49], v[152:155], v[194:197], v[46:49]
	v_mfma_f32_16x16x32_bf16 v[42:45], v[160:163], v[194:197], v[42:45]
	v_mfma_f32_16x16x32_bf16 v[30:33], v[152:155], v[202:205], v[30:33]
	v_mfma_f32_16x16x32_bf16 v[26:29], v[160:163], v[202:205], v[26:29]
	v_mfma_f32_16x16x32_bf16 v[14:17], v[152:155], v[210:213], v[14:17]
	v_mfma_f32_16x16x32_bf16 v[10:13], v[160:163], v[210:213], v[10:13]
	v_mfma_f32_16x16x32_bf16 v[62:65], v[156:159], v[190:193], v[62:65]
	v_mfma_f32_16x16x32_bf16 v[58:61], v[164:167], v[190:193], v[58:61]
	v_mfma_f32_16x16x32_bf16 v[46:49], v[156:159], v[198:201], v[46:49]
	v_mfma_f32_16x16x32_bf16 v[42:45], v[164:167], v[198:201], v[42:45]
	v_mfma_f32_16x16x32_bf16 v[30:33], v[156:159], v[206:209], v[30:33]
	v_mfma_f32_16x16x32_bf16 v[26:29], v[164:167], v[206:209], v[26:29]
	v_mfma_f32_16x16x32_bf16 v[14:17], v[156:159], v[214:217], v[14:17]
	v_mfma_f32_16x16x32_bf16 v[10:13], v[164:167], v[214:217], v[10:13]
	v_mfma_f32_16x16x32_bf16 v[54:57], v[170:173], v[186:189], v[54:57]
	v_mfma_f32_16x16x32_bf16 v[50:53], v[178:181], v[186:189], v[50:53]
	v_mfma_f32_16x16x32_bf16 v[38:41], v[170:173], v[194:197], v[38:41]
	v_mfma_f32_16x16x32_bf16 v[34:37], v[178:181], v[194:197], v[34:37]
	v_mfma_f32_16x16x32_bf16 v[22:25], v[170:173], v[202:205], v[22:25]
	v_mfma_f32_16x16x32_bf16 v[18:21], v[178:181], v[202:205], v[18:21]
	v_mfma_f32_16x16x32_bf16 v[6:9], v[170:173], v[210:213], v[6:9]
	v_mfma_f32_16x16x32_bf16 v[2:5], v[178:181], v[210:213], v[2:5]
	v_mfma_f32_16x16x32_bf16 v[54:57], v[174:177], v[190:193], v[54:57]
	v_mfma_f32_16x16x32_bf16 v[50:53], v[182:185], v[190:193], v[50:53]
	v_mfma_f32_16x16x32_bf16 v[38:41], v[174:177], v[198:201], v[38:41]
	v_mfma_f32_16x16x32_bf16 v[34:37], v[182:185], v[198:201], v[34:37]
	v_mfma_f32_16x16x32_bf16 v[22:25], v[174:177], v[206:209], v[22:25]
	v_mfma_f32_16x16x32_bf16 v[18:21], v[182:185], v[206:209], v[18:21]
	v_mfma_f32_16x16x32_bf16 v[6:9], v[174:177], v[214:217], v[6:9]
	v_mfma_f32_16x16x32_bf16 v[2:5], v[182:185], v[214:217], v[2:5]
	s_setprio 0
	s_barrier
	s_add_i32 s61, 0, 0x18000
	v_add_u32_e32 v138, s61, v1
	s_add_i32 s62, 0, 0x1c000
	ds_read_b128 v[152:155], v138
	ds_read_b128 v[156:159], v138 offset:1024
	ds_read_b128 v[160:163], v138 offset:2048
	ds_read_b128 v[164:167], v138 offset:3072
	v_add_u32_e32 v138, s62, v1
	ds_read_b128 v[170:173], v138
	ds_read_b128 v[174:177], v138 offset:1024
	ds_read_b128 v[178:181], v138 offset:2048
	ds_read_b128 v[182:185], v138 offset:3072
	s_add_u32 s26, s26, s6
	s_addc_u32 s27, s27, s7
	s_mov_b32 m0, s42
	v_lshl_add_u64 v[230:231], s[26:27], 0, v[136:137]
	ds_read_b128 v[186:189], v150 offset:32768
	ds_read_b128 v[190:193], v150 offset:33792
	ds_read_b128 v[194:197], v150 offset:34816
	ds_read_b128 v[198:201], v150 offset:35840
	ds_read_b128 v[202:205], v150 offset:36864
	ds_read_b128 v[206:209], v150 offset:37888
	ds_read_b128 v[210:213], v150 offset:38912
	ds_read_b128 v[214:217], v150 offset:39936
	global_load_lds_dwordx4 v[230:231], off
	v_lshl_add_u64 v[230:231], s[26:27], 0, v[132:133]
	s_mov_b32 m0, s43
	s_nop 0
	global_load_lds_dwordx4 v[230:231], off
	s_waitcnt vmcnt(8)
	s_waitcnt lgkmcnt(0)
	s_barrier
	s_setprio 1
	v_mfma_f32_16x16x32_bf16 v[122:125], v[152:155], v[186:189], v[122:125]
	v_mfma_f32_16x16x32_bf16 v[126:129], v[160:163], v[186:189], v[126:129]
	v_mfma_f32_16x16x32_bf16 v[110:113], v[152:155], v[194:197], v[110:113]
	v_mfma_f32_16x16x32_bf16 v[106:109], v[160:163], v[194:197], v[106:109]
	v_mfma_f32_16x16x32_bf16 v[94:97], v[152:155], v[202:205], v[94:97]
	v_mfma_f32_16x16x32_bf16 v[90:93], v[160:163], v[202:205], v[90:93]
	v_mfma_f32_16x16x32_bf16 v[78:81], v[152:155], v[210:213], v[78:81]
	v_mfma_f32_16x16x32_bf16 v[74:77], v[160:163], v[210:213], v[74:77]
	v_mfma_f32_16x16x32_bf16 v[122:125], v[156:159], v[190:193], v[122:125]
	v_mfma_f32_16x16x32_bf16 v[126:129], v[164:167], v[190:193], v[126:129]
	v_mfma_f32_16x16x32_bf16 v[110:113], v[156:159], v[198:201], v[110:113]
	v_mfma_f32_16x16x32_bf16 v[106:109], v[164:167], v[198:201], v[106:109]
	v_mfma_f32_16x16x32_bf16 v[94:97], v[156:159], v[206:209], v[94:97]
	v_mfma_f32_16x16x32_bf16 v[90:93], v[164:167], v[206:209], v[90:93]
	v_mfma_f32_16x16x32_bf16 v[78:81], v[156:159], v[214:217], v[78:81]
	v_mfma_f32_16x16x32_bf16 v[74:77], v[164:167], v[214:217], v[74:77]
	v_mfma_f32_16x16x32_bf16 v[118:121], v[170:173], v[186:189], v[118:121]
	v_mfma_f32_16x16x32_bf16 v[114:117], v[178:181], v[186:189], v[114:117]
	v_mfma_f32_16x16x32_bf16 v[102:105], v[170:173], v[194:197], v[102:105]
	v_mfma_f32_16x16x32_bf16 v[98:101], v[178:181], v[194:197], v[98:101]
	v_mfma_f32_16x16x32_bf16 v[86:89], v[170:173], v[202:205], v[86:89]
	v_mfma_f32_16x16x32_bf16 v[82:85], v[178:181], v[202:205], v[82:85]
	v_mfma_f32_16x16x32_bf16 v[70:73], v[170:173], v[210:213], v[70:73]
	v_mfma_f32_16x16x32_bf16 v[66:69], v[178:181], v[210:213], v[66:69]
	v_mfma_f32_16x16x32_bf16 v[118:121], v[174:177], v[190:193], v[118:121]
	v_mfma_f32_16x16x32_bf16 v[114:117], v[182:185], v[190:193], v[114:117]
	v_mfma_f32_16x16x32_bf16 v[102:105], v[174:177], v[198:201], v[102:105]
	v_mfma_f32_16x16x32_bf16 v[98:101], v[182:185], v[198:201], v[98:101]
	v_mfma_f32_16x16x32_bf16 v[86:89], v[174:177], v[206:209], v[86:89]
	v_mfma_f32_16x16x32_bf16 v[82:85], v[182:185], v[206:209], v[82:85]
	v_mfma_f32_16x16x32_bf16 v[70:73], v[174:177], v[214:217], v[70:73]
	v_mfma_f32_16x16x32_bf16 v[66:69], v[182:185], v[214:217], v[66:69]
	s_setprio 0
	s_barrier
	s_add_i32 s26, s61, s36
	v_lshl_add_u64 v[218:219], v[218:219], 0, s[14:15]
	s_mov_b32 m0, s26
	ds_read_b128 v[186:189], v150 offset:49152
	ds_read_b128 v[190:193], v150 offset:50176
	ds_read_b128 v[194:197], v150 offset:51200
	ds_read_b128 v[198:201], v150 offset:52224
	ds_read_b128 v[202:205], v150 offset:53248
	ds_read_b128 v[206:209], v150 offset:54272
	ds_read_b128 v[210:213], v150 offset:55296
	ds_read_b128 v[214:217], v150 offset:56320
	global_load_lds_dwordx4 v[218:219], off
	v_lshl_add_u64 v[218:219], v[220:221], 0, s[14:15]
	s_add_i32 m0, s26, 0x2000
	s_add_i32 s26, s62, s36
	global_load_lds_dwordx4 v[218:219], off
	v_lshl_add_u64 v[218:219], v[222:223], 0, s[14:15]
	s_mov_b32 m0, s26
	s_nop 0
	global_load_lds_dwordx4 v[218:219], off
	v_lshl_add_u64 v[218:219], v[224:225], 0, s[14:15]
	s_add_i32 m0, s26, 0x2000
	s_nop 0
	global_load_lds_dwordx4 v[218:219], off
	v_lshl_add_u64 v[218:219], v[226:227], 0, s[14:15]
	s_mov_b32 m0, s48
	s_nop 0
	global_load_lds_dwordx4 v[218:219], off
	v_lshl_add_u64 v[218:219], v[228:229], 0, s[14:15]
	s_mov_b32 m0, s49
	s_nop 0
	global_load_lds_dwordx4 v[218:219], off
	s_waitcnt vmcnt(8)
	s_waitcnt lgkmcnt(0)
	s_barrier
	s_setprio 1
	v_mfma_f32_16x16x32_bf16 v[62:65], v[152:155], v[186:189], v[62:65]
	v_mfma_f32_16x16x32_bf16 v[58:61], v[160:163], v[186:189], v[58:61]
	v_mfma_f32_16x16x32_bf16 v[46:49], v[152:155], v[194:197], v[46:49]
	v_mfma_f32_16x16x32_bf16 v[42:45], v[160:163], v[194:197], v[42:45]
	v_mfma_f32_16x16x32_bf16 v[30:33], v[152:155], v[202:205], v[30:33]
	v_mfma_f32_16x16x32_bf16 v[26:29], v[160:163], v[202:205], v[26:29]
	v_mfma_f32_16x16x32_bf16 v[14:17], v[152:155], v[210:213], v[14:17]
	v_mfma_f32_16x16x32_bf16 v[10:13], v[160:163], v[210:213], v[10:13]
	v_mfma_f32_16x16x32_bf16 v[62:65], v[156:159], v[190:193], v[62:65]
	v_mfma_f32_16x16x32_bf16 v[58:61], v[164:167], v[190:193], v[58:61]
	v_mfma_f32_16x16x32_bf16 v[46:49], v[156:159], v[198:201], v[46:49]
	v_mfma_f32_16x16x32_bf16 v[42:45], v[164:167], v[198:201], v[42:45]
	v_mfma_f32_16x16x32_bf16 v[30:33], v[156:159], v[206:209], v[30:33]
	v_mfma_f32_16x16x32_bf16 v[26:29], v[164:167], v[206:209], v[26:29]
	v_mfma_f32_16x16x32_bf16 v[14:17], v[156:159], v[214:217], v[14:17]
	v_mfma_f32_16x16x32_bf16 v[10:13], v[164:167], v[214:217], v[10:13]
	v_mfma_f32_16x16x32_bf16 v[54:57], v[170:173], v[186:189], v[54:57]
	v_mfma_f32_16x16x32_bf16 v[50:53], v[178:181], v[186:189], v[50:53]
	v_mfma_f32_16x16x32_bf16 v[38:41], v[170:173], v[194:197], v[38:41]
	v_mfma_f32_16x16x32_bf16 v[34:37], v[178:181], v[194:197], v[34:37]
	v_mfma_f32_16x16x32_bf16 v[22:25], v[170:173], v[202:205], v[22:25]
	v_mfma_f32_16x16x32_bf16 v[18:21], v[178:181], v[202:205], v[18:21]
	v_mfma_f32_16x16x32_bf16 v[6:9], v[170:173], v[210:213], v[6:9]
	v_mfma_f32_16x16x32_bf16 v[2:5], v[178:181], v[210:213], v[2:5]
	v_mfma_f32_16x16x32_bf16 v[54:57], v[174:177], v[190:193], v[54:57]
	v_mfma_f32_16x16x32_bf16 v[50:53], v[182:185], v[190:193], v[50:53]
	v_mfma_f32_16x16x32_bf16 v[38:41], v[174:177], v[198:201], v[38:41]
	v_mfma_f32_16x16x32_bf16 v[34:37], v[182:185], v[198:201], v[34:37]
	v_mfma_f32_16x16x32_bf16 v[22:25], v[174:177], v[206:209], v[22:25]
	v_mfma_f32_16x16x32_bf16 v[18:21], v[182:185], v[206:209], v[18:21]
	v_mfma_f32_16x16x32_bf16 v[6:9], v[174:177], v[214:217], v[6:9]
	v_mfma_f32_16x16x32_bf16 v[2:5], v[182:185], v[214:217], v[2:5]
	s_setprio 0
	s_barrier
	s_add_u32 s24, s24, 0x100
	s_addc_u32 s25, s25, 0
	s_add_u32 s58, s58, 0x100
	s_addc_u32 s59, s59, 0
	s_cmp_ge_i32 s60, s44
	s_mov_b32 s26, s60
	s_cbranch_scc0 .LBB0_757

.LBB0_778:
	v_add_u32_e32 v138, s57, v1
	ds_read_b128 v[148:151], v138
	ds_read_b128 v[152:155], v138 offset:1024
	ds_read_b128 v[158:161], v138 offset:2048
	ds_read_b128 v[162:165], v138 offset:3072
	v_add_u32_e32 v138, s58, v1
	ds_read_b128 v[170:173], v138
	ds_read_b128 v[174:177], v138 offset:1024
	ds_read_b128 v[178:181], v138 offset:2048
	ds_read_b128 v[182:185], v138 offset:3072
	s_add_i32 s66, s28, 2
	s_add_u32 s67, s26, 0x80
	s_addc_u32 s29, s27, 0
	s_cmp_eq_u32 s55, s28
	s_cselect_b32 s28, s2, s67
	s_cselect_b32 s29, s3, s29
	s_cselect_b32 s69, s25, s65
	s_cselect_b32 s68, s24, s64
	v_lshl_add_u64 v[166:167], s[26:27], 0, v[140:141]
	s_add_i32 m0, s43, 0xc000
	ds_read_b128 v[186:189], v157
	ds_read_b128 v[190:193], v157 offset:1024
	ds_read_b128 v[194:197], v157 offset:2048
	ds_read_b128 v[198:201], v157 offset:3072
	ds_read_b128 v[202:205], v157 offset:4096
	ds_read_b128 v[206:209], v157 offset:5120
	ds_read_b128 v[210:213], v157 offset:6144
	ds_read_b128 v[214:217], v157 offset:7168
	global_load_lds_dwordx4 v[166:167], off
	v_lshl_add_u64 v[166:167], s[26:27], 0, v[142:143]
	s_add_i32 m0, s43, 0xe000
	s_nop 0
	global_load_lds_dwordx4 v[166:167], off
	s_waitcnt vmcnt(8)
	s_waitcnt lgkmcnt(0)
	s_barrier
	s_setprio 1
	v_mfma_i32_16x16x64_i8 v[126:129], v[148:151], v[186:189], v[126:129]
	v_mfma_i32_16x16x64_i8 v[122:125], v[158:161], v[186:189], v[122:125]
	v_mfma_i32_16x16x64_i8 v[118:121], v[148:151], v[194:197], v[118:121]
	v_mfma_i32_16x16x64_i8 v[114:117], v[158:161], v[194:197], v[114:117]
	v_mfma_i32_16x16x64_i8 v[106:109], v[148:151], v[202:205], v[106:109]
	v_mfma_i32_16x16x64_i8 v[98:101], v[158:161], v[202:205], v[98:101]
	v_mfma_i32_16x16x64_i8 v[90:93], v[148:151], v[210:213], v[90:93]
	v_mfma_i32_16x16x64_i8 v[82:85], v[158:161], v[210:213], v[82:85]
	v_mfma_i32_16x16x64_i8 v[126:129], v[152:155], v[190:193], v[126:129]
	v_mfma_i32_16x16x64_i8 v[122:125], v[162:165], v[190:193], v[122:125]
	v_mfma_i32_16x16x64_i8 v[118:121], v[152:155], v[198:201], v[118:121]
	v_mfma_i32_16x16x64_i8 v[114:117], v[162:165], v[198:201], v[114:117]
	v_mfma_i32_16x16x64_i8 v[106:109], v[152:155], v[206:209], v[106:109]
	v_mfma_i32_16x16x64_i8 v[98:101], v[162:165], v[206:209], v[98:101]
	v_mfma_i32_16x16x64_i8 v[90:93], v[152:155], v[214:217], v[90:93]
	v_mfma_i32_16x16x64_i8 v[82:85], v[162:165], v[214:217], v[82:85]
	v_mfma_i32_16x16x64_i8 v[110:113], v[170:173], v[186:189], v[110:113]
	v_mfma_i32_16x16x64_i8 v[102:105], v[178:181], v[186:189], v[102:105]
	v_mfma_i32_16x16x64_i8 v[94:97], v[170:173], v[194:197], v[94:97]
	v_mfma_i32_16x16x64_i8 v[86:89], v[178:181], v[194:197], v[86:89]
	v_mfma_i32_16x16x64_i8 v[78:81], v[170:173], v[202:205], v[78:81]
	v_mfma_i32_16x16x64_i8 v[74:77], v[178:181], v[202:205], v[74:77]
	v_mfma_i32_16x16x64_i8 v[70:73], v[170:173], v[210:213], v[70:73]
	v_mfma_i32_16x16x64_i8 v[66:69], v[178:181], v[210:213], v[66:69]
	v_mfma_i32_16x16x64_i8 v[110:113], v[174:177], v[190:193], v[110:113]
	v_mfma_i32_16x16x64_i8 v[102:105], v[182:185], v[190:193], v[102:105]
	v_mfma_i32_16x16x64_i8 v[94:97], v[174:177], v[198:201], v[94:97]
	v_mfma_i32_16x16x64_i8 v[86:89], v[182:185], v[198:201], v[86:89]
	v_mfma_i32_16x16x64_i8 v[78:81], v[174:177], v[206:209], v[78:81]
	v_mfma_i32_16x16x64_i8 v[74:77], v[182:185], v[206:209], v[74:77]
	v_mfma_i32_16x16x64_i8 v[70:73], v[174:177], v[214:217], v[70:73]
	v_mfma_i32_16x16x64_i8 v[66:69], v[182:185], v[214:217], v[66:69]
	s_setprio 0
	s_barrier
	s_add_i32 s67, s57, s38
	v_lshl_add_u64 v[166:167], s[68:69], 0, v[134:135]
	s_mov_b32 m0, s67
	ds_read_b128 v[186:189], v157 offset:16384
	ds_read_b128 v[190:193], v157 offset:17408
	ds_read_b128 v[194:197], v157 offset:18432
	ds_read_b128 v[198:201], v157 offset:19456
	ds_read_b128 v[202:205], v157 offset:20480
	ds_read_b128 v[206:209], v157 offset:21504
	ds_read_b128 v[210:213], v157 offset:22528
	ds_read_b128 v[214:217], v157 offset:23552
	global_load_lds_dwordx4 v[166:167], off
	s_add_i32 m0, s67, 0x2000
	v_lshl_add_u64 v[218:219], s[68:69], 0, v[130:131]
	s_add_u32 s68, s68, s6
	s_addc_u32 s69, s69, s7
	s_add_i32 s67, s58, s38
	global_load_lds_dwordx4 v[218:219], off
	v_lshl_add_u64 v[220:221], s[68:69], 0, v[134:135]
	s_mov_b32 m0, s67
	v_lshl_add_u64 v[222:223], s[68:69], 0, v[130:131]
	global_load_lds_dwordx4 v[220:221], off
	s_add_i32 m0, s67, 0x2000
	v_lshl_add_u64 v[224:225], s[28:29], 0, v[136:137]
	global_load_lds_dwordx4 v[222:223], off
	s_mov_b32 m0, s43
	v_lshl_add_u64 v[226:227], s[28:29], 0, v[132:133]
	global_load_lds_dwordx4 v[224:225], off
	s_mov_b32 m0, s44
	s_nop 0
	global_load_lds_dwordx4 v[226:227], off
	s_waitcnt vmcnt(8)
	s_waitcnt lgkmcnt(0)
	s_barrier
	s_setprio 1
	v_mfma_i32_16x16x64_i8 v[62:65], v[148:151], v[186:189], v[62:65]
	v_mfma_i32_16x16x64_i8 v[58:61], v[158:161], v[186:189], v[58:61]
	v_mfma_i32_16x16x64_i8 v[54:57], v[148:151], v[194:197], v[54:57]
	v_mfma_i32_16x16x64_i8 v[50:53], v[158:161], v[194:197], v[50:53]
	v_mfma_i32_16x16x64_i8 v[42:45], v[148:151], v[202:205], v[42:45]
	v_mfma_i32_16x16x64_i8 v[34:37], v[158:161], v[202:205], v[34:37]
	v_mfma_i32_16x16x64_i8 v[26:29], v[148:151], v[210:213], v[26:29]
	v_mfma_i32_16x16x64_i8 v[18:21], v[158:161], v[210:213], v[18:21]
	v_mfma_i32_16x16x64_i8 v[62:65], v[152:155], v[190:193], v[62:65]
	v_mfma_i32_16x16x64_i8 v[58:61], v[162:165], v[190:193], v[58:61]
	v_mfma_i32_16x16x64_i8 v[54:57], v[152:155], v[198:201], v[54:57]
	v_mfma_i32_16x16x64_i8 v[50:53], v[162:165], v[198:201], v[50:53]
	v_mfma_i32_16x16x64_i8 v[42:45], v[152:155], v[206:209], v[42:45]
	v_mfma_i32_16x16x64_i8 v[34:37], v[162:165], v[206:209], v[34:37]
	v_mfma_i32_16x16x64_i8 v[26:29], v[152:155], v[214:217], v[26:29]
	v_mfma_i32_16x16x64_i8 v[18:21], v[162:165], v[214:217], v[18:21]
	v_mfma_i32_16x16x64_i8 v[46:49], v[170:173], v[186:189], v[46:49]
	v_mfma_i32_16x16x64_i8 v[38:41], v[178:181], v[186:189], v[38:41]
	v_mfma_i32_16x16x64_i8 v[30:33], v[170:173], v[194:197], v[30:33]
	v_mfma_i32_16x16x64_i8 v[22:25], v[178:181], v[194:197], v[22:25]
	v_mfma_i32_16x16x64_i8 v[14:17], v[170:173], v[202:205], v[14:17]
	v_mfma_i32_16x16x64_i8 v[10:13], v[178:181], v[202:205], v[10:13]
	v_mfma_i32_16x16x64_i8 v[6:9], v[170:173], v[210:213], v[6:9]
	v_mfma_i32_16x16x64_i8 v[2:5], v[178:181], v[210:213], v[2:5]
	v_mfma_i32_16x16x64_i8 v[46:49], v[174:177], v[190:193], v[46:49]
	v_mfma_i32_16x16x64_i8 v[38:41], v[182:185], v[190:193], v[38:41]
	v_mfma_i32_16x16x64_i8 v[30:33], v[174:177], v[198:201], v[30:33]
	v_mfma_i32_16x16x64_i8 v[22:25], v[182:185], v[198:201], v[22:25]
	v_mfma_i32_16x16x64_i8 v[14:17], v[174:177], v[206:209], v[14:17]
	v_mfma_i32_16x16x64_i8 v[10:13], v[182:185], v[206:209], v[10:13]
	v_mfma_i32_16x16x64_i8 v[6:9], v[174:177], v[214:217], v[6:9]
	v_mfma_i32_16x16x64_i8 v[2:5], v[182:185], v[214:217], v[2:5]
	s_setprio 0
	s_barrier
	s_add_i32 s67, 0, 0x18000
	v_add_u32_e32 v138, s67, v1
	s_add_i32 s68, 0, 0x1c000
	ds_read_b128 v[148:151], v138
	ds_read_b128 v[152:155], v138 offset:1024
	ds_read_b128 v[158:161], v138 offset:2048
	ds_read_b128 v[162:165], v138 offset:3072
	v_add_u32_e32 v138, s68, v1
	ds_read_b128 v[170:173], v138
	ds_read_b128 v[174:177], v138 offset:1024
	ds_read_b128 v[178:181], v138 offset:2048
	ds_read_b128 v[182:185], v138 offset:3072
	s_add_u32 s28, s28, s6
	s_addc_u32 s29, s29, s7
	s_mov_b32 m0, s45
	v_lshl_add_u64 v[228:229], s[28:29], 0, v[136:137]
	ds_read_b128 v[186:189], v157 offset:32768
	ds_read_b128 v[190:193], v157 offset:33792
	ds_read_b128 v[194:197], v157 offset:34816
	ds_read_b128 v[198:201], v157 offset:35840
	ds_read_b128 v[202:205], v157 offset:36864
	ds_read_b128 v[206:209], v157 offset:37888
	ds_read_b128 v[210:213], v157 offset:38912
	ds_read_b128 v[214:217], v157 offset:39936
	global_load_lds_dwordx4 v[228:229], off
	v_lshl_add_u64 v[228:229], s[28:29], 0, v[132:133]
	s_mov_b32 m0, s46
	s_nop 0
	global_load_lds_dwordx4 v[228:229], off
	s_waitcnt vmcnt(8)
	s_waitcnt lgkmcnt(0)
	s_barrier
	s_setprio 1
	v_mfma_i32_16x16x64_i8 v[126:129], v[148:151], v[186:189], v[126:129]
	v_mfma_i32_16x16x64_i8 v[122:125], v[158:161], v[186:189], v[122:125]
	v_mfma_i32_16x16x64_i8 v[118:121], v[148:151], v[194:197], v[118:121]
	v_mfma_i32_16x16x64_i8 v[114:117], v[158:161], v[194:197], v[114:117]
	v_mfma_i32_16x16x64_i8 v[106:109], v[148:151], v[202:205], v[106:109]
	v_mfma_i32_16x16x64_i8 v[98:101], v[158:161], v[202:205], v[98:101]
	v_mfma_i32_16x16x64_i8 v[90:93], v[148:151], v[210:213], v[90:93]
	v_mfma_i32_16x16x64_i8 v[82:85], v[158:161], v[210:213], v[82:85]
	v_mfma_i32_16x16x64_i8 v[126:129], v[152:155], v[190:193], v[126:129]
	v_mfma_i32_16x16x64_i8 v[122:125], v[162:165], v[190:193], v[122:125]
	v_mfma_i32_16x16x64_i8 v[118:121], v[152:155], v[198:201], v[118:121]
	v_mfma_i32_16x16x64_i8 v[114:117], v[162:165], v[198:201], v[114:117]
	v_mfma_i32_16x16x64_i8 v[106:109], v[152:155], v[206:209], v[106:109]
	v_mfma_i32_16x16x64_i8 v[98:101], v[162:165], v[206:209], v[98:101]
	v_mfma_i32_16x16x64_i8 v[90:93], v[152:155], v[214:217], v[90:93]
	v_mfma_i32_16x16x64_i8 v[82:85], v[162:165], v[214:217], v[82:85]
	v_mfma_i32_16x16x64_i8 v[110:113], v[170:173], v[186:189], v[110:113]
	v_mfma_i32_16x16x64_i8 v[102:105], v[178:181], v[186:189], v[102:105]
	v_mfma_i32_16x16x64_i8 v[94:97], v[170:173], v[194:197], v[94:97]
	v_mfma_i32_16x16x64_i8 v[86:89], v[178:181], v[194:197], v[86:89]
	v_mfma_i32_16x16x64_i8 v[78:81], v[170:173], v[202:205], v[78:81]
	v_mfma_i32_16x16x64_i8 v[74:77], v[178:181], v[202:205], v[74:77]
	v_mfma_i32_16x16x64_i8 v[70:73], v[170:173], v[210:213], v[70:73]
	v_mfma_i32_16x16x64_i8 v[66:69], v[178:181], v[210:213], v[66:69]
	v_mfma_i32_16x16x64_i8 v[110:113], v[174:177], v[190:193], v[110:113]
	v_mfma_i32_16x16x64_i8 v[102:105], v[182:185], v[190:193], v[102:105]
	v_mfma_i32_16x16x64_i8 v[94:97], v[174:177], v[198:201], v[94:97]
	v_mfma_i32_16x16x64_i8 v[86:89], v[182:185], v[198:201], v[86:89]
	v_mfma_i32_16x16x64_i8 v[78:81], v[174:177], v[206:209], v[78:81]
	v_mfma_i32_16x16x64_i8 v[74:77], v[182:185], v[206:209], v[74:77]
	v_mfma_i32_16x16x64_i8 v[70:73], v[174:177], v[214:217], v[70:73]
	v_mfma_i32_16x16x64_i8 v[66:69], v[182:185], v[214:217], v[66:69]
	s_setprio 0
	s_barrier
	s_add_i32 s28, s67, s38
	v_lshl_add_u64 v[166:167], v[166:167], 0, s[16:17]
	s_mov_b32 m0, s28
	ds_read_b128 v[186:189], v157 offset:49152
	ds_read_b128 v[190:193], v157 offset:50176
	ds_read_b128 v[194:197], v157 offset:51200
	ds_read_b128 v[198:201], v157 offset:52224
	ds_read_b128 v[202:205], v157 offset:53248
	ds_read_b128 v[206:209], v157 offset:54272
	ds_read_b128 v[210:213], v157 offset:55296
	ds_read_b128 v[214:217], v157 offset:56320
	global_load_lds_dwordx4 v[166:167], off
	v_lshl_add_u64 v[166:167], v[218:219], 0, s[16:17]
	s_add_i32 m0, s28, 0x2000
	s_add_i32 s28, s68, s38
	global_load_lds_dwordx4 v[166:167], off
	v_lshl_add_u64 v[166:167], v[220:221], 0, s[16:17]
	s_mov_b32 m0, s28
	s_nop 0
	global_load_lds_dwordx4 v[166:167], off
	v_lshl_add_u64 v[166:167], v[222:223], 0, s[16:17]
	s_add_i32 m0, s28, 0x2000
	s_nop 0
	global_load_lds_dwordx4 v[166:167], off
	v_lshl_add_u64 v[166:167], v[224:225], 0, s[16:17]
	s_mov_b32 m0, s53
	s_nop 0
	global_load_lds_dwordx4 v[166:167], off
	v_lshl_add_u64 v[166:167], v[226:227], 0, s[16:17]
	s_mov_b32 m0, s54
	s_nop 0
	global_load_lds_dwordx4 v[166:167], off
	s_waitcnt vmcnt(8)
	s_waitcnt lgkmcnt(0)
	s_barrier
	s_setprio 1
	v_mfma_i32_16x16x64_i8 v[62:65], v[148:151], v[186:189], v[62:65]
	v_mfma_i32_16x16x64_i8 v[58:61], v[158:161], v[186:189], v[58:61]
	v_mfma_i32_16x16x64_i8 v[54:57], v[148:151], v[194:197], v[54:57]
	v_mfma_i32_16x16x64_i8 v[50:53], v[158:161], v[194:197], v[50:53]
	v_mfma_i32_16x16x64_i8 v[42:45], v[148:151], v[202:205], v[42:45]
	v_mfma_i32_16x16x64_i8 v[34:37], v[158:161], v[202:205], v[34:37]
	v_mfma_i32_16x16x64_i8 v[26:29], v[148:151], v[210:213], v[26:29]
	v_mfma_i32_16x16x64_i8 v[18:21], v[158:161], v[210:213], v[18:21]
	v_mfma_i32_16x16x64_i8 v[62:65], v[152:155], v[190:193], v[62:65]
	v_mfma_i32_16x16x64_i8 v[58:61], v[162:165], v[190:193], v[58:61]
	v_mfma_i32_16x16x64_i8 v[54:57], v[152:155], v[198:201], v[54:57]
	v_mfma_i32_16x16x64_i8 v[50:53], v[162:165], v[198:201], v[50:53]
	v_mfma_i32_16x16x64_i8 v[42:45], v[152:155], v[206:209], v[42:45]
	v_mfma_i32_16x16x64_i8 v[34:37], v[162:165], v[206:209], v[34:37]
	v_mfma_i32_16x16x64_i8 v[26:29], v[152:155], v[214:217], v[26:29]
	v_mfma_i32_16x16x64_i8 v[18:21], v[162:165], v[214:217], v[18:21]
	v_mfma_i32_16x16x64_i8 v[46:49], v[170:173], v[186:189], v[46:49]
	v_mfma_i32_16x16x64_i8 v[38:41], v[178:181], v[186:189], v[38:41]
	v_mfma_i32_16x16x64_i8 v[30:33], v[170:173], v[194:197], v[30:33]
	v_mfma_i32_16x16x64_i8 v[22:25], v[178:181], v[194:197], v[22:25]
	v_mfma_i32_16x16x64_i8 v[14:17], v[170:173], v[202:205], v[14:17]
	v_mfma_i32_16x16x64_i8 v[10:13], v[178:181], v[202:205], v[10:13]
	v_mfma_i32_16x16x64_i8 v[6:9], v[170:173], v[210:213], v[6:9]
	v_mfma_i32_16x16x64_i8 v[2:5], v[178:181], v[210:213], v[2:5]
	v_mfma_i32_16x16x64_i8 v[46:49], v[174:177], v[190:193], v[46:49]
	v_mfma_i32_16x16x64_i8 v[38:41], v[182:185], v[190:193], v[38:41]
	v_mfma_i32_16x16x64_i8 v[30:33], v[174:177], v[198:201], v[30:33]
	v_mfma_i32_16x16x64_i8 v[22:25], v[182:185], v[198:201], v[22:25]
	v_mfma_i32_16x16x64_i8 v[14:17], v[174:177], v[206:209], v[14:17]
	v_mfma_i32_16x16x64_i8 v[10:13], v[182:185], v[206:209], v[10:13]
	v_mfma_i32_16x16x64_i8 v[6:9], v[174:177], v[214:217], v[6:9]
	v_mfma_i32_16x16x64_i8 v[2:5], v[182:185], v[214:217], v[2:5]
	s_setprio 0
	s_barrier
	s_add_u32 s26, s26, 0x100
	s_addc_u32 s27, s27, 0
	s_add_u32 s64, s64, 0x100
	s_addc_u32 s65, s65, 0
	s_cmp_ge_i32 s66, s50
	s_mov_b32 s28, s66
	s_cbranch_scc0 .LBB0_778
	v_cvt_f32_i32_e32 v162, v126
	v_cvt_f32_i32_e32 v163, v127
	v_cvt_f32_i32_e32 v160, v128
	v_cvt_f32_i32_e32 v161, v129
	v_cvt_f32_i32_e32 v164, v122
	v_cvt_f32_i32_e32 v165, v123
	v_cvt_f32_i32_e32 v166, v124
	v_cvt_f32_i32_e32 v167, v125
	v_cvt_f32_i32_e32 v148, v110
	v_cvt_f32_i32_e32 v149, v111
	v_cvt_f32_i32_e32 v150, v112
	v_cvt_f32_i32_e32 v151, v113
	v_cvt_f32_i32_e32 v126, v102
	v_cvt_f32_i32_e32 v127, v103
	v_cvt_f32_i32_e32 v128, v104
	v_cvt_f32_i32_e32 v129, v105
	v_cvt_f32_i32_e32 v122, v118
	v_cvt_f32_i32_e32 v123, v119
	v_cvt_f32_i32_e32 v124, v120
	v_cvt_f32_i32_e32 v125, v121
	v_cvt_f32_i32_e32 v118, v114
	v_cvt_f32_i32_e32 v119, v115
	v_cvt_f32_i32_e32 v120, v116
	v_cvt_f32_i32_e32 v121, v117
	v_cvt_f32_i32_e32 v112, v94
	v_cvt_f32_i32_e32 v113, v95
	v_cvt_f32_i32_e32 v116, v96
	v_cvt_f32_i32_e32 v117, v97
	v_cvt_f32_i32_e32 v110, v86
	v_cvt_f32_i32_e32 v111, v87
	v_cvt_f32_i32_e32 v114, v88
	v_cvt_f32_i32_e32 v115, v89
	v_cvt_f32_i32_e32 v96, v106
	v_cvt_f32_i32_e32 v97, v107
	v_cvt_f32_i32_e32 v102, v108
	v_cvt_f32_i32_e32 v103, v109
	v_cvt_f32_i32_e32 v94, v98
	v_cvt_f32_i32_e32 v95, v99
	v_cvt_f32_i32_e32 v98, v100
	v_cvt_f32_i32_e32 v99, v101
	v_cvt_f32_i32_e32 v104, v78
	v_cvt_f32_i32_e32 v105, v79
	v_cvt_f32_i32_e32 v108, v80
	v_cvt_f32_i32_e32 v109, v81
	v_cvt_f32_i32_e32 v100, v74
	v_cvt_f32_i32_e32 v101, v75
	v_cvt_f32_i32_e32 v106, v76
	v_cvt_f32_i32_e32 v107, v77
	v_cvt_f32_i32_e32 v76, v90
	v_cvt_f32_i32_e32 v77, v91
	v_cvt_f32_i32_e32 v80, v92
	v_cvt_f32_i32_e32 v81, v93
	v_cvt_f32_i32_e32 v74, v82
	v_cvt_f32_i32_e32 v75, v83
	v_cvt_f32_i32_e32 v78, v84
	v_cvt_f32_i32_e32 v79, v85
	v_cvt_f32_i32_e32 v82, v70
	v_cvt_f32_i32_e32 v83, v71
	v_cvt_f32_i32_e32 v88, v72
	v_cvt_f32_i32_e32 v89, v73
	v_cvt_f32_i32_e32 v70, v66
	v_cvt_f32_i32_e32 v71, v67
	v_cvt_f32_i32_e32 v86, v68
	v_cvt_f32_i32_e32 v87, v69
	v_cvt_f32_i32_e32 v66, v62
	v_cvt_f32_i32_e32 v67, v63
	v_cvt_f32_i32_e32 v68, v64
	v_cvt_f32_i32_e32 v69, v65
	v_cvt_f32_i32_e32 v62, v58
	v_cvt_f32_i32_e32 v63, v59
	v_cvt_f32_i32_e32 v64, v60
	v_cvt_f32_i32_e32 v65, v61
	v_cvt_f32_i32_e32 v84, v46
	v_cvt_f32_i32_e32 v85, v47
	v_cvt_f32_i32_e32 v92, v48
	v_cvt_f32_i32_e32 v93, v49
	v_cvt_f32_i32_e32 v72, v38
	v_cvt_f32_i32_e32 v73, v39
	v_cvt_f32_i32_e32 v90, v40
	v_cvt_f32_i32_e32 v91, v41
	v_cvt_f32_i32_e32 v48, v54
	v_cvt_f32_i32_e32 v49, v55
	v_cvt_f32_i32_e32 v54, v56
	v_cvt_f32_i32_e32 v55, v57
	v_cvt_f32_i32_e32 v46, v50
	v_cvt_f32_i32_e32 v47, v51
	v_cvt_f32_i32_e32 v50, v52
	v_cvt_f32_i32_e32 v51, v53
	v_cvt_f32_i32_e32 v56, v30
	v_cvt_f32_i32_e32 v57, v31
	v_cvt_f32_i32_e32 v60, v32
	v_cvt_f32_i32_e32 v61, v33
	v_cvt_f32_i32_e32 v52, v22
	v_cvt_f32_i32_e32 v53, v23
	v_cvt_f32_i32_e32 v58, v24
	v_cvt_f32_i32_e32 v59, v25
	v_cvt_f32_i32_e32 v24, v42
	v_cvt_f32_i32_e32 v25, v43
	v_cvt_f32_i32_e32 v32, v44
	v_cvt_f32_i32_e32 v33, v45
	v_cvt_f32_i32_e32 v22, v34
	v_cvt_f32_i32_e32 v23, v35
	v_cvt_f32_i32_e32 v30, v36
	v_cvt_f32_i32_e32 v31, v37
	v_cvt_f32_i32_e32 v36, v14
	v_cvt_f32_i32_e32 v37, v15
	v_cvt_f32_i32_e32 v40, v16
	v_cvt_f32_i32_e32 v41, v17
	v_cvt_f32_i32_e32 v34, v10
	v_cvt_f32_i32_e32 v35, v11
	v_cvt_f32_i32_e32 v38, v12
	v_cvt_f32_i32_e32 v39, v13
	v_cvt_f32_i32_e32 v12, v26
	v_cvt_f32_i32_e32 v13, v27
	v_cvt_f32_i32_e32 v16, v28
	v_cvt_f32_i32_e32 v17, v29
	v_cvt_f32_i32_e32 v10, v18
	v_cvt_f32_i32_e32 v11, v19
	v_cvt_f32_i32_e32 v14, v20
	v_cvt_f32_i32_e32 v15, v21
	v_cvt_f32_i32_e32 v6, v6
	v_cvt_f32_i32_e32 v7, v7
	v_cvt_f32_i32_e32 v8, v8
	v_cvt_f32_i32_e32 v9, v9
	v_cvt_f32_i32_e32 v2, v2
	v_cvt_f32_i32_e32 v3, v3
	v_cvt_f32_i32_e32 v4, v4
	v_cvt_f32_i32_e32 v5, v5

.LBB0_800:
	v_add_u32_e32 v138, s55, v1
	ds_read_b128 v[148:151], v138
	ds_read_b128 v[152:155], v138 offset:1024
	ds_read_b128 v[158:161], v138 offset:2048
	ds_read_b128 v[162:165], v138 offset:3072
	v_add_u32_e32 v138, s56, v1
	ds_read_b128 v[170:173], v138
	ds_read_b128 v[174:177], v138 offset:1024
	ds_read_b128 v[178:181], v138 offset:2048
	ds_read_b128 v[182:185], v138 offset:3072
	s_add_i32 s63, s28, 2
	s_add_u32 s64, s26, 0x80
	s_addc_u32 s29, s27, 0
	s_cmp_eq_u32 s53, s28
	s_cselect_b32 s28, s2, s64
	s_cselect_b32 s29, s3, s29
	s_cselect_b32 s65, s25, s62
	s_cselect_b32 s64, s24, s61
	v_lshl_add_u64 v[166:167], s[26:27], 0, v[140:141]
	s_add_i32 m0, s39, 0xc000
	ds_read_b128 v[186:189], v157
	ds_read_b128 v[190:193], v157 offset:1024
	ds_read_b128 v[194:197], v157 offset:2048
	ds_read_b128 v[198:201], v157 offset:3072
	ds_read_b128 v[202:205], v157 offset:4096
	ds_read_b128 v[206:209], v157 offset:5120
	ds_read_b128 v[210:213], v157 offset:6144
	ds_read_b128 v[214:217], v157 offset:7168
	global_load_lds_dwordx4 v[166:167], off
	v_lshl_add_u64 v[166:167], s[26:27], 0, v[142:143]
	s_add_i32 m0, s39, 0xe000
	s_nop 0
	global_load_lds_dwordx4 v[166:167], off
	s_waitcnt vmcnt(8)
	s_waitcnt lgkmcnt(0)
	s_barrier
	s_setprio 1
	v_mfma_i32_16x16x64_i8 v[126:129], v[148:151], v[186:189], v[126:129]
	v_mfma_i32_16x16x64_i8 v[122:125], v[158:161], v[186:189], v[122:125]
	v_mfma_i32_16x16x64_i8 v[118:121], v[148:151], v[194:197], v[118:121]
	v_mfma_i32_16x16x64_i8 v[114:117], v[158:161], v[194:197], v[114:117]
	v_mfma_i32_16x16x64_i8 v[106:109], v[148:151], v[202:205], v[106:109]
	v_mfma_i32_16x16x64_i8 v[98:101], v[158:161], v[202:205], v[98:101]
	v_mfma_i32_16x16x64_i8 v[90:93], v[148:151], v[210:213], v[90:93]
	v_mfma_i32_16x16x64_i8 v[82:85], v[158:161], v[210:213], v[82:85]
	v_mfma_i32_16x16x64_i8 v[126:129], v[152:155], v[190:193], v[126:129]
	v_mfma_i32_16x16x64_i8 v[122:125], v[162:165], v[190:193], v[122:125]
	v_mfma_i32_16x16x64_i8 v[118:121], v[152:155], v[198:201], v[118:121]
	v_mfma_i32_16x16x64_i8 v[114:117], v[162:165], v[198:201], v[114:117]
	v_mfma_i32_16x16x64_i8 v[106:109], v[152:155], v[206:209], v[106:109]
	v_mfma_i32_16x16x64_i8 v[98:101], v[162:165], v[206:209], v[98:101]
	v_mfma_i32_16x16x64_i8 v[90:93], v[152:155], v[214:217], v[90:93]
	v_mfma_i32_16x16x64_i8 v[82:85], v[162:165], v[214:217], v[82:85]
	v_mfma_i32_16x16x64_i8 v[110:113], v[170:173], v[186:189], v[110:113]
	v_mfma_i32_16x16x64_i8 v[102:105], v[178:181], v[186:189], v[102:105]
	v_mfma_i32_16x16x64_i8 v[94:97], v[170:173], v[194:197], v[94:97]
	v_mfma_i32_16x16x64_i8 v[86:89], v[178:181], v[194:197], v[86:89]
	v_mfma_i32_16x16x64_i8 v[78:81], v[170:173], v[202:205], v[78:81]
	v_mfma_i32_16x16x64_i8 v[74:77], v[178:181], v[202:205], v[74:77]
	v_mfma_i32_16x16x64_i8 v[70:73], v[170:173], v[210:213], v[70:73]
	v_mfma_i32_16x16x64_i8 v[66:69], v[178:181], v[210:213], v[66:69]
	v_mfma_i32_16x16x64_i8 v[110:113], v[174:177], v[190:193], v[110:113]
	v_mfma_i32_16x16x64_i8 v[102:105], v[182:185], v[190:193], v[102:105]
	v_mfma_i32_16x16x64_i8 v[94:97], v[174:177], v[198:201], v[94:97]
	v_mfma_i32_16x16x64_i8 v[86:89], v[182:185], v[198:201], v[86:89]
	v_mfma_i32_16x16x64_i8 v[78:81], v[174:177], v[206:209], v[78:81]
	v_mfma_i32_16x16x64_i8 v[74:77], v[182:185], v[206:209], v[74:77]
	v_mfma_i32_16x16x64_i8 v[70:73], v[174:177], v[214:217], v[70:73]
	v_mfma_i32_16x16x64_i8 v[66:69], v[182:185], v[214:217], v[66:69]
	s_setprio 0
	s_barrier
	s_add_i32 s66, s55, s36
	v_lshl_add_u64 v[166:167], s[64:65], 0, v[134:135]
	s_mov_b32 m0, s66
	ds_read_b128 v[186:189], v157 offset:16384
	ds_read_b128 v[190:193], v157 offset:17408
	ds_read_b128 v[194:197], v157 offset:18432
	ds_read_b128 v[198:201], v157 offset:19456
	ds_read_b128 v[202:205], v157 offset:20480
	ds_read_b128 v[206:209], v157 offset:21504
	ds_read_b128 v[210:213], v157 offset:22528
	ds_read_b128 v[214:217], v157 offset:23552
	global_load_lds_dwordx4 v[166:167], off
	s_add_i32 m0, s66, 0x2000
	v_lshl_add_u64 v[218:219], s[64:65], 0, v[130:131]
	s_add_u32 s64, s64, s6
	s_addc_u32 s65, s65, s7
	s_add_i32 s66, s56, s36
	global_load_lds_dwordx4 v[218:219], off
	v_lshl_add_u64 v[220:221], s[64:65], 0, v[134:135]
	s_mov_b32 m0, s66
	v_lshl_add_u64 v[222:223], s[64:65], 0, v[130:131]
	global_load_lds_dwordx4 v[220:221], off
	s_add_i32 m0, s66, 0x2000
	v_lshl_add_u64 v[224:225], s[28:29], 0, v[136:137]
	global_load_lds_dwordx4 v[222:223], off
	s_mov_b32 m0, s39
	v_lshl_add_u64 v[226:227], s[28:29], 0, v[132:133]
	global_load_lds_dwordx4 v[224:225], off
	s_mov_b32 m0, s42
	s_nop 0
	global_load_lds_dwordx4 v[226:227], off
	s_waitcnt vmcnt(8)
	s_waitcnt lgkmcnt(0)
	s_barrier
	s_setprio 1
	v_mfma_i32_16x16x64_i8 v[62:65], v[148:151], v[186:189], v[62:65]
	v_mfma_i32_16x16x64_i8 v[58:61], v[158:161], v[186:189], v[58:61]
	v_mfma_i32_16x16x64_i8 v[54:57], v[148:151], v[194:197], v[54:57]
	v_mfma_i32_16x16x64_i8 v[50:53], v[158:161], v[194:197], v[50:53]
	v_mfma_i32_16x16x64_i8 v[42:45], v[148:151], v[202:205], v[42:45]
	v_mfma_i32_16x16x64_i8 v[34:37], v[158:161], v[202:205], v[34:37]
	v_mfma_i32_16x16x64_i8 v[26:29], v[148:151], v[210:213], v[26:29]
	v_mfma_i32_16x16x64_i8 v[18:21], v[158:161], v[210:213], v[18:21]
	v_mfma_i32_16x16x64_i8 v[62:65], v[152:155], v[190:193], v[62:65]
	v_mfma_i32_16x16x64_i8 v[58:61], v[162:165], v[190:193], v[58:61]
	v_mfma_i32_16x16x64_i8 v[54:57], v[152:155], v[198:201], v[54:57]
	v_mfma_i32_16x16x64_i8 v[50:53], v[162:165], v[198:201], v[50:53]
	v_mfma_i32_16x16x64_i8 v[42:45], v[152:155], v[206:209], v[42:45]
	v_mfma_i32_16x16x64_i8 v[34:37], v[162:165], v[206:209], v[34:37]
	v_mfma_i32_16x16x64_i8 v[26:29], v[152:155], v[214:217], v[26:29]
	v_mfma_i32_16x16x64_i8 v[18:21], v[162:165], v[214:217], v[18:21]
	v_mfma_i32_16x16x64_i8 v[46:49], v[170:173], v[186:189], v[46:49]
	v_mfma_i32_16x16x64_i8 v[38:41], v[178:181], v[186:189], v[38:41]
	v_mfma_i32_16x16x64_i8 v[30:33], v[170:173], v[194:197], v[30:33]
	v_mfma_i32_16x16x64_i8 v[22:25], v[178:181], v[194:197], v[22:25]
	v_mfma_i32_16x16x64_i8 v[14:17], v[170:173], v[202:205], v[14:17]
	v_mfma_i32_16x16x64_i8 v[10:13], v[178:181], v[202:205], v[10:13]
	v_mfma_i32_16x16x64_i8 v[6:9], v[170:173], v[210:213], v[6:9]
	v_mfma_i32_16x16x64_i8 v[2:5], v[178:181], v[210:213], v[2:5]
	v_mfma_i32_16x16x64_i8 v[46:49], v[174:177], v[190:193], v[46:49]
	v_mfma_i32_16x16x64_i8 v[38:41], v[182:185], v[190:193], v[38:41]
	v_mfma_i32_16x16x64_i8 v[30:33], v[174:177], v[198:201], v[30:33]
	v_mfma_i32_16x16x64_i8 v[22:25], v[182:185], v[198:201], v[22:25]
	v_mfma_i32_16x16x64_i8 v[14:17], v[174:177], v[206:209], v[14:17]
	v_mfma_i32_16x16x64_i8 v[10:13], v[182:185], v[206:209], v[10:13]
	v_mfma_i32_16x16x64_i8 v[6:9], v[174:177], v[214:217], v[6:9]
	v_mfma_i32_16x16x64_i8 v[2:5], v[182:185], v[214:217], v[2:5]
	s_setprio 0
	s_barrier
	s_add_i32 s64, 0, 0x18000
	v_add_u32_e32 v138, s64, v1
	s_add_i32 s65, 0, 0x1c000
	ds_read_b128 v[148:151], v138
	ds_read_b128 v[152:155], v138 offset:1024
	ds_read_b128 v[158:161], v138 offset:2048
	ds_read_b128 v[162:165], v138 offset:3072
	v_add_u32_e32 v138, s65, v1
	ds_read_b128 v[170:173], v138
	ds_read_b128 v[174:177], v138 offset:1024
	ds_read_b128 v[178:181], v138 offset:2048
	ds_read_b128 v[182:185], v138 offset:3072
	s_add_u32 s28, s28, s6
	s_addc_u32 s29, s29, s7
	s_mov_b32 m0, s43
	v_lshl_add_u64 v[228:229], s[28:29], 0, v[136:137]
	ds_read_b128 v[186:189], v157 offset:32768
	ds_read_b128 v[190:193], v157 offset:33792
	ds_read_b128 v[194:197], v157 offset:34816
	ds_read_b128 v[198:201], v157 offset:35840
	ds_read_b128 v[202:205], v157 offset:36864
	ds_read_b128 v[206:209], v157 offset:37888
	ds_read_b128 v[210:213], v157 offset:38912
	ds_read_b128 v[214:217], v157 offset:39936
	global_load_lds_dwordx4 v[228:229], off
	v_lshl_add_u64 v[228:229], s[28:29], 0, v[132:133]
	s_mov_b32 m0, s44
	s_nop 0
	global_load_lds_dwordx4 v[228:229], off
	s_waitcnt vmcnt(8)
	s_waitcnt lgkmcnt(0)
	s_barrier
	s_setprio 1
	v_mfma_i32_16x16x64_i8 v[126:129], v[148:151], v[186:189], v[126:129]
	v_mfma_i32_16x16x64_i8 v[122:125], v[158:161], v[186:189], v[122:125]
	v_mfma_i32_16x16x64_i8 v[118:121], v[148:151], v[194:197], v[118:121]
	v_mfma_i32_16x16x64_i8 v[114:117], v[158:161], v[194:197], v[114:117]
	v_mfma_i32_16x16x64_i8 v[106:109], v[148:151], v[202:205], v[106:109]
	v_mfma_i32_16x16x64_i8 v[98:101], v[158:161], v[202:205], v[98:101]
	v_mfma_i32_16x16x64_i8 v[90:93], v[148:151], v[210:213], v[90:93]
	v_mfma_i32_16x16x64_i8 v[82:85], v[158:161], v[210:213], v[82:85]
	v_mfma_i32_16x16x64_i8 v[126:129], v[152:155], v[190:193], v[126:129]
	v_mfma_i32_16x16x64_i8 v[122:125], v[162:165], v[190:193], v[122:125]
	v_mfma_i32_16x16x64_i8 v[118:121], v[152:155], v[198:201], v[118:121]
	v_mfma_i32_16x16x64_i8 v[114:117], v[162:165], v[198:201], v[114:117]
	v_mfma_i32_16x16x64_i8 v[106:109], v[152:155], v[206:209], v[106:109]
	v_mfma_i32_16x16x64_i8 v[98:101], v[162:165], v[206:209], v[98:101]
	v_mfma_i32_16x16x64_i8 v[90:93], v[152:155], v[214:217], v[90:93]
	v_mfma_i32_16x16x64_i8 v[82:85], v[162:165], v[214:217], v[82:85]
	v_mfma_i32_16x16x64_i8 v[110:113], v[170:173], v[186:189], v[110:113]
	v_mfma_i32_16x16x64_i8 v[102:105], v[178:181], v[186:189], v[102:105]
	v_mfma_i32_16x16x64_i8 v[94:97], v[170:173], v[194:197], v[94:97]
	v_mfma_i32_16x16x64_i8 v[86:89], v[178:181], v[194:197], v[86:89]
	v_mfma_i32_16x16x64_i8 v[78:81], v[170:173], v[202:205], v[78:81]
	v_mfma_i32_16x16x64_i8 v[74:77], v[178:181], v[202:205], v[74:77]
	v_mfma_i32_16x16x64_i8 v[70:73], v[170:173], v[210:213], v[70:73]
	v_mfma_i32_16x16x64_i8 v[66:69], v[178:181], v[210:213], v[66:69]
	v_mfma_i32_16x16x64_i8 v[110:113], v[174:177], v[190:193], v[110:113]
	v_mfma_i32_16x16x64_i8 v[102:105], v[182:185], v[190:193], v[102:105]
	v_mfma_i32_16x16x64_i8 v[94:97], v[174:177], v[198:201], v[94:97]
	v_mfma_i32_16x16x64_i8 v[86:89], v[182:185], v[198:201], v[86:89]
	v_mfma_i32_16x16x64_i8 v[78:81], v[174:177], v[206:209], v[78:81]
	v_mfma_i32_16x16x64_i8 v[74:77], v[182:185], v[206:209], v[74:77]
	v_mfma_i32_16x16x64_i8 v[70:73], v[174:177], v[214:217], v[70:73]
	v_mfma_i32_16x16x64_i8 v[66:69], v[182:185], v[214:217], v[66:69]
	s_setprio 0
	s_barrier
	s_add_i32 s28, s64, s36
	v_lshl_add_u64 v[166:167], v[166:167], 0, s[16:17]
	s_mov_b32 m0, s28
	ds_read_b128 v[186:189], v157 offset:49152
	ds_read_b128 v[190:193], v157 offset:50176
	ds_read_b128 v[194:197], v157 offset:51200
	ds_read_b128 v[198:201], v157 offset:52224
	ds_read_b128 v[202:205], v157 offset:53248
	ds_read_b128 v[206:209], v157 offset:54272
	ds_read_b128 v[210:213], v157 offset:55296
	ds_read_b128 v[214:217], v157 offset:56320
	global_load_lds_dwordx4 v[166:167], off
	v_lshl_add_u64 v[166:167], v[218:219], 0, s[16:17]
	s_add_i32 m0, s28, 0x2000
	s_add_i32 s28, s65, s36
	global_load_lds_dwordx4 v[166:167], off
	v_lshl_add_u64 v[166:167], v[220:221], 0, s[16:17]
	s_mov_b32 m0, s28
	s_nop 0
	global_load_lds_dwordx4 v[166:167], off
	v_lshl_add_u64 v[166:167], v[222:223], 0, s[16:17]
	s_add_i32 m0, s28, 0x2000
	s_nop 0
	global_load_lds_dwordx4 v[166:167], off
	v_lshl_add_u64 v[166:167], v[224:225], 0, s[16:17]
	s_mov_b32 m0, s51
	s_nop 0
	global_load_lds_dwordx4 v[166:167], off
	v_lshl_add_u64 v[166:167], v[226:227], 0, s[16:17]
	s_mov_b32 m0, s52
	s_nop 0
	global_load_lds_dwordx4 v[166:167], off
	s_waitcnt vmcnt(8)
	s_waitcnt lgkmcnt(0)
	s_barrier
	s_setprio 1
	v_mfma_i32_16x16x64_i8 v[62:65], v[148:151], v[186:189], v[62:65]
	v_mfma_i32_16x16x64_i8 v[58:61], v[158:161], v[186:189], v[58:61]
	v_mfma_i32_16x16x64_i8 v[54:57], v[148:151], v[194:197], v[54:57]
	v_mfma_i32_16x16x64_i8 v[50:53], v[158:161], v[194:197], v[50:53]
	v_mfma_i32_16x16x64_i8 v[42:45], v[148:151], v[202:205], v[42:45]
	v_mfma_i32_16x16x64_i8 v[34:37], v[158:161], v[202:205], v[34:37]
	v_mfma_i32_16x16x64_i8 v[26:29], v[148:151], v[210:213], v[26:29]
	v_mfma_i32_16x16x64_i8 v[18:21], v[158:161], v[210:213], v[18:21]
	v_mfma_i32_16x16x64_i8 v[62:65], v[152:155], v[190:193], v[62:65]
	v_mfma_i32_16x16x64_i8 v[58:61], v[162:165], v[190:193], v[58:61]
	v_mfma_i32_16x16x64_i8 v[54:57], v[152:155], v[198:201], v[54:57]
	v_mfma_i32_16x16x64_i8 v[50:53], v[162:165], v[198:201], v[50:53]
	v_mfma_i32_16x16x64_i8 v[42:45], v[152:155], v[206:209], v[42:45]
	v_mfma_i32_16x16x64_i8 v[34:37], v[162:165], v[206:209], v[34:37]
	v_mfma_i32_16x16x64_i8 v[26:29], v[152:155], v[214:217], v[26:29]
	v_mfma_i32_16x16x64_i8 v[18:21], v[162:165], v[214:217], v[18:21]
	v_mfma_i32_16x16x64_i8 v[46:49], v[170:173], v[186:189], v[46:49]
	v_mfma_i32_16x16x64_i8 v[38:41], v[178:181], v[186:189], v[38:41]
	v_mfma_i32_16x16x64_i8 v[30:33], v[170:173], v[194:197], v[30:33]
	v_mfma_i32_16x16x64_i8 v[22:25], v[178:181], v[194:197], v[22:25]
	v_mfma_i32_16x16x64_i8 v[14:17], v[170:173], v[202:205], v[14:17]
	v_mfma_i32_16x16x64_i8 v[10:13], v[178:181], v[202:205], v[10:13]
	v_mfma_i32_16x16x64_i8 v[6:9], v[170:173], v[210:213], v[6:9]
	v_mfma_i32_16x16x64_i8 v[2:5], v[178:181], v[210:213], v[2:5]
	v_mfma_i32_16x16x64_i8 v[46:49], v[174:177], v[190:193], v[46:49]
	v_mfma_i32_16x16x64_i8 v[38:41], v[182:185], v[190:193], v[38:41]
	v_mfma_i32_16x16x64_i8 v[30:33], v[174:177], v[198:201], v[30:33]
	v_mfma_i32_16x16x64_i8 v[22:25], v[182:185], v[198:201], v[22:25]
	v_mfma_i32_16x16x64_i8 v[14:17], v[174:177], v[206:209], v[14:17]
	v_mfma_i32_16x16x64_i8 v[10:13], v[182:185], v[206:209], v[10:13]
	v_mfma_i32_16x16x64_i8 v[6:9], v[174:177], v[214:217], v[6:9]
	v_mfma_i32_16x16x64_i8 v[2:5], v[182:185], v[214:217], v[2:5]
	s_setprio 0
	s_barrier
	s_add_u32 s26, s26, 0x100
	s_addc_u32 s27, s27, 0
	s_add_u32 s61, s61, 0x100
	s_addc_u32 s62, s62, 0
	s_cmp_ge_i32 s63, s48
	s_mov_b32 s28, s63
	s_cbranch_scc0 .LBB0_800
	v_cvt_f32_i32_e32 v172, v126
	v_cvt_f32_i32_e32 v173, v127
	v_cvt_f32_i32_e32 v166, v128
	v_cvt_f32_i32_e32 v167, v129
	v_cvt_f32_i32_e32 v174, v122
	v_cvt_f32_i32_e32 v175, v123
	v_cvt_f32_i32_e32 v176, v124
	v_cvt_f32_i32_e32 v177, v125
	v_cvt_f32_i32_e32 v158, v110
	v_cvt_f32_i32_e32 v159, v111
	v_cvt_f32_i32_e32 v160, v112
	v_cvt_f32_i32_e32 v161, v113
	v_cvt_f32_i32_e32 v162, v102
	v_cvt_f32_i32_e32 v163, v103
	v_cvt_f32_i32_e32 v164, v104
	v_cvt_f32_i32_e32 v165, v105
	v_cvt_f32_i32_e32 v148, v118
	v_cvt_f32_i32_e32 v149, v119
	v_cvt_f32_i32_e32 v150, v120
	v_cvt_f32_i32_e32 v151, v121
	v_cvt_f32_i32_e32 v152, v114
	v_cvt_f32_i32_e32 v153, v115
	v_cvt_f32_i32_e32 v154, v116
	v_cvt_f32_i32_e32 v155, v117
	v_cvt_f32_i32_e32 v112, v94
	v_cvt_f32_i32_e32 v113, v95
	v_cvt_f32_i32_e32 v116, v96
	v_cvt_f32_i32_e32 v117, v97
	v_cvt_f32_i32_e32 v110, v86
	v_cvt_f32_i32_e32 v111, v87
	v_cvt_f32_i32_e32 v114, v88
	v_cvt_f32_i32_e32 v115, v89
	v_cvt_f32_i32_e32 v96, v106
	v_cvt_f32_i32_e32 v97, v107
	v_cvt_f32_i32_e32 v102, v108
	v_cvt_f32_i32_e32 v103, v109
	v_cvt_f32_i32_e32 v94, v98
	v_cvt_f32_i32_e32 v95, v99
	v_cvt_f32_i32_e32 v98, v100
	v_cvt_f32_i32_e32 v99, v101
	v_cvt_f32_i32_e32 v104, v78
	v_cvt_f32_i32_e32 v105, v79
	v_cvt_f32_i32_e32 v108, v80
	v_cvt_f32_i32_e32 v109, v81
	v_cvt_f32_i32_e32 v100, v74
	v_cvt_f32_i32_e32 v101, v75
	v_cvt_f32_i32_e32 v106, v76
	v_cvt_f32_i32_e32 v107, v77
	v_cvt_f32_i32_e32 v76, v90
	v_cvt_f32_i32_e32 v77, v91
	v_cvt_f32_i32_e32 v80, v92
	v_cvt_f32_i32_e32 v81, v93
	v_cvt_f32_i32_e32 v74, v82
	v_cvt_f32_i32_e32 v75, v83
	v_cvt_f32_i32_e32 v78, v84
	v_cvt_f32_i32_e32 v79, v85
	v_cvt_f32_i32_e32 v84, v70
	v_cvt_f32_i32_e32 v85, v71
	v_cvt_f32_i32_e32 v92, v72
	v_cvt_f32_i32_e32 v93, v73
	v_cvt_f32_i32_e32 v82, v66
	v_cvt_f32_i32_e32 v83, v67
	v_cvt_f32_i32_e32 v90, v68
	v_cvt_f32_i32_e32 v91, v69
	v_cvt_f32_i32_e32 v66, v62
	v_cvt_f32_i32_e32 v67, v63
	v_cvt_f32_i32_e32 v68, v64
	v_cvt_f32_i32_e32 v69, v65
	v_cvt_f32_i32_e32 v62, v58
	v_cvt_f32_i32_e32 v63, v59
	v_cvt_f32_i32_e32 v64, v60
	v_cvt_f32_i32_e32 v65, v61
	v_cvt_f32_i32_e32 v72, v46
	v_cvt_f32_i32_e32 v73, v47
	v_cvt_f32_i32_e32 v88, v48
	v_cvt_f32_i32_e32 v89, v49
	v_cvt_f32_i32_e32 v70, v38
	v_cvt_f32_i32_e32 v71, v39
	v_cvt_f32_i32_e32 v86, v40
	v_cvt_f32_i32_e32 v87, v41
	v_cvt_f32_i32_e32 v48, v54
	v_cvt_f32_i32_e32 v49, v55
	v_cvt_f32_i32_e32 v54, v56
	v_cvt_f32_i32_e32 v55, v57
	v_cvt_f32_i32_e32 v46, v50
	v_cvt_f32_i32_e32 v47, v51
	v_cvt_f32_i32_e32 v50, v52
	v_cvt_f32_i32_e32 v51, v53
	v_cvt_f32_i32_e32 v56, v30
	v_cvt_f32_i32_e32 v57, v31
	v_cvt_f32_i32_e32 v60, v32
	v_cvt_f32_i32_e32 v61, v33
	v_cvt_f32_i32_e32 v52, v22
	v_cvt_f32_i32_e32 v53, v23
	v_cvt_f32_i32_e32 v58, v24
	v_cvt_f32_i32_e32 v59, v25
	v_cvt_f32_i32_e32 v24, v42
	v_cvt_f32_i32_e32 v25, v43
	v_cvt_f32_i32_e32 v32, v44
	v_cvt_f32_i32_e32 v33, v45
	v_cvt_f32_i32_e32 v22, v34
	v_cvt_f32_i32_e32 v23, v35
	v_cvt_f32_i32_e32 v30, v36
	v_cvt_f32_i32_e32 v31, v37
	v_cvt_f32_i32_e32 v36, v14
	v_cvt_f32_i32_e32 v37, v15
	v_cvt_f32_i32_e32 v40, v16
	v_cvt_f32_i32_e32 v41, v17
	v_cvt_f32_i32_e32 v34, v10
	v_cvt_f32_i32_e32 v35, v11
	v_cvt_f32_i32_e32 v38, v12
	v_cvt_f32_i32_e32 v39, v13
	v_cvt_f32_i32_e32 v12, v26
	v_cvt_f32_i32_e32 v13, v27
	v_cvt_f32_i32_e32 v16, v28
	v_cvt_f32_i32_e32 v17, v29
	v_cvt_f32_i32_e32 v10, v18
	v_cvt_f32_i32_e32 v11, v19
	v_cvt_f32_i32_e32 v14, v20
	v_cvt_f32_i32_e32 v15, v21
	v_cvt_f32_i32_e32 v18, v6
	v_cvt_f32_i32_e32 v19, v7
	v_cvt_f32_i32_e32 v20, v8
	v_cvt_f32_i32_e32 v21, v9
	v_cvt_f32_i32_e32 v6, v2
	v_cvt_f32_i32_e32 v7, v3
	v_cvt_f32_i32_e32 v8, v4
	v_cvt_f32_i32_e32 v9, v5

.LBB0_1297:
	v_add_u32_e32 v138, s77, v1
	ds_read_b128 v[148:151], v138
	ds_read_b128 v[152:155], v138 offset:1024
	ds_read_b128 v[156:159], v138 offset:2048
	ds_read_b128 v[160:163], v138 offset:3072
	v_add_u32_e32 v138, s78, v1
	ds_read_b128 v[164:167], v138
	ds_read_b128 v[170:173], v138 offset:1024
	ds_read_b128 v[174:177], v138 offset:2048
	ds_read_b128 v[178:181], v138 offset:3072
	s_add_i32 s46, s6, 2
	s_add_u32 s47, s4, 0x80
	s_addc_u32 s7, s5, 0
	s_cmp_eq_u32 s55, s6
	s_cselect_b32 s6, s40, s47
	s_cselect_b32 s7, s41, s7
	s_cselect_b32 s51, s43, s45
	s_cselect_b32 s50, s42, s44
	v_lshl_add_u64 v[198:199], s[4:5], 0, v[140:141]
	s_add_i32 m0, s70, 0xc000
	ds_read_b128 v[182:185], v169
	ds_read_b128 v[186:189], v169 offset:1024
	ds_read_b128 v[190:193], v169 offset:2048
	ds_read_b128 v[194:197], v169 offset:3072
	ds_read_b128 v[202:205], v169 offset:4096
	ds_read_b128 v[206:209], v169 offset:5120
	ds_read_b128 v[210:213], v169 offset:6144
	ds_read_b128 v[214:217], v169 offset:7168
	global_load_lds_dwordx4 v[198:199], off
	v_lshl_add_u64 v[198:199], s[4:5], 0, v[142:143]
	s_add_i32 m0, s70, 0xe000
	s_nop 0
	global_load_lds_dwordx4 v[198:199], off
	s_waitcnt vmcnt(8)
	s_waitcnt lgkmcnt(0)
	s_barrier
	s_setprio 1
	v_mfma_i32_16x16x64_i8 v[126:129], v[148:151], v[182:185], v[126:129]
	v_mfma_i32_16x16x64_i8 v[122:125], v[156:159], v[182:185], v[122:125]
	v_mfma_i32_16x16x64_i8 v[118:121], v[148:151], v[190:193], v[118:121]
	v_mfma_i32_16x16x64_i8 v[114:117], v[156:159], v[190:193], v[114:117]
	v_mfma_i32_16x16x64_i8 v[106:109], v[148:151], v[202:205], v[106:109]
	v_mfma_i32_16x16x64_i8 v[98:101], v[156:159], v[202:205], v[98:101]
	v_mfma_i32_16x16x64_i8 v[90:93], v[148:151], v[210:213], v[90:93]
	v_mfma_i32_16x16x64_i8 v[82:85], v[156:159], v[210:213], v[82:85]
	v_mfma_i32_16x16x64_i8 v[126:129], v[152:155], v[186:189], v[126:129]
	v_mfma_i32_16x16x64_i8 v[122:125], v[160:163], v[186:189], v[122:125]
	v_mfma_i32_16x16x64_i8 v[118:121], v[152:155], v[194:197], v[118:121]
	v_mfma_i32_16x16x64_i8 v[114:117], v[160:163], v[194:197], v[114:117]
	v_mfma_i32_16x16x64_i8 v[106:109], v[152:155], v[206:209], v[106:109]
	v_mfma_i32_16x16x64_i8 v[98:101], v[160:163], v[206:209], v[98:101]
	v_mfma_i32_16x16x64_i8 v[90:93], v[152:155], v[214:217], v[90:93]
	v_mfma_i32_16x16x64_i8 v[82:85], v[160:163], v[214:217], v[82:85]
	v_mfma_i32_16x16x64_i8 v[110:113], v[164:167], v[182:185], v[110:113]
	v_mfma_i32_16x16x64_i8 v[102:105], v[174:177], v[182:185], v[102:105]
	v_mfma_i32_16x16x64_i8 v[94:97], v[164:167], v[190:193], v[94:97]
	v_mfma_i32_16x16x64_i8 v[86:89], v[174:177], v[190:193], v[86:89]
	v_mfma_i32_16x16x64_i8 v[78:81], v[164:167], v[202:205], v[78:81]
	v_mfma_i32_16x16x64_i8 v[74:77], v[174:177], v[202:205], v[74:77]
	v_mfma_i32_16x16x64_i8 v[70:73], v[164:167], v[210:213], v[70:73]
	v_mfma_i32_16x16x64_i8 v[66:69], v[174:177], v[210:213], v[66:69]
	v_mfma_i32_16x16x64_i8 v[110:113], v[170:173], v[186:189], v[110:113]
	v_mfma_i32_16x16x64_i8 v[102:105], v[178:181], v[186:189], v[102:105]
	v_mfma_i32_16x16x64_i8 v[94:97], v[170:173], v[194:197], v[94:97]
	v_mfma_i32_16x16x64_i8 v[86:89], v[178:181], v[194:197], v[86:89]
	v_mfma_i32_16x16x64_i8 v[78:81], v[170:173], v[206:209], v[78:81]
	v_mfma_i32_16x16x64_i8 v[74:77], v[178:181], v[206:209], v[74:77]
	v_mfma_i32_16x16x64_i8 v[70:73], v[170:173], v[214:217], v[70:73]
	v_mfma_i32_16x16x64_i8 v[66:69], v[178:181], v[214:217], v[66:69]
	s_setprio 0
	s_barrier
	s_add_i32 s47, s77, s69
	v_lshl_add_u64 v[198:199], s[50:51], 0, v[132:133]
	s_mov_b32 m0, s47
	ds_read_b128 v[182:185], v169 offset:16384
	ds_read_b128 v[186:189], v169 offset:17408
	ds_read_b128 v[190:193], v169 offset:18432
	ds_read_b128 v[194:197], v169 offset:19456
	ds_read_b128 v[202:205], v169 offset:20480
	ds_read_b128 v[206:209], v169 offset:21504
	ds_read_b128 v[210:213], v169 offset:22528
	ds_read_b128 v[214:217], v169 offset:23552
	global_load_lds_dwordx4 v[198:199], off
	s_add_i32 m0, s47, 0x2000
	v_lshl_add_u64 v[218:219], s[50:51], 0, v[136:137]
	s_add_u32 s50, s50, s22
	s_addc_u32 s51, s51, s23
	s_add_i32 s47, s78, s69
	global_load_lds_dwordx4 v[218:219], off
	v_lshl_add_u64 v[220:221], s[50:51], 0, v[132:133]
	s_mov_b32 m0, s47
	v_lshl_add_u64 v[222:223], s[50:51], 0, v[136:137]
	global_load_lds_dwordx4 v[220:221], off
	s_add_i32 m0, s47, 0x2000
	v_lshl_add_u64 v[224:225], s[6:7], 0, v[130:131]
	global_load_lds_dwordx4 v[222:223], off
	s_mov_b32 m0, s70
	v_lshl_add_u64 v[226:227], s[6:7], 0, v[134:135]
	global_load_lds_dwordx4 v[224:225], off
	s_mov_b32 m0, s71
	s_nop 0
	global_load_lds_dwordx4 v[226:227], off
	s_waitcnt vmcnt(8)
	s_waitcnt lgkmcnt(0)
	s_barrier
	s_setprio 1
	v_mfma_i32_16x16x64_i8 v[62:65], v[148:151], v[182:185], v[62:65]
	v_mfma_i32_16x16x64_i8 v[58:61], v[156:159], v[182:185], v[58:61]
	v_mfma_i32_16x16x64_i8 v[54:57], v[148:151], v[190:193], v[54:57]
	v_mfma_i32_16x16x64_i8 v[50:53], v[156:159], v[190:193], v[50:53]
	v_mfma_i32_16x16x64_i8 v[42:45], v[148:151], v[202:205], v[42:45]
	v_mfma_i32_16x16x64_i8 v[34:37], v[156:159], v[202:205], v[34:37]
	v_mfma_i32_16x16x64_i8 v[26:29], v[148:151], v[210:213], v[26:29]
	v_mfma_i32_16x16x64_i8 v[18:21], v[156:159], v[210:213], v[18:21]
	v_mfma_i32_16x16x64_i8 v[62:65], v[152:155], v[186:189], v[62:65]
	v_mfma_i32_16x16x64_i8 v[58:61], v[160:163], v[186:189], v[58:61]
	v_mfma_i32_16x16x64_i8 v[54:57], v[152:155], v[194:197], v[54:57]
	v_mfma_i32_16x16x64_i8 v[50:53], v[160:163], v[194:197], v[50:53]
	v_mfma_i32_16x16x64_i8 v[42:45], v[152:155], v[206:209], v[42:45]
	v_mfma_i32_16x16x64_i8 v[34:37], v[160:163], v[206:209], v[34:37]
	v_mfma_i32_16x16x64_i8 v[26:29], v[152:155], v[214:217], v[26:29]
	v_mfma_i32_16x16x64_i8 v[18:21], v[160:163], v[214:217], v[18:21]
	v_mfma_i32_16x16x64_i8 v[46:49], v[164:167], v[182:185], v[46:49]
	v_mfma_i32_16x16x64_i8 v[38:41], v[174:177], v[182:185], v[38:41]
	v_mfma_i32_16x16x64_i8 v[30:33], v[164:167], v[190:193], v[30:33]
	v_mfma_i32_16x16x64_i8 v[22:25], v[174:177], v[190:193], v[22:25]
	v_mfma_i32_16x16x64_i8 v[14:17], v[164:167], v[202:205], v[14:17]
	v_mfma_i32_16x16x64_i8 v[10:13], v[174:177], v[202:205], v[10:13]
	v_mfma_i32_16x16x64_i8 v[6:9], v[164:167], v[210:213], v[6:9]
	v_mfma_i32_16x16x64_i8 v[2:5], v[174:177], v[210:213], v[2:5]
	v_mfma_i32_16x16x64_i8 v[46:49], v[170:173], v[186:189], v[46:49]
	v_mfma_i32_16x16x64_i8 v[38:41], v[178:181], v[186:189], v[38:41]
	v_mfma_i32_16x16x64_i8 v[30:33], v[170:173], v[194:197], v[30:33]
	v_mfma_i32_16x16x64_i8 v[22:25], v[178:181], v[194:197], v[22:25]
	v_mfma_i32_16x16x64_i8 v[14:17], v[170:173], v[206:209], v[14:17]
	v_mfma_i32_16x16x64_i8 v[10:13], v[178:181], v[206:209], v[10:13]
	v_mfma_i32_16x16x64_i8 v[6:9], v[170:173], v[214:217], v[6:9]
	v_mfma_i32_16x16x64_i8 v[2:5], v[178:181], v[214:217], v[2:5]
	s_setprio 0
	s_barrier
	s_add_i32 s47, 0, 0x18000
	v_add_u32_e32 v138, s47, v1
	s_add_i32 s49, 0, 0x1c000
	ds_read_b128 v[148:151], v138
	ds_read_b128 v[152:155], v138 offset:1024
	ds_read_b128 v[156:159], v138 offset:2048
	ds_read_b128 v[160:163], v138 offset:3072
	v_add_u32_e32 v138, s49, v1
	ds_read_b128 v[164:167], v138
	ds_read_b128 v[170:173], v138 offset:1024
	ds_read_b128 v[174:177], v138 offset:2048
	ds_read_b128 v[178:181], v138 offset:3072
	s_add_u32 s6, s6, s22
	s_addc_u32 s7, s7, s23
	s_mov_b32 m0, s72
	v_lshl_add_u64 v[228:229], s[6:7], 0, v[130:131]
	ds_read_b128 v[182:185], v169 offset:32768
	ds_read_b128 v[186:189], v169 offset:33792
	ds_read_b128 v[190:193], v169 offset:34816
	ds_read_b128 v[194:197], v169 offset:35840
	ds_read_b128 v[202:205], v169 offset:36864
	ds_read_b128 v[206:209], v169 offset:37888
	ds_read_b128 v[210:213], v169 offset:38912
	ds_read_b128 v[214:217], v169 offset:39936
	global_load_lds_dwordx4 v[228:229], off
	v_lshl_add_u64 v[228:229], s[6:7], 0, v[134:135]
	s_mov_b32 m0, s73
	s_nop 0
	global_load_lds_dwordx4 v[228:229], off
	s_waitcnt vmcnt(8)
	s_waitcnt lgkmcnt(0)
	s_barrier
	s_setprio 1
	v_mfma_i32_16x16x64_i8 v[126:129], v[148:151], v[182:185], v[126:129]
	v_mfma_i32_16x16x64_i8 v[122:125], v[156:159], v[182:185], v[122:125]
	v_mfma_i32_16x16x64_i8 v[118:121], v[148:151], v[190:193], v[118:121]
	v_mfma_i32_16x16x64_i8 v[114:117], v[156:159], v[190:193], v[114:117]
	v_mfma_i32_16x16x64_i8 v[106:109], v[148:151], v[202:205], v[106:109]
	v_mfma_i32_16x16x64_i8 v[98:101], v[156:159], v[202:205], v[98:101]
	v_mfma_i32_16x16x64_i8 v[90:93], v[148:151], v[210:213], v[90:93]
	v_mfma_i32_16x16x64_i8 v[82:85], v[156:159], v[210:213], v[82:85]
	v_mfma_i32_16x16x64_i8 v[126:129], v[152:155], v[186:189], v[126:129]
	v_mfma_i32_16x16x64_i8 v[122:125], v[160:163], v[186:189], v[122:125]
	v_mfma_i32_16x16x64_i8 v[118:121], v[152:155], v[194:197], v[118:121]
	v_mfma_i32_16x16x64_i8 v[114:117], v[160:163], v[194:197], v[114:117]
	v_mfma_i32_16x16x64_i8 v[106:109], v[152:155], v[206:209], v[106:109]
	v_mfma_i32_16x16x64_i8 v[98:101], v[160:163], v[206:209], v[98:101]
	v_mfma_i32_16x16x64_i8 v[90:93], v[152:155], v[214:217], v[90:93]
	v_mfma_i32_16x16x64_i8 v[82:85], v[160:163], v[214:217], v[82:85]
	v_mfma_i32_16x16x64_i8 v[110:113], v[164:167], v[182:185], v[110:113]
	v_mfma_i32_16x16x64_i8 v[102:105], v[174:177], v[182:185], v[102:105]
	v_mfma_i32_16x16x64_i8 v[94:97], v[164:167], v[190:193], v[94:97]
	v_mfma_i32_16x16x64_i8 v[86:89], v[174:177], v[190:193], v[86:89]
	v_mfma_i32_16x16x64_i8 v[78:81], v[164:167], v[202:205], v[78:81]
	v_mfma_i32_16x16x64_i8 v[74:77], v[174:177], v[202:205], v[74:77]
	v_mfma_i32_16x16x64_i8 v[70:73], v[164:167], v[210:213], v[70:73]
	v_mfma_i32_16x16x64_i8 v[66:69], v[174:177], v[210:213], v[66:69]
	v_mfma_i32_16x16x64_i8 v[110:113], v[170:173], v[186:189], v[110:113]
	v_mfma_i32_16x16x64_i8 v[102:105], v[178:181], v[186:189], v[102:105]
	v_mfma_i32_16x16x64_i8 v[94:97], v[170:173], v[194:197], v[94:97]
	v_mfma_i32_16x16x64_i8 v[86:89], v[178:181], v[194:197], v[86:89]
	v_mfma_i32_16x16x64_i8 v[78:81], v[170:173], v[206:209], v[78:81]
	v_mfma_i32_16x16x64_i8 v[74:77], v[178:181], v[206:209], v[74:77]
	v_mfma_i32_16x16x64_i8 v[70:73], v[170:173], v[214:217], v[70:73]
	v_mfma_i32_16x16x64_i8 v[66:69], v[178:181], v[214:217], v[66:69]
	s_setprio 0
	s_barrier
	s_add_i32 s6, s47, s69
	v_lshl_add_u64 v[198:199], v[198:199], 0, s[34:35]
	s_mov_b32 m0, s6
	ds_read_b128 v[182:185], v169 offset:49152
	ds_read_b128 v[186:189], v169 offset:50176
	ds_read_b128 v[190:193], v169 offset:51200
	ds_read_b128 v[194:197], v169 offset:52224
	ds_read_b128 v[202:205], v169 offset:53248
	ds_read_b128 v[206:209], v169 offset:54272
	ds_read_b128 v[210:213], v169 offset:55296
	ds_read_b128 v[214:217], v169 offset:56320
	global_load_lds_dwordx4 v[198:199], off
	v_lshl_add_u64 v[198:199], v[218:219], 0, s[34:35]
	s_add_i32 m0, s6, 0x2000
	s_add_i32 s6, s49, s69
	global_load_lds_dwordx4 v[198:199], off
	v_lshl_add_u64 v[198:199], v[220:221], 0, s[34:35]
	s_mov_b32 m0, s6
	s_nop 0
	global_load_lds_dwordx4 v[198:199], off
	v_lshl_add_u64 v[198:199], v[222:223], 0, s[34:35]
	s_add_i32 m0, s6, 0x2000
	s_nop 0
	global_load_lds_dwordx4 v[198:199], off
	v_lshl_add_u64 v[198:199], v[224:225], 0, s[34:35]
	s_mov_b32 m0, s74
	s_nop 0
	global_load_lds_dwordx4 v[198:199], off
	v_lshl_add_u64 v[198:199], v[226:227], 0, s[34:35]
	s_mov_b32 m0, s75
	s_nop 0
	global_load_lds_dwordx4 v[198:199], off
	s_waitcnt vmcnt(8)
	s_waitcnt lgkmcnt(0)
	s_barrier
	s_setprio 1
	v_mfma_i32_16x16x64_i8 v[62:65], v[148:151], v[182:185], v[62:65]
	v_mfma_i32_16x16x64_i8 v[58:61], v[156:159], v[182:185], v[58:61]
	v_mfma_i32_16x16x64_i8 v[54:57], v[148:151], v[190:193], v[54:57]
	v_mfma_i32_16x16x64_i8 v[50:53], v[156:159], v[190:193], v[50:53]
	v_mfma_i32_16x16x64_i8 v[42:45], v[148:151], v[202:205], v[42:45]
	v_mfma_i32_16x16x64_i8 v[34:37], v[156:159], v[202:205], v[34:37]
	v_mfma_i32_16x16x64_i8 v[26:29], v[148:151], v[210:213], v[26:29]
	v_mfma_i32_16x16x64_i8 v[18:21], v[156:159], v[210:213], v[18:21]
	v_mfma_i32_16x16x64_i8 v[62:65], v[152:155], v[186:189], v[62:65]
	v_mfma_i32_16x16x64_i8 v[58:61], v[160:163], v[186:189], v[58:61]
	v_mfma_i32_16x16x64_i8 v[54:57], v[152:155], v[194:197], v[54:57]
	v_mfma_i32_16x16x64_i8 v[50:53], v[160:163], v[194:197], v[50:53]
	v_mfma_i32_16x16x64_i8 v[42:45], v[152:155], v[206:209], v[42:45]
	v_mfma_i32_16x16x64_i8 v[34:37], v[160:163], v[206:209], v[34:37]
	v_mfma_i32_16x16x64_i8 v[26:29], v[152:155], v[214:217], v[26:29]
	v_mfma_i32_16x16x64_i8 v[18:21], v[160:163], v[214:217], v[18:21]
	v_mfma_i32_16x16x64_i8 v[46:49], v[164:167], v[182:185], v[46:49]
	v_mfma_i32_16x16x64_i8 v[38:41], v[174:177], v[182:185], v[38:41]
	v_mfma_i32_16x16x64_i8 v[30:33], v[164:167], v[190:193], v[30:33]
	v_mfma_i32_16x16x64_i8 v[22:25], v[174:177], v[190:193], v[22:25]
	v_mfma_i32_16x16x64_i8 v[14:17], v[164:167], v[202:205], v[14:17]
	v_mfma_i32_16x16x64_i8 v[10:13], v[174:177], v[202:205], v[10:13]
	v_mfma_i32_16x16x64_i8 v[6:9], v[164:167], v[210:213], v[6:9]
	v_mfma_i32_16x16x64_i8 v[2:5], v[174:177], v[210:213], v[2:5]
	v_mfma_i32_16x16x64_i8 v[46:49], v[170:173], v[186:189], v[46:49]
	v_mfma_i32_16x16x64_i8 v[38:41], v[178:181], v[186:189], v[38:41]
	v_mfma_i32_16x16x64_i8 v[30:33], v[170:173], v[194:197], v[30:33]
	v_mfma_i32_16x16x64_i8 v[22:25], v[178:181], v[194:197], v[22:25]
	v_mfma_i32_16x16x64_i8 v[14:17], v[170:173], v[206:209], v[14:17]
	v_mfma_i32_16x16x64_i8 v[10:13], v[178:181], v[206:209], v[10:13]
	v_mfma_i32_16x16x64_i8 v[6:9], v[170:173], v[214:217], v[6:9]
	v_mfma_i32_16x16x64_i8 v[2:5], v[178:181], v[214:217], v[2:5]
	s_setprio 0
	s_barrier
	s_add_u32 s4, s4, 0x100
	s_addc_u32 s5, s5, 0
	s_add_u32 s44, s44, 0x100
	s_addc_u32 s45, s45, 0
	s_cmp_ge_i32 s46, s52
	s_mov_b32 s6, s46
	s_cbranch_scc0 .LBB0_1297
	v_cvt_f32_i32_e32 v182, v126
	v_cvt_f32_i32_e32 v183, v127
	v_cvt_f32_i32_e32 v180, v128
	v_cvt_f32_i32_e32 v181, v129
	v_cvt_f32_i32_e32 v184, v122
	v_cvt_f32_i32_e32 v185, v123
	v_cvt_f32_i32_e32 v186, v124
	v_cvt_f32_i32_e32 v187, v125
	v_cvt_f32_i32_e32 v170, v110
	v_cvt_f32_i32_e32 v171, v111
	v_cvt_f32_i32_e32 v174, v112
	v_cvt_f32_i32_e32 v175, v113
	v_cvt_f32_i32_e32 v172, v102
	v_cvt_f32_i32_e32 v173, v103
	v_cvt_f32_i32_e32 v166, v104
	v_cvt_f32_i32_e32 v167, v105
	v_cvt_f32_i32_e32 v162, v118
	v_cvt_f32_i32_e32 v163, v119
	v_cvt_f32_i32_e32 v164, v120
	v_cvt_f32_i32_e32 v165, v121
	v_cvt_f32_i32_e32 v158, v114
	v_cvt_f32_i32_e32 v159, v115
	v_cvt_f32_i32_e32 v160, v116
	v_cvt_f32_i32_e32 v161, v117
	v_cvt_f32_i32_e32 v152, v94
	v_cvt_f32_i32_e32 v153, v95
	v_cvt_f32_i32_e32 v154, v96
	v_cvt_f32_i32_e32 v155, v97
	v_cvt_f32_i32_e32 v128, v86
	v_cvt_f32_i32_e32 v129, v87
	v_cvt_f32_i32_e32 v148, v88
	v_cvt_f32_i32_e32 v149, v89
	v_cvt_f32_i32_e32 v124, v106
	v_cvt_f32_i32_e32 v125, v107
	v_cvt_f32_i32_e32 v126, v108
	v_cvt_f32_i32_e32 v127, v109
	v_cvt_f32_i32_e32 v120, v98
	v_cvt_f32_i32_e32 v121, v99
	v_cvt_f32_i32_e32 v122, v100
	v_cvt_f32_i32_e32 v123, v101
	v_cvt_f32_i32_e32 v114, v78
	v_cvt_f32_i32_e32 v115, v79
	v_cvt_f32_i32_e32 v116, v80
	v_cvt_f32_i32_e32 v117, v81
	v_cvt_f32_i32_e32 v110, v74
	v_cvt_f32_i32_e32 v111, v75
	v_cvt_f32_i32_e32 v112, v76
	v_cvt_f32_i32_e32 v113, v77
	v_cvt_f32_i32_e32 v104, v90
	v_cvt_f32_i32_e32 v105, v91
	v_cvt_f32_i32_e32 v106, v92
	v_cvt_f32_i32_e32 v107, v93
	v_cvt_f32_i32_e32 v100, v82
	v_cvt_f32_i32_e32 v101, v83
	v_cvt_f32_i32_e32 v102, v84
	v_cvt_f32_i32_e32 v103, v85
	v_cvt_f32_i32_e32 v96, v70
	v_cvt_f32_i32_e32 v97, v71
	v_cvt_f32_i32_e32 v98, v72
	v_cvt_f32_i32_e32 v99, v73
	v_cvt_f32_i32_e32 v92, v66
	v_cvt_f32_i32_e32 v93, v67
	v_cvt_f32_i32_e32 v94, v68
	v_cvt_f32_i32_e32 v95, v69
	v_cvt_f32_i32_e32 v86, v62
	v_cvt_f32_i32_e32 v87, v63
	v_cvt_f32_i32_e32 v88, v64
	v_cvt_f32_i32_e32 v89, v65
	v_cvt_f32_i32_e32 v82, v58
	v_cvt_f32_i32_e32 v83, v59
	v_cvt_f32_i32_e32 v84, v60
	v_cvt_f32_i32_e32 v85, v61
	v_cvt_f32_i32_e32 v78, v46
	v_cvt_f32_i32_e32 v79, v47
	v_cvt_f32_i32_e32 v80, v48
	v_cvt_f32_i32_e32 v81, v49
	v_cvt_f32_i32_e32 v74, v38
	v_cvt_f32_i32_e32 v75, v39
	v_cvt_f32_i32_e32 v76, v40
	v_cvt_f32_i32_e32 v77, v41
	v_cvt_f32_i32_e32 v68, v54
	v_cvt_f32_i32_e32 v69, v55
	v_cvt_f32_i32_e32 v70, v56
	v_cvt_f32_i32_e32 v71, v57
	v_cvt_f32_i32_e32 v64, v50
	v_cvt_f32_i32_e32 v65, v51
	v_cvt_f32_i32_e32 v66, v52
	v_cvt_f32_i32_e32 v67, v53
	v_cvt_f32_i32_e32 v60, v30
	v_cvt_f32_i32_e32 v61, v31
	v_cvt_f32_i32_e32 v62, v32
	v_cvt_f32_i32_e32 v63, v33
	v_cvt_f32_i32_e32 v56, v22
	v_cvt_f32_i32_e32 v57, v23
	v_cvt_f32_i32_e32 v58, v24
	v_cvt_f32_i32_e32 v59, v25
	v_cvt_f32_i32_e32 v50, v42
	v_cvt_f32_i32_e32 v51, v43
	v_cvt_f32_i32_e32 v52, v44
	v_cvt_f32_i32_e32 v53, v45
	v_cvt_f32_i32_e32 v46, v34
	v_cvt_f32_i32_e32 v47, v35
	v_cvt_f32_i32_e32 v48, v36
	v_cvt_f32_i32_e32 v49, v37
	v_cvt_f32_i32_e32 v34, v14
	v_cvt_f32_i32_e32 v35, v15
	v_cvt_f32_i32_e32 v36, v16
	v_cvt_f32_i32_e32 v37, v17
	v_cvt_f32_i32_e32 v30, v10
	v_cvt_f32_i32_e32 v31, v11
	v_cvt_f32_i32_e32 v32, v12
	v_cvt_f32_i32_e32 v33, v13
	v_cvt_f32_i32_e32 v22, v26
	v_cvt_f32_i32_e32 v23, v27
	v_cvt_f32_i32_e32 v24, v28
	v_cvt_f32_i32_e32 v25, v29
	v_cvt_f32_i32_e32 v18, v18
	v_cvt_f32_i32_e32 v19, v19
	v_cvt_f32_i32_e32 v20, v20
	v_cvt_f32_i32_e32 v21, v21
	v_cvt_f32_i32_e32 v14, v6
	v_cvt_f32_i32_e32 v15, v7
	v_cvt_f32_i32_e32 v16, v8
	v_cvt_f32_i32_e32 v17, v9
	v_cvt_f32_i32_e32 v10, v2
	v_cvt_f32_i32_e32 v11, v3
	v_cvt_f32_i32_e32 v12, v4
	v_cvt_f32_i32_e32 v13, v5

.LBB0_1513:
	v_add_u32_e32 v138, s55, v1
	ds_read_b128 v[148:151], v138
	ds_read_b128 v[152:155], v138 offset:1024
	ds_read_b128 v[156:159], v138 offset:2048
	ds_read_b128 v[160:163], v138 offset:3072
	v_add_u32_e32 v138, s76, v1
	ds_read_b128 v[164:167], v138
	ds_read_b128 v[170:173], v138 offset:1024
	ds_read_b128 v[174:177], v138 offset:2048
	ds_read_b128 v[178:181], v138 offset:3072
	s_add_i32 s46, s6, 2
	s_add_u32 s47, s4, 0x80
	s_addc_u32 s7, s5, 0
	s_cmp_eq_u32 s53, s6
	s_cselect_b32 s6, s40, s47
	s_cselect_b32 s7, s41, s7
	s_cselect_b32 s51, s43, s45
	s_cselect_b32 s50, s42, s44
	v_lshl_add_u64 v[198:199], s[4:5], 0, v[140:141]
	s_add_i32 m0, s68, 0xc000
	ds_read_b128 v[182:185], v169
	ds_read_b128 v[186:189], v169 offset:1024
	ds_read_b128 v[190:193], v169 offset:2048
	ds_read_b128 v[194:197], v169 offset:3072
	ds_read_b128 v[202:205], v169 offset:4096
	ds_read_b128 v[206:209], v169 offset:5120
	ds_read_b128 v[210:213], v169 offset:6144
	ds_read_b128 v[214:217], v169 offset:7168
	global_load_lds_dwordx4 v[198:199], off
	v_lshl_add_u64 v[198:199], s[4:5], 0, v[142:143]
	s_add_i32 m0, s68, 0xe000
	s_nop 0
	global_load_lds_dwordx4 v[198:199], off
	s_waitcnt vmcnt(8)
	s_waitcnt lgkmcnt(0)
	s_barrier
	s_setprio 1
	v_mfma_i32_16x16x64_i8 v[126:129], v[148:151], v[182:185], v[126:129]
	v_mfma_i32_16x16x64_i8 v[122:125], v[156:159], v[182:185], v[122:125]
	v_mfma_i32_16x16x64_i8 v[118:121], v[148:151], v[190:193], v[118:121]
	v_mfma_i32_16x16x64_i8 v[114:117], v[156:159], v[190:193], v[114:117]
	v_mfma_i32_16x16x64_i8 v[106:109], v[148:151], v[202:205], v[106:109]
	v_mfma_i32_16x16x64_i8 v[98:101], v[156:159], v[202:205], v[98:101]
	v_mfma_i32_16x16x64_i8 v[90:93], v[148:151], v[210:213], v[90:93]
	v_mfma_i32_16x16x64_i8 v[82:85], v[156:159], v[210:213], v[82:85]
	v_mfma_i32_16x16x64_i8 v[126:129], v[152:155], v[186:189], v[126:129]
	v_mfma_i32_16x16x64_i8 v[122:125], v[160:163], v[186:189], v[122:125]
	v_mfma_i32_16x16x64_i8 v[118:121], v[152:155], v[194:197], v[118:121]
	v_mfma_i32_16x16x64_i8 v[114:117], v[160:163], v[194:197], v[114:117]
	v_mfma_i32_16x16x64_i8 v[106:109], v[152:155], v[206:209], v[106:109]
	v_mfma_i32_16x16x64_i8 v[98:101], v[160:163], v[206:209], v[98:101]
	v_mfma_i32_16x16x64_i8 v[90:93], v[152:155], v[214:217], v[90:93]
	v_mfma_i32_16x16x64_i8 v[82:85], v[160:163], v[214:217], v[82:85]
	v_mfma_i32_16x16x64_i8 v[110:113], v[164:167], v[182:185], v[110:113]
	v_mfma_i32_16x16x64_i8 v[102:105], v[174:177], v[182:185], v[102:105]
	v_mfma_i32_16x16x64_i8 v[94:97], v[164:167], v[190:193], v[94:97]
	v_mfma_i32_16x16x64_i8 v[86:89], v[174:177], v[190:193], v[86:89]
	v_mfma_i32_16x16x64_i8 v[78:81], v[164:167], v[202:205], v[78:81]
	v_mfma_i32_16x16x64_i8 v[74:77], v[174:177], v[202:205], v[74:77]
	v_mfma_i32_16x16x64_i8 v[70:73], v[164:167], v[210:213], v[70:73]
	v_mfma_i32_16x16x64_i8 v[66:69], v[174:177], v[210:213], v[66:69]
	v_mfma_i32_16x16x64_i8 v[110:113], v[170:173], v[186:189], v[110:113]
	v_mfma_i32_16x16x64_i8 v[102:105], v[178:181], v[186:189], v[102:105]
	v_mfma_i32_16x16x64_i8 v[94:97], v[170:173], v[194:197], v[94:97]
	v_mfma_i32_16x16x64_i8 v[86:89], v[178:181], v[194:197], v[86:89]
	v_mfma_i32_16x16x64_i8 v[78:81], v[170:173], v[206:209], v[78:81]
	v_mfma_i32_16x16x64_i8 v[74:77], v[178:181], v[206:209], v[74:77]
	v_mfma_i32_16x16x64_i8 v[70:73], v[170:173], v[214:217], v[70:73]
	v_mfma_i32_16x16x64_i8 v[66:69], v[178:181], v[214:217], v[66:69]
	s_setprio 0
	s_barrier
	s_add_i32 s47, s55, s67
	v_lshl_add_u64 v[198:199], s[50:51], 0, v[132:133]
	s_mov_b32 m0, s47
	ds_read_b128 v[182:185], v169 offset:16384
	ds_read_b128 v[186:189], v169 offset:17408
	ds_read_b128 v[190:193], v169 offset:18432
	ds_read_b128 v[194:197], v169 offset:19456
	ds_read_b128 v[202:205], v169 offset:20480
	ds_read_b128 v[206:209], v169 offset:21504
	ds_read_b128 v[210:213], v169 offset:22528
	ds_read_b128 v[214:217], v169 offset:23552
	global_load_lds_dwordx4 v[198:199], off
	s_add_i32 m0, s47, 0x2000
	v_lshl_add_u64 v[218:219], s[50:51], 0, v[136:137]
	s_add_u32 s50, s50, s22
	s_addc_u32 s51, s51, s23
	s_add_i32 s47, s76, s67
	global_load_lds_dwordx4 v[218:219], off
	v_lshl_add_u64 v[220:221], s[50:51], 0, v[132:133]
	s_mov_b32 m0, s47
	v_lshl_add_u64 v[222:223], s[50:51], 0, v[136:137]
	global_load_lds_dwordx4 v[220:221], off
	s_add_i32 m0, s47, 0x2000
	v_lshl_add_u64 v[224:225], s[6:7], 0, v[130:131]
	global_load_lds_dwordx4 v[222:223], off
	s_mov_b32 m0, s68
	v_lshl_add_u64 v[226:227], s[6:7], 0, v[134:135]
	global_load_lds_dwordx4 v[224:225], off
	s_mov_b32 m0, s69
	s_nop 0
	global_load_lds_dwordx4 v[226:227], off
	s_waitcnt vmcnt(8)
	s_waitcnt lgkmcnt(0)
	s_barrier
	s_setprio 1
	v_mfma_i32_16x16x64_i8 v[62:65], v[148:151], v[182:185], v[62:65]
	v_mfma_i32_16x16x64_i8 v[58:61], v[156:159], v[182:185], v[58:61]
	v_mfma_i32_16x16x64_i8 v[54:57], v[148:151], v[190:193], v[54:57]
	v_mfma_i32_16x16x64_i8 v[50:53], v[156:159], v[190:193], v[50:53]
	v_mfma_i32_16x16x64_i8 v[42:45], v[148:151], v[202:205], v[42:45]
	v_mfma_i32_16x16x64_i8 v[34:37], v[156:159], v[202:205], v[34:37]
	v_mfma_i32_16x16x64_i8 v[26:29], v[148:151], v[210:213], v[26:29]
	v_mfma_i32_16x16x64_i8 v[18:21], v[156:159], v[210:213], v[18:21]
	v_mfma_i32_16x16x64_i8 v[62:65], v[152:155], v[186:189], v[62:65]
	v_mfma_i32_16x16x64_i8 v[58:61], v[160:163], v[186:189], v[58:61]
	v_mfma_i32_16x16x64_i8 v[54:57], v[152:155], v[194:197], v[54:57]
	v_mfma_i32_16x16x64_i8 v[50:53], v[160:163], v[194:197], v[50:53]
	v_mfma_i32_16x16x64_i8 v[42:45], v[152:155], v[206:209], v[42:45]
	v_mfma_i32_16x16x64_i8 v[34:37], v[160:163], v[206:209], v[34:37]
	v_mfma_i32_16x16x64_i8 v[26:29], v[152:155], v[214:217], v[26:29]
	v_mfma_i32_16x16x64_i8 v[18:21], v[160:163], v[214:217], v[18:21]
	v_mfma_i32_16x16x64_i8 v[46:49], v[164:167], v[182:185], v[46:49]
	v_mfma_i32_16x16x64_i8 v[38:41], v[174:177], v[182:185], v[38:41]
	v_mfma_i32_16x16x64_i8 v[30:33], v[164:167], v[190:193], v[30:33]
	v_mfma_i32_16x16x64_i8 v[22:25], v[174:177], v[190:193], v[22:25]
	v_mfma_i32_16x16x64_i8 v[14:17], v[164:167], v[202:205], v[14:17]
	v_mfma_i32_16x16x64_i8 v[10:13], v[174:177], v[202:205], v[10:13]
	v_mfma_i32_16x16x64_i8 v[6:9], v[164:167], v[210:213], v[6:9]
	v_mfma_i32_16x16x64_i8 v[2:5], v[174:177], v[210:213], v[2:5]
	v_mfma_i32_16x16x64_i8 v[46:49], v[170:173], v[186:189], v[46:49]
	v_mfma_i32_16x16x64_i8 v[38:41], v[178:181], v[186:189], v[38:41]
	v_mfma_i32_16x16x64_i8 v[30:33], v[170:173], v[194:197], v[30:33]
	v_mfma_i32_16x16x64_i8 v[22:25], v[178:181], v[194:197], v[22:25]
	v_mfma_i32_16x16x64_i8 v[14:17], v[170:173], v[206:209], v[14:17]
	v_mfma_i32_16x16x64_i8 v[10:13], v[178:181], v[206:209], v[10:13]
	v_mfma_i32_16x16x64_i8 v[6:9], v[170:173], v[214:217], v[6:9]
	v_mfma_i32_16x16x64_i8 v[2:5], v[178:181], v[214:217], v[2:5]
	s_setprio 0
	s_barrier
	s_add_i32 s47, 0, 0x18000
	v_add_u32_e32 v138, s47, v1
	s_add_i32 s49, 0, 0x1c000
	ds_read_b128 v[148:151], v138
	ds_read_b128 v[152:155], v138 offset:1024
	ds_read_b128 v[156:159], v138 offset:2048
	ds_read_b128 v[160:163], v138 offset:3072
	v_add_u32_e32 v138, s49, v1
	ds_read_b128 v[164:167], v138
	ds_read_b128 v[170:173], v138 offset:1024
	ds_read_b128 v[174:177], v138 offset:2048
	ds_read_b128 v[178:181], v138 offset:3072
	s_add_u32 s6, s6, s22
	s_addc_u32 s7, s7, s23
	s_mov_b32 m0, s70
	v_lshl_add_u64 v[228:229], s[6:7], 0, v[130:131]
	ds_read_b128 v[182:185], v169 offset:32768
	ds_read_b128 v[186:189], v169 offset:33792
	ds_read_b128 v[190:193], v169 offset:34816
	ds_read_b128 v[194:197], v169 offset:35840
	ds_read_b128 v[202:205], v169 offset:36864
	ds_read_b128 v[206:209], v169 offset:37888
	ds_read_b128 v[210:213], v169 offset:38912
	ds_read_b128 v[214:217], v169 offset:39936
	global_load_lds_dwordx4 v[228:229], off
	v_lshl_add_u64 v[228:229], s[6:7], 0, v[134:135]
	s_mov_b32 m0, s71
	s_nop 0
	global_load_lds_dwordx4 v[228:229], off
	s_waitcnt vmcnt(8)
	s_waitcnt lgkmcnt(0)
	s_barrier
	s_setprio 1
	v_mfma_i32_16x16x64_i8 v[126:129], v[148:151], v[182:185], v[126:129]
	v_mfma_i32_16x16x64_i8 v[122:125], v[156:159], v[182:185], v[122:125]
	v_mfma_i32_16x16x64_i8 v[118:121], v[148:151], v[190:193], v[118:121]
	v_mfma_i32_16x16x64_i8 v[114:117], v[156:159], v[190:193], v[114:117]
	v_mfma_i32_16x16x64_i8 v[106:109], v[148:151], v[202:205], v[106:109]
	v_mfma_i32_16x16x64_i8 v[98:101], v[156:159], v[202:205], v[98:101]
	v_mfma_i32_16x16x64_i8 v[90:93], v[148:151], v[210:213], v[90:93]
	v_mfma_i32_16x16x64_i8 v[82:85], v[156:159], v[210:213], v[82:85]
	v_mfma_i32_16x16x64_i8 v[126:129], v[152:155], v[186:189], v[126:129]
	v_mfma_i32_16x16x64_i8 v[122:125], v[160:163], v[186:189], v[122:125]
	v_mfma_i32_16x16x64_i8 v[118:121], v[152:155], v[194:197], v[118:121]
	v_mfma_i32_16x16x64_i8 v[114:117], v[160:163], v[194:197], v[114:117]
	v_mfma_i32_16x16x64_i8 v[106:109], v[152:155], v[206:209], v[106:109]
	v_mfma_i32_16x16x64_i8 v[98:101], v[160:163], v[206:209], v[98:101]
	v_mfma_i32_16x16x64_i8 v[90:93], v[152:155], v[214:217], v[90:93]
	v_mfma_i32_16x16x64_i8 v[82:85], v[160:163], v[214:217], v[82:85]
	v_mfma_i32_16x16x64_i8 v[110:113], v[164:167], v[182:185], v[110:113]
	v_mfma_i32_16x16x64_i8 v[102:105], v[174:177], v[182:185], v[102:105]
	v_mfma_i32_16x16x64_i8 v[94:97], v[164:167], v[190:193], v[94:97]
	v_mfma_i32_16x16x64_i8 v[86:89], v[174:177], v[190:193], v[86:89]
	v_mfma_i32_16x16x64_i8 v[78:81], v[164:167], v[202:205], v[78:81]
	v_mfma_i32_16x16x64_i8 v[74:77], v[174:177], v[202:205], v[74:77]
	v_mfma_i32_16x16x64_i8 v[70:73], v[164:167], v[210:213], v[70:73]
	v_mfma_i32_16x16x64_i8 v[66:69], v[174:177], v[210:213], v[66:69]
	v_mfma_i32_16x16x64_i8 v[110:113], v[170:173], v[186:189], v[110:113]
	v_mfma_i32_16x16x64_i8 v[102:105], v[178:181], v[186:189], v[102:105]
	v_mfma_i32_16x16x64_i8 v[94:97], v[170:173], v[194:197], v[94:97]
	v_mfma_i32_16x16x64_i8 v[86:89], v[178:181], v[194:197], v[86:89]
	v_mfma_i32_16x16x64_i8 v[78:81], v[170:173], v[206:209], v[78:81]
	v_mfma_i32_16x16x64_i8 v[74:77], v[178:181], v[206:209], v[74:77]
	v_mfma_i32_16x16x64_i8 v[70:73], v[170:173], v[214:217], v[70:73]
	v_mfma_i32_16x16x64_i8 v[66:69], v[178:181], v[214:217], v[66:69]
	s_setprio 0
	s_barrier
	s_add_i32 s6, s47, s67
	v_lshl_add_u64 v[198:199], v[198:199], 0, s[34:35]
	s_mov_b32 m0, s6
	ds_read_b128 v[182:185], v169 offset:49152
	ds_read_b128 v[186:189], v169 offset:50176
	ds_read_b128 v[190:193], v169 offset:51200
	ds_read_b128 v[194:197], v169 offset:52224
	ds_read_b128 v[202:205], v169 offset:53248
	ds_read_b128 v[206:209], v169 offset:54272
	ds_read_b128 v[210:213], v169 offset:55296
	ds_read_b128 v[214:217], v169 offset:56320
	global_load_lds_dwordx4 v[198:199], off
	v_lshl_add_u64 v[198:199], v[218:219], 0, s[34:35]
	s_add_i32 m0, s6, 0x2000
	s_add_i32 s6, s49, s67
	global_load_lds_dwordx4 v[198:199], off
	v_lshl_add_u64 v[198:199], v[220:221], 0, s[34:35]
	s_mov_b32 m0, s6
	s_nop 0
	global_load_lds_dwordx4 v[198:199], off
	v_lshl_add_u64 v[198:199], v[222:223], 0, s[34:35]
	s_add_i32 m0, s6, 0x2000
	s_nop 0
	global_load_lds_dwordx4 v[198:199], off
	v_lshl_add_u64 v[198:199], v[224:225], 0, s[34:35]
	s_mov_b32 m0, s72
	s_nop 0
	global_load_lds_dwordx4 v[198:199], off
	v_lshl_add_u64 v[198:199], v[226:227], 0, s[34:35]
	s_mov_b32 m0, s73
	s_nop 0
	global_load_lds_dwordx4 v[198:199], off
	s_waitcnt vmcnt(8)
	s_waitcnt lgkmcnt(0)
	s_barrier
	s_setprio 1
	v_mfma_i32_16x16x64_i8 v[62:65], v[148:151], v[182:185], v[62:65]
	v_mfma_i32_16x16x64_i8 v[58:61], v[156:159], v[182:185], v[58:61]
	v_mfma_i32_16x16x64_i8 v[54:57], v[148:151], v[190:193], v[54:57]
	v_mfma_i32_16x16x64_i8 v[50:53], v[156:159], v[190:193], v[50:53]
	v_mfma_i32_16x16x64_i8 v[42:45], v[148:151], v[202:205], v[42:45]
	v_mfma_i32_16x16x64_i8 v[34:37], v[156:159], v[202:205], v[34:37]
	v_mfma_i32_16x16x64_i8 v[26:29], v[148:151], v[210:213], v[26:29]
	v_mfma_i32_16x16x64_i8 v[18:21], v[156:159], v[210:213], v[18:21]
	v_mfma_i32_16x16x64_i8 v[62:65], v[152:155], v[186:189], v[62:65]
	v_mfma_i32_16x16x64_i8 v[58:61], v[160:163], v[186:189], v[58:61]
	v_mfma_i32_16x16x64_i8 v[54:57], v[152:155], v[194:197], v[54:57]
	v_mfma_i32_16x16x64_i8 v[50:53], v[160:163], v[194:197], v[50:53]
	v_mfma_i32_16x16x64_i8 v[42:45], v[152:155], v[206:209], v[42:45]
	v_mfma_i32_16x16x64_i8 v[34:37], v[160:163], v[206:209], v[34:37]
	v_mfma_i32_16x16x64_i8 v[26:29], v[152:155], v[214:217], v[26:29]
	v_mfma_i32_16x16x64_i8 v[18:21], v[160:163], v[214:217], v[18:21]
	v_mfma_i32_16x16x64_i8 v[46:49], v[164:167], v[182:185], v[46:49]
	v_mfma_i32_16x16x64_i8 v[38:41], v[174:177], v[182:185], v[38:41]
	v_mfma_i32_16x16x64_i8 v[30:33], v[164:167], v[190:193], v[30:33]
	v_mfma_i32_16x16x64_i8 v[22:25], v[174:177], v[190:193], v[22:25]
	v_mfma_i32_16x16x64_i8 v[14:17], v[164:167], v[202:205], v[14:17]
	v_mfma_i32_16x16x64_i8 v[10:13], v[174:177], v[202:205], v[10:13]
	v_mfma_i32_16x16x64_i8 v[6:9], v[164:167], v[210:213], v[6:9]
	v_mfma_i32_16x16x64_i8 v[2:5], v[174:177], v[210:213], v[2:5]
	v_mfma_i32_16x16x64_i8 v[46:49], v[170:173], v[186:189], v[46:49]
	v_mfma_i32_16x16x64_i8 v[38:41], v[178:181], v[186:189], v[38:41]
	v_mfma_i32_16x16x64_i8 v[30:33], v[170:173], v[194:197], v[30:33]
	v_mfma_i32_16x16x64_i8 v[22:25], v[178:181], v[194:197], v[22:25]
	v_mfma_i32_16x16x64_i8 v[14:17], v[170:173], v[206:209], v[14:17]
	v_mfma_i32_16x16x64_i8 v[10:13], v[178:181], v[206:209], v[10:13]
	v_mfma_i32_16x16x64_i8 v[6:9], v[170:173], v[214:217], v[6:9]
	v_mfma_i32_16x16x64_i8 v[2:5], v[178:181], v[214:217], v[2:5]
	s_setprio 0
	s_barrier
	s_add_u32 s4, s4, 0x100
	s_addc_u32 s5, s5, 0
	s_add_u32 s44, s44, 0x100
	s_addc_u32 s45, s45, 0
	s_cmp_lt_i32 s46, s74
	s_mov_b32 s6, s46
	s_cbranch_scc1 .LBB0_1513
	v_cvt_f32_i32_e32 v182, v126
	v_cvt_f32_i32_e32 v183, v127
	v_cvt_f32_i32_e32 v180, v128
	v_cvt_f32_i32_e32 v181, v129
	v_cvt_f32_i32_e32 v184, v122
	v_cvt_f32_i32_e32 v185, v123
	v_cvt_f32_i32_e32 v186, v124
	v_cvt_f32_i32_e32 v187, v125
	v_cvt_f32_i32_e32 v170, v110
	v_cvt_f32_i32_e32 v171, v111
	v_cvt_f32_i32_e32 v174, v112
	v_cvt_f32_i32_e32 v175, v113
	v_cvt_f32_i32_e32 v172, v102
	v_cvt_f32_i32_e32 v173, v103
	v_cvt_f32_i32_e32 v166, v104
	v_cvt_f32_i32_e32 v167, v105
	v_cvt_f32_i32_e32 v162, v118
	v_cvt_f32_i32_e32 v163, v119
	v_cvt_f32_i32_e32 v164, v120
	v_cvt_f32_i32_e32 v165, v121
	v_cvt_f32_i32_e32 v158, v114
	v_cvt_f32_i32_e32 v159, v115
	v_cvt_f32_i32_e32 v160, v116
	v_cvt_f32_i32_e32 v161, v117
	v_cvt_f32_i32_e32 v150, v94
	v_cvt_f32_i32_e32 v151, v95
	v_cvt_f32_i32_e32 v154, v96
	v_cvt_f32_i32_e32 v155, v97
	v_cvt_f32_i32_e32 v128, v86
	v_cvt_f32_i32_e32 v129, v87
	v_cvt_f32_i32_e32 v148, v88
	v_cvt_f32_i32_e32 v149, v89
	v_cvt_f32_i32_e32 v124, v106
	v_cvt_f32_i32_e32 v125, v107
	v_cvt_f32_i32_e32 v126, v108
	v_cvt_f32_i32_e32 v127, v109
	v_cvt_f32_i32_e32 v120, v98
	v_cvt_f32_i32_e32 v121, v99
	v_cvt_f32_i32_e32 v122, v100
	v_cvt_f32_i32_e32 v123, v101
	v_cvt_f32_i32_e32 v114, v78
	v_cvt_f32_i32_e32 v115, v79
	v_cvt_f32_i32_e32 v116, v80
	v_cvt_f32_i32_e32 v117, v81
	v_cvt_f32_i32_e32 v110, v74
	v_cvt_f32_i32_e32 v111, v75
	v_cvt_f32_i32_e32 v112, v76
	v_cvt_f32_i32_e32 v113, v77
	v_cvt_f32_i32_e32 v104, v90
	v_cvt_f32_i32_e32 v105, v91
	v_cvt_f32_i32_e32 v106, v92
	v_cvt_f32_i32_e32 v107, v93
	v_cvt_f32_i32_e32 v100, v82
	v_cvt_f32_i32_e32 v101, v83
	v_cvt_f32_i32_e32 v102, v84
	v_cvt_f32_i32_e32 v103, v85
	v_cvt_f32_i32_e32 v96, v70
	v_cvt_f32_i32_e32 v97, v71
	v_cvt_f32_i32_e32 v98, v72
	v_cvt_f32_i32_e32 v99, v73
	v_cvt_f32_i32_e32 v92, v66
	v_cvt_f32_i32_e32 v93, v67
	v_cvt_f32_i32_e32 v94, v68
	v_cvt_f32_i32_e32 v95, v69
	v_cvt_f32_i32_e32 v86, v62
	v_cvt_f32_i32_e32 v87, v63
	v_cvt_f32_i32_e32 v88, v64
	v_cvt_f32_i32_e32 v89, v65
	v_cvt_f32_i32_e32 v82, v58
	v_cvt_f32_i32_e32 v83, v59
	v_cvt_f32_i32_e32 v84, v60
	v_cvt_f32_i32_e32 v85, v61
	v_cvt_f32_i32_e32 v78, v46
	v_cvt_f32_i32_e32 v79, v47
	v_cvt_f32_i32_e32 v80, v48
	v_cvt_f32_i32_e32 v81, v49
	v_cvt_f32_i32_e32 v74, v38
	v_cvt_f32_i32_e32 v75, v39
	v_cvt_f32_i32_e32 v76, v40
	v_cvt_f32_i32_e32 v77, v41
	v_cvt_f32_i32_e32 v68, v54
	v_cvt_f32_i32_e32 v69, v55
	v_cvt_f32_i32_e32 v70, v56
	v_cvt_f32_i32_e32 v71, v57
	v_cvt_f32_i32_e32 v64, v50
	v_cvt_f32_i32_e32 v65, v51
	v_cvt_f32_i32_e32 v66, v52
	v_cvt_f32_i32_e32 v67, v53
	v_cvt_f32_i32_e32 v60, v30
	v_cvt_f32_i32_e32 v61, v31
	v_cvt_f32_i32_e32 v62, v32
	v_cvt_f32_i32_e32 v63, v33
	v_cvt_f32_i32_e32 v56, v22
	v_cvt_f32_i32_e32 v57, v23
	v_cvt_f32_i32_e32 v58, v24
	v_cvt_f32_i32_e32 v59, v25
	v_cvt_f32_i32_e32 v50, v42
	v_cvt_f32_i32_e32 v51, v43
	v_cvt_f32_i32_e32 v52, v44
	v_cvt_f32_i32_e32 v53, v45
	v_cvt_f32_i32_e32 v46, v34
	v_cvt_f32_i32_e32 v47, v35
	v_cvt_f32_i32_e32 v48, v36
	v_cvt_f32_i32_e32 v49, v37
	v_cvt_f32_i32_e32 v34, v14
	v_cvt_f32_i32_e32 v35, v15
	v_cvt_f32_i32_e32 v36, v16
	v_cvt_f32_i32_e32 v37, v17
	v_cvt_f32_i32_e32 v30, v10
	v_cvt_f32_i32_e32 v31, v11
	v_cvt_f32_i32_e32 v32, v12
	v_cvt_f32_i32_e32 v33, v13
	v_cvt_f32_i32_e32 v22, v26
	v_cvt_f32_i32_e32 v23, v27
	v_cvt_f32_i32_e32 v24, v28
	v_cvt_f32_i32_e32 v25, v29
	v_cvt_f32_i32_e32 v18, v18
	v_cvt_f32_i32_e32 v19, v19
	v_cvt_f32_i32_e32 v20, v20
	v_cvt_f32_i32_e32 v21, v21
	v_cvt_f32_i32_e32 v14, v6
	v_cvt_f32_i32_e32 v15, v7
	v_cvt_f32_i32_e32 v16, v8
	v_cvt_f32_i32_e32 v17, v9
	v_cvt_f32_i32_e32 v10, v2
	v_cvt_f32_i32_e32 v11, v3
	v_cvt_f32_i32_e32 v12, v4
	v_cvt_f32_i32_e32 v13, v5

.LBB0_1727:
	v_add_u32_e32 v150, s52, v1
	ds_read_b128 v[146:149], v150
	ds_read_b128 v[154:157], v150 offset:1024
	ds_read_b128 v[158:161], v150 offset:2048
	ds_read_b128 v[162:165], v150 offset:3072
	v_add_u32_e32 v150, s53, v1
	ds_read_b128 v[170:173], v150
	ds_read_b128 v[174:177], v150 offset:1024
	ds_read_b128 v[178:181], v150 offset:2048
	ds_read_b128 v[182:185], v150 offset:3072
	s_add_i32 s77, s48, 2
	s_add_u32 s78, s46, 0x80
	s_addc_u32 s49, s47, 0
	s_cmp_eq_u32 s72, s48
	s_cselect_b32 s48, s4, s78
	s_cselect_b32 s49, s5, s49
	s_cselect_b32 s79, s45, s76
	s_cselect_b32 s78, s44, s75
	v_lshl_add_u64 v[150:151], s[46:47], 0, v[138:139]
	s_add_i32 m0, s58, 0xc000
	ds_read_b128 v[186:189], v153
	ds_read_b128 v[190:193], v153 offset:1024
	ds_read_b128 v[194:197], v153 offset:2048
	ds_read_b128 v[198:201], v153 offset:3072
	ds_read_b128 v[202:205], v153 offset:4096
	ds_read_b128 v[206:209], v153 offset:5120
	ds_read_b128 v[210:213], v153 offset:6144
	ds_read_b128 v[214:217], v153 offset:7168
	global_load_lds_dwordx4 v[150:151], off
	v_lshl_add_u64 v[150:151], s[46:47], 0, v[140:141]
	s_add_i32 m0, s58, 0xe000
	s_nop 0
	global_load_lds_dwordx4 v[150:151], off
	s_waitcnt vmcnt(8)
	s_waitcnt lgkmcnt(0)
	s_barrier
	s_setprio 1
	v_mfma_i32_16x16x64_i8 v[126:129], v[146:149], v[186:189], v[126:129]
	v_mfma_i32_16x16x64_i8 v[122:125], v[158:161], v[186:189], v[122:125]
	v_mfma_i32_16x16x64_i8 v[118:121], v[146:149], v[194:197], v[118:121]
	v_mfma_i32_16x16x64_i8 v[114:117], v[158:161], v[194:197], v[114:117]
	v_mfma_i32_16x16x64_i8 v[106:109], v[146:149], v[202:205], v[106:109]
	v_mfma_i32_16x16x64_i8 v[98:101], v[158:161], v[202:205], v[98:101]
	v_mfma_i32_16x16x64_i8 v[90:93], v[146:149], v[210:213], v[90:93]
	v_mfma_i32_16x16x64_i8 v[82:85], v[158:161], v[210:213], v[82:85]
	v_mfma_i32_16x16x64_i8 v[126:129], v[154:157], v[190:193], v[126:129]
	v_mfma_i32_16x16x64_i8 v[122:125], v[162:165], v[190:193], v[122:125]
	v_mfma_i32_16x16x64_i8 v[118:121], v[154:157], v[198:201], v[118:121]
	v_mfma_i32_16x16x64_i8 v[114:117], v[162:165], v[198:201], v[114:117]
	v_mfma_i32_16x16x64_i8 v[106:109], v[154:157], v[206:209], v[106:109]
	v_mfma_i32_16x16x64_i8 v[98:101], v[162:165], v[206:209], v[98:101]
	v_mfma_i32_16x16x64_i8 v[90:93], v[154:157], v[214:217], v[90:93]
	v_mfma_i32_16x16x64_i8 v[82:85], v[162:165], v[214:217], v[82:85]
	v_mfma_i32_16x16x64_i8 v[110:113], v[170:173], v[186:189], v[110:113]
	v_mfma_i32_16x16x64_i8 v[102:105], v[178:181], v[186:189], v[102:105]
	v_mfma_i32_16x16x64_i8 v[94:97], v[170:173], v[194:197], v[94:97]
	v_mfma_i32_16x16x64_i8 v[86:89], v[178:181], v[194:197], v[86:89]
	v_mfma_i32_16x16x64_i8 v[78:81], v[170:173], v[202:205], v[78:81]
	v_mfma_i32_16x16x64_i8 v[74:77], v[178:181], v[202:205], v[74:77]
	v_mfma_i32_16x16x64_i8 v[70:73], v[170:173], v[210:213], v[70:73]
	v_mfma_i32_16x16x64_i8 v[66:69], v[178:181], v[210:213], v[66:69]
	v_mfma_i32_16x16x64_i8 v[110:113], v[174:177], v[190:193], v[110:113]
	v_mfma_i32_16x16x64_i8 v[102:105], v[182:185], v[190:193], v[102:105]
	v_mfma_i32_16x16x64_i8 v[94:97], v[174:177], v[198:201], v[94:97]
	v_mfma_i32_16x16x64_i8 v[86:89], v[182:185], v[198:201], v[86:89]
	v_mfma_i32_16x16x64_i8 v[78:81], v[174:177], v[206:209], v[78:81]
	v_mfma_i32_16x16x64_i8 v[74:77], v[182:185], v[206:209], v[74:77]
	v_mfma_i32_16x16x64_i8 v[70:73], v[174:177], v[214:217], v[70:73]
	v_mfma_i32_16x16x64_i8 v[66:69], v[182:185], v[214:217], v[66:69]
	s_setprio 0
	s_barrier
	s_add_i32 s80, s52, s51
	v_lshl_add_u64 v[150:151], s[78:79], 0, v[134:135]
	s_mov_b32 m0, s80
	ds_read_b128 v[186:189], v153 offset:16384
	ds_read_b128 v[190:193], v153 offset:17408
	ds_read_b128 v[194:197], v153 offset:18432
	ds_read_b128 v[198:201], v153 offset:19456
	ds_read_b128 v[202:205], v153 offset:20480
	ds_read_b128 v[206:209], v153 offset:21504
	ds_read_b128 v[210:213], v153 offset:22528
	ds_read_b128 v[214:217], v153 offset:23552
	global_load_lds_dwordx4 v[150:151], off
	s_add_i32 m0, s80, 0x2000
	v_lshl_add_u64 v[166:167], s[78:79], 0, v[130:131]
	s_add_u32 s78, s78, s14
	s_addc_u32 s79, s79, s15
	s_add_i32 s80, s53, s51
	global_load_lds_dwordx4 v[166:167], off
	v_lshl_add_u64 v[218:219], s[78:79], 0, v[134:135]
	s_mov_b32 m0, s80
	v_lshl_add_u64 v[220:221], s[78:79], 0, v[130:131]
	global_load_lds_dwordx4 v[218:219], off
	s_add_i32 m0, s80, 0x2000
	v_lshl_add_u64 v[222:223], s[48:49], 0, v[136:137]
	global_load_lds_dwordx4 v[220:221], off
	s_mov_b32 m0, s58
	v_lshl_add_u64 v[224:225], s[48:49], 0, v[132:133]
	global_load_lds_dwordx4 v[222:223], off
	s_mov_b32 m0, s59
	s_nop 0
	global_load_lds_dwordx4 v[224:225], off
	s_waitcnt vmcnt(8)
	s_waitcnt lgkmcnt(0)
	s_barrier
	s_setprio 1
	v_mfma_i32_16x16x64_i8 v[62:65], v[146:149], v[186:189], v[62:65]
	v_mfma_i32_16x16x64_i8 v[58:61], v[158:161], v[186:189], v[58:61]
	v_mfma_i32_16x16x64_i8 v[54:57], v[146:149], v[194:197], v[54:57]
	v_mfma_i32_16x16x64_i8 v[50:53], v[158:161], v[194:197], v[50:53]
	v_mfma_i32_16x16x64_i8 v[42:45], v[146:149], v[202:205], v[42:45]
	v_mfma_i32_16x16x64_i8 v[34:37], v[158:161], v[202:205], v[34:37]
	v_mfma_i32_16x16x64_i8 v[26:29], v[146:149], v[210:213], v[26:29]
	v_mfma_i32_16x16x64_i8 v[18:21], v[158:161], v[210:213], v[18:21]
	v_mfma_i32_16x16x64_i8 v[62:65], v[154:157], v[190:193], v[62:65]
	v_mfma_i32_16x16x64_i8 v[58:61], v[162:165], v[190:193], v[58:61]
	v_mfma_i32_16x16x64_i8 v[54:57], v[154:157], v[198:201], v[54:57]
	v_mfma_i32_16x16x64_i8 v[50:53], v[162:165], v[198:201], v[50:53]
	v_mfma_i32_16x16x64_i8 v[42:45], v[154:157], v[206:209], v[42:45]
	v_mfma_i32_16x16x64_i8 v[34:37], v[162:165], v[206:209], v[34:37]
	v_mfma_i32_16x16x64_i8 v[26:29], v[154:157], v[214:217], v[26:29]
	v_mfma_i32_16x16x64_i8 v[18:21], v[162:165], v[214:217], v[18:21]
	v_mfma_i32_16x16x64_i8 v[46:49], v[170:173], v[186:189], v[46:49]
	v_mfma_i32_16x16x64_i8 v[38:41], v[178:181], v[186:189], v[38:41]
	v_mfma_i32_16x16x64_i8 v[30:33], v[170:173], v[194:197], v[30:33]
	v_mfma_i32_16x16x64_i8 v[22:25], v[178:181], v[194:197], v[22:25]
	v_mfma_i32_16x16x64_i8 v[14:17], v[170:173], v[202:205], v[14:17]
	v_mfma_i32_16x16x64_i8 v[10:13], v[178:181], v[202:205], v[10:13]
	v_mfma_i32_16x16x64_i8 v[6:9], v[170:173], v[210:213], v[6:9]
	v_mfma_i32_16x16x64_i8 v[2:5], v[178:181], v[210:213], v[2:5]
	v_mfma_i32_16x16x64_i8 v[46:49], v[174:177], v[190:193], v[46:49]
	v_mfma_i32_16x16x64_i8 v[38:41], v[182:185], v[190:193], v[38:41]
	v_mfma_i32_16x16x64_i8 v[30:33], v[174:177], v[198:201], v[30:33]
	v_mfma_i32_16x16x64_i8 v[22:25], v[182:185], v[198:201], v[22:25]
	v_mfma_i32_16x16x64_i8 v[14:17], v[174:177], v[206:209], v[14:17]
	v_mfma_i32_16x16x64_i8 v[10:13], v[182:185], v[206:209], v[10:13]
	v_mfma_i32_16x16x64_i8 v[6:9], v[174:177], v[214:217], v[6:9]
	v_mfma_i32_16x16x64_i8 v[2:5], v[182:185], v[214:217], v[2:5]
	s_setprio 0
	s_barrier
	s_add_i32 s78, 0, 0x18000
	v_add_u32_e32 v152, s78, v1
	s_add_i32 s79, 0, 0x1c000
	ds_read_b128 v[146:149], v152
	ds_read_b128 v[154:157], v152 offset:1024
	ds_read_b128 v[158:161], v152 offset:2048
	ds_read_b128 v[162:165], v152 offset:3072
	v_add_u32_e32 v152, s79, v1
	ds_read_b128 v[170:173], v152
	ds_read_b128 v[174:177], v152 offset:1024
	ds_read_b128 v[178:181], v152 offset:2048
	ds_read_b128 v[182:185], v152 offset:3072
	s_add_u32 s48, s48, s14
	s_addc_u32 s49, s49, s15
	s_mov_b32 m0, s62
	v_lshl_add_u64 v[226:227], s[48:49], 0, v[136:137]
	ds_read_b128 v[186:189], v153 offset:32768
	ds_read_b128 v[190:193], v153 offset:33792
	ds_read_b128 v[194:197], v153 offset:34816
	ds_read_b128 v[198:201], v153 offset:35840
	ds_read_b128 v[202:205], v153 offset:36864
	ds_read_b128 v[206:209], v153 offset:37888
	ds_read_b128 v[210:213], v153 offset:38912
	ds_read_b128 v[214:217], v153 offset:39936
	global_load_lds_dwordx4 v[226:227], off
	v_lshl_add_u64 v[226:227], s[48:49], 0, v[132:133]
	s_mov_b32 m0, s63
	s_nop 0
	global_load_lds_dwordx4 v[226:227], off
	s_waitcnt vmcnt(8)
	s_waitcnt lgkmcnt(0)
	s_barrier
	s_setprio 1
	v_mfma_i32_16x16x64_i8 v[126:129], v[146:149], v[186:189], v[126:129]
	v_mfma_i32_16x16x64_i8 v[122:125], v[158:161], v[186:189], v[122:125]
	v_mfma_i32_16x16x64_i8 v[118:121], v[146:149], v[194:197], v[118:121]
	v_mfma_i32_16x16x64_i8 v[114:117], v[158:161], v[194:197], v[114:117]
	v_mfma_i32_16x16x64_i8 v[106:109], v[146:149], v[202:205], v[106:109]
	v_mfma_i32_16x16x64_i8 v[98:101], v[158:161], v[202:205], v[98:101]
	v_mfma_i32_16x16x64_i8 v[90:93], v[146:149], v[210:213], v[90:93]
	v_mfma_i32_16x16x64_i8 v[82:85], v[158:161], v[210:213], v[82:85]
	v_mfma_i32_16x16x64_i8 v[126:129], v[154:157], v[190:193], v[126:129]
	v_mfma_i32_16x16x64_i8 v[122:125], v[162:165], v[190:193], v[122:125]
	v_mfma_i32_16x16x64_i8 v[118:121], v[154:157], v[198:201], v[118:121]
	v_mfma_i32_16x16x64_i8 v[114:117], v[162:165], v[198:201], v[114:117]
	v_mfma_i32_16x16x64_i8 v[106:109], v[154:157], v[206:209], v[106:109]
	v_mfma_i32_16x16x64_i8 v[98:101], v[162:165], v[206:209], v[98:101]
	v_mfma_i32_16x16x64_i8 v[90:93], v[154:157], v[214:217], v[90:93]
	v_mfma_i32_16x16x64_i8 v[82:85], v[162:165], v[214:217], v[82:85]
	v_mfma_i32_16x16x64_i8 v[110:113], v[170:173], v[186:189], v[110:113]
	v_mfma_i32_16x16x64_i8 v[102:105], v[178:181], v[186:189], v[102:105]
	v_mfma_i32_16x16x64_i8 v[94:97], v[170:173], v[194:197], v[94:97]
	v_mfma_i32_16x16x64_i8 v[86:89], v[178:181], v[194:197], v[86:89]
	v_mfma_i32_16x16x64_i8 v[78:81], v[170:173], v[202:205], v[78:81]
	v_mfma_i32_16x16x64_i8 v[74:77], v[178:181], v[202:205], v[74:77]
	v_mfma_i32_16x16x64_i8 v[70:73], v[170:173], v[210:213], v[70:73]
	v_mfma_i32_16x16x64_i8 v[66:69], v[178:181], v[210:213], v[66:69]
	v_mfma_i32_16x16x64_i8 v[110:113], v[174:177], v[190:193], v[110:113]
	v_mfma_i32_16x16x64_i8 v[102:105], v[182:185], v[190:193], v[102:105]
	v_mfma_i32_16x16x64_i8 v[94:97], v[174:177], v[198:201], v[94:97]
	v_mfma_i32_16x16x64_i8 v[86:89], v[182:185], v[198:201], v[86:89]
	v_mfma_i32_16x16x64_i8 v[78:81], v[174:177], v[206:209], v[78:81]
	v_mfma_i32_16x16x64_i8 v[74:77], v[182:185], v[206:209], v[74:77]
	v_mfma_i32_16x16x64_i8 v[70:73], v[174:177], v[214:217], v[70:73]
	v_mfma_i32_16x16x64_i8 v[66:69], v[182:185], v[214:217], v[66:69]
	s_setprio 0
	s_barrier
	s_add_i32 s48, s78, s51
	v_lshl_add_u64 v[150:151], v[150:151], 0, s[24:25]
	s_mov_b32 m0, s48
	ds_read_b128 v[186:189], v153 offset:49152
	ds_read_b128 v[190:193], v153 offset:50176
	ds_read_b128 v[194:197], v153 offset:51200
	ds_read_b128 v[198:201], v153 offset:52224
	ds_read_b128 v[202:205], v153 offset:53248
	ds_read_b128 v[206:209], v153 offset:54272
	ds_read_b128 v[210:213], v153 offset:55296
	ds_read_b128 v[214:217], v153 offset:56320
	global_load_lds_dwordx4 v[150:151], off
	v_lshl_add_u64 v[150:151], v[166:167], 0, s[24:25]
	s_add_i32 m0, s48, 0x2000
	s_add_i32 s48, s79, s51
	global_load_lds_dwordx4 v[150:151], off
	v_lshl_add_u64 v[150:151], v[218:219], 0, s[24:25]
	s_mov_b32 m0, s48
	s_nop 0
	global_load_lds_dwordx4 v[150:151], off
	v_lshl_add_u64 v[150:151], v[220:221], 0, s[24:25]
	s_add_i32 m0, s48, 0x2000
	s_nop 0
	global_load_lds_dwordx4 v[150:151], off
	v_lshl_add_u64 v[150:151], v[222:223], 0, s[24:25]
	s_mov_b32 m0, s67
	s_nop 0
	global_load_lds_dwordx4 v[150:151], off
	v_lshl_add_u64 v[150:151], v[224:225], 0, s[24:25]
	s_mov_b32 m0, s68
	s_nop 0
	global_load_lds_dwordx4 v[150:151], off
	s_waitcnt vmcnt(8)
	s_waitcnt lgkmcnt(0)
	s_barrier
	s_setprio 1
	v_mfma_i32_16x16x64_i8 v[62:65], v[146:149], v[186:189], v[62:65]
	v_mfma_i32_16x16x64_i8 v[58:61], v[158:161], v[186:189], v[58:61]
	v_mfma_i32_16x16x64_i8 v[54:57], v[146:149], v[194:197], v[54:57]
	v_mfma_i32_16x16x64_i8 v[50:53], v[158:161], v[194:197], v[50:53]
	v_mfma_i32_16x16x64_i8 v[42:45], v[146:149], v[202:205], v[42:45]
	v_mfma_i32_16x16x64_i8 v[34:37], v[158:161], v[202:205], v[34:37]
	v_mfma_i32_16x16x64_i8 v[26:29], v[146:149], v[210:213], v[26:29]
	v_mfma_i32_16x16x64_i8 v[18:21], v[158:161], v[210:213], v[18:21]
	v_mfma_i32_16x16x64_i8 v[62:65], v[154:157], v[190:193], v[62:65]
	v_mfma_i32_16x16x64_i8 v[58:61], v[162:165], v[190:193], v[58:61]
	v_mfma_i32_16x16x64_i8 v[54:57], v[154:157], v[198:201], v[54:57]
	v_mfma_i32_16x16x64_i8 v[50:53], v[162:165], v[198:201], v[50:53]
	v_mfma_i32_16x16x64_i8 v[42:45], v[154:157], v[206:209], v[42:45]
	v_mfma_i32_16x16x64_i8 v[34:37], v[162:165], v[206:209], v[34:37]
	v_mfma_i32_16x16x64_i8 v[26:29], v[154:157], v[214:217], v[26:29]
	v_mfma_i32_16x16x64_i8 v[18:21], v[162:165], v[214:217], v[18:21]
	v_mfma_i32_16x16x64_i8 v[46:49], v[170:173], v[186:189], v[46:49]
	v_mfma_i32_16x16x64_i8 v[38:41], v[178:181], v[186:189], v[38:41]
	v_mfma_i32_16x16x64_i8 v[30:33], v[170:173], v[194:197], v[30:33]
	v_mfma_i32_16x16x64_i8 v[22:25], v[178:181], v[194:197], v[22:25]
	v_mfma_i32_16x16x64_i8 v[14:17], v[170:173], v[202:205], v[14:17]
	v_mfma_i32_16x16x64_i8 v[10:13], v[178:181], v[202:205], v[10:13]
	v_mfma_i32_16x16x64_i8 v[6:9], v[170:173], v[210:213], v[6:9]
	v_mfma_i32_16x16x64_i8 v[2:5], v[178:181], v[210:213], v[2:5]
	v_mfma_i32_16x16x64_i8 v[46:49], v[174:177], v[190:193], v[46:49]
	v_mfma_i32_16x16x64_i8 v[38:41], v[182:185], v[190:193], v[38:41]
	v_mfma_i32_16x16x64_i8 v[30:33], v[174:177], v[198:201], v[30:33]
	v_mfma_i32_16x16x64_i8 v[22:25], v[182:185], v[198:201], v[22:25]
	v_mfma_i32_16x16x64_i8 v[14:17], v[174:177], v[206:209], v[14:17]
	v_mfma_i32_16x16x64_i8 v[10:13], v[182:185], v[206:209], v[10:13]
	v_mfma_i32_16x16x64_i8 v[6:9], v[174:177], v[214:217], v[6:9]
	v_mfma_i32_16x16x64_i8 v[2:5], v[182:185], v[214:217], v[2:5]
	s_setprio 0
	s_barrier
	s_add_u32 s46, s46, 0x100
	s_addc_u32 s47, s47, 0
	s_add_u32 s75, s75, 0x100
	s_addc_u32 s76, s76, 0
	s_cmp_ge_i32 s77, s69
	s_mov_b32 s48, s77
	s_cbranch_scc0 .LBB0_1727
	v_cvt_f32_i32_e32 v180, v126
	v_cvt_f32_i32_e32 v181, v127
	v_cvt_f32_i32_e32 v178, v128
	v_cvt_f32_i32_e32 v179, v129
	v_cvt_f32_i32_e32 v182, v122
	v_cvt_f32_i32_e32 v183, v123
	v_cvt_f32_i32_e32 v184, v124
	v_cvt_f32_i32_e32 v185, v125
	v_cvt_f32_i32_e32 v164, v110
	v_cvt_f32_i32_e32 v165, v111
	v_cvt_f32_i32_e32 v166, v112
	v_cvt_f32_i32_e32 v167, v113
	v_cvt_f32_i32_e32 v170, v102
	v_cvt_f32_i32_e32 v171, v103
	v_cvt_f32_i32_e32 v172, v104
	v_cvt_f32_i32_e32 v173, v105
	v_cvt_f32_i32_e32 v156, v118
	v_cvt_f32_i32_e32 v157, v119
	v_cvt_f32_i32_e32 v158, v120
	v_cvt_f32_i32_e32 v159, v121
	v_cvt_f32_i32_e32 v160, v114
	v_cvt_f32_i32_e32 v161, v115
	v_cvt_f32_i32_e32 v162, v116
	v_cvt_f32_i32_e32 v163, v117
	v_cvt_f32_i32_e32 v126, v94
	v_cvt_f32_i32_e32 v127, v95
	v_cvt_f32_i32_e32 v128, v96
	v_cvt_f32_i32_e32 v129, v97
	v_cvt_f32_i32_e32 v146, v86
	v_cvt_f32_i32_e32 v147, v87
	v_cvt_f32_i32_e32 v148, v88
	v_cvt_f32_i32_e32 v149, v89
	v_cvt_f32_i32_e32 v118, v106
	v_cvt_f32_i32_e32 v119, v107
	v_cvt_f32_i32_e32 v120, v108
	v_cvt_f32_i32_e32 v121, v109
	v_cvt_f32_i32_e32 v122, v98
	v_cvt_f32_i32_e32 v123, v99
	v_cvt_f32_i32_e32 v124, v100
	v_cvt_f32_i32_e32 v125, v101
	v_cvt_f32_i32_e32 v108, v78
	v_cvt_f32_i32_e32 v109, v79
	v_cvt_f32_i32_e32 v110, v80
	v_cvt_f32_i32_e32 v111, v81
	v_cvt_f32_i32_e32 v112, v74
	v_cvt_f32_i32_e32 v113, v75
	v_cvt_f32_i32_e32 v114, v76
	v_cvt_f32_i32_e32 v115, v77
	v_cvt_f32_i32_e32 v100, v90
	v_cvt_f32_i32_e32 v101, v91
	v_cvt_f32_i32_e32 v102, v92
	v_cvt_f32_i32_e32 v103, v93
	v_cvt_f32_i32_e32 v104, v82
	v_cvt_f32_i32_e32 v105, v83
	v_cvt_f32_i32_e32 v106, v84
	v_cvt_f32_i32_e32 v107, v85
	v_cvt_f32_i32_e32 v90, v70
	v_cvt_f32_i32_e32 v91, v71
	v_cvt_f32_i32_e32 v92, v72
	v_cvt_f32_i32_e32 v93, v73
	v_cvt_f32_i32_e32 v94, v66
	v_cvt_f32_i32_e32 v95, v67
	v_cvt_f32_i32_e32 v96, v68
	v_cvt_f32_i32_e32 v97, v69
	v_cvt_f32_i32_e32 v82, v62
	v_cvt_f32_i32_e32 v83, v63
	v_cvt_f32_i32_e32 v84, v64
	v_cvt_f32_i32_e32 v85, v65
	v_cvt_f32_i32_e32 v86, v58
	v_cvt_f32_i32_e32 v87, v59
	v_cvt_f32_i32_e32 v88, v60
	v_cvt_f32_i32_e32 v89, v61
	v_cvt_f32_i32_e32 v72, v46
	v_cvt_f32_i32_e32 v73, v47
	v_cvt_f32_i32_e32 v74, v48
	v_cvt_f32_i32_e32 v75, v49
	v_cvt_f32_i32_e32 v76, v38
	v_cvt_f32_i32_e32 v77, v39
	v_cvt_f32_i32_e32 v78, v40
	v_cvt_f32_i32_e32 v79, v41
	v_cvt_f32_i32_e32 v64, v54
	v_cvt_f32_i32_e32 v65, v55
	v_cvt_f32_i32_e32 v66, v56
	v_cvt_f32_i32_e32 v67, v57
	v_cvt_f32_i32_e32 v68, v50
	v_cvt_f32_i32_e32 v69, v51
	v_cvt_f32_i32_e32 v70, v52
	v_cvt_f32_i32_e32 v71, v53
	v_cvt_f32_i32_e32 v54, v30
	v_cvt_f32_i32_e32 v55, v31
	v_cvt_f32_i32_e32 v56, v32
	v_cvt_f32_i32_e32 v57, v33
	v_cvt_f32_i32_e32 v58, v22
	v_cvt_f32_i32_e32 v59, v23
	v_cvt_f32_i32_e32 v60, v24
	v_cvt_f32_i32_e32 v61, v25
	v_cvt_f32_i32_e32 v46, v42
	v_cvt_f32_i32_e32 v47, v43
	v_cvt_f32_i32_e32 v48, v44
	v_cvt_f32_i32_e32 v49, v45
	v_cvt_f32_i32_e32 v50, v34
	v_cvt_f32_i32_e32 v51, v35
	v_cvt_f32_i32_e32 v52, v36
	v_cvt_f32_i32_e32 v53, v37
	v_cvt_f32_i32_e32 v34, v14
	v_cvt_f32_i32_e32 v35, v15
	v_cvt_f32_i32_e32 v36, v16
	v_cvt_f32_i32_e32 v37, v17
	v_cvt_f32_i32_e32 v38, v10
	v_cvt_f32_i32_e32 v39, v11
	v_cvt_f32_i32_e32 v40, v12
	v_cvt_f32_i32_e32 v41, v13
	v_cvt_f32_i32_e32 v26, v26
	v_cvt_f32_i32_e32 v27, v27
	v_cvt_f32_i32_e32 v28, v28
	v_cvt_f32_i32_e32 v29, v29
	v_cvt_f32_i32_e32 v30, v18
	v_cvt_f32_i32_e32 v31, v19
	v_cvt_f32_i32_e32 v32, v20
	v_cvt_f32_i32_e32 v33, v21
	v_cvt_f32_i32_e32 v18, v6
	v_cvt_f32_i32_e32 v19, v7
	v_cvt_f32_i32_e32 v20, v8
	v_cvt_f32_i32_e32 v21, v9
	v_cvt_f32_i32_e32 v22, v2
	v_cvt_f32_i32_e32 v23, v3
	v_cvt_f32_i32_e32 v24, v4
	v_cvt_f32_i32_e32 v25, v5
	v_readlane_b32 s77, v237, 59

.LBB0_1751:
	v_add_u32_e32 v158, s58, v1
	ds_read_b128 v[146:149], v158
	ds_read_b128 v[150:153], v158 offset:1024
	ds_read_b128 v[154:157], v158 offset:2048
	ds_read_b128 v[162:165], v158 offset:3072
	v_add_u32_e32 v158, s59, v1
	ds_read_b128 v[170:173], v158
	ds_read_b128 v[174:177], v158 offset:1024
	ds_read_b128 v[178:181], v158 offset:2048
	ds_read_b128 v[182:185], v158 offset:3072
	s_add_i32 s68, s38, 2
	s_add_u32 s69, s36, 0x80
	s_addc_u32 s39, s37, 0
	s_cmp_eq_u32 s55, s38
	s_cselect_b32 s38, s2, s69
	s_cselect_b32 s39, s3, s39
	s_cselect_b32 s71, s35, s67
	s_cselect_b32 s70, s34, s66
	v_lshl_add_u64 v[158:159], s[36:37], 0, v[138:139]
	s_add_i32 m0, s43, 0xc000
	ds_read_b128 v[186:189], v161
	ds_read_b128 v[190:193], v161 offset:1024
	ds_read_b128 v[194:197], v161 offset:2048
	ds_read_b128 v[198:201], v161 offset:3072
	ds_read_b128 v[202:205], v161 offset:4096
	ds_read_b128 v[206:209], v161 offset:5120
	ds_read_b128 v[210:213], v161 offset:6144
	ds_read_b128 v[214:217], v161 offset:7168
	global_load_lds_dwordx4 v[158:159], off
	v_lshl_add_u64 v[158:159], s[36:37], 0, v[140:141]
	s_add_i32 m0, s43, 0xe000
	s_nop 0
	global_load_lds_dwordx4 v[158:159], off
	s_waitcnt vmcnt(8)
	s_waitcnt lgkmcnt(0)
	s_barrier
	s_setprio 1
	v_mfma_i32_16x16x64_i8 v[126:129], v[146:149], v[186:189], v[126:129]
	v_mfma_i32_16x16x64_i8 v[122:125], v[154:157], v[186:189], v[122:125]
	v_mfma_i32_16x16x64_i8 v[118:121], v[146:149], v[194:197], v[118:121]
	v_mfma_i32_16x16x64_i8 v[114:117], v[154:157], v[194:197], v[114:117]
	v_mfma_i32_16x16x64_i8 v[106:109], v[146:149], v[202:205], v[106:109]
	v_mfma_i32_16x16x64_i8 v[98:101], v[154:157], v[202:205], v[98:101]
	v_mfma_i32_16x16x64_i8 v[90:93], v[146:149], v[210:213], v[90:93]
	v_mfma_i32_16x16x64_i8 v[82:85], v[154:157], v[210:213], v[82:85]
	v_mfma_i32_16x16x64_i8 v[126:129], v[150:153], v[190:193], v[126:129]
	v_mfma_i32_16x16x64_i8 v[122:125], v[162:165], v[190:193], v[122:125]
	v_mfma_i32_16x16x64_i8 v[118:121], v[150:153], v[198:201], v[118:121]
	v_mfma_i32_16x16x64_i8 v[114:117], v[162:165], v[198:201], v[114:117]
	v_mfma_i32_16x16x64_i8 v[106:109], v[150:153], v[206:209], v[106:109]
	v_mfma_i32_16x16x64_i8 v[98:101], v[162:165], v[206:209], v[98:101]
	v_mfma_i32_16x16x64_i8 v[90:93], v[150:153], v[214:217], v[90:93]
	v_mfma_i32_16x16x64_i8 v[82:85], v[162:165], v[214:217], v[82:85]
	v_mfma_i32_16x16x64_i8 v[110:113], v[170:173], v[186:189], v[110:113]
	v_mfma_i32_16x16x64_i8 v[102:105], v[178:181], v[186:189], v[102:105]
	v_mfma_i32_16x16x64_i8 v[94:97], v[170:173], v[194:197], v[94:97]
	v_mfma_i32_16x16x64_i8 v[86:89], v[178:181], v[194:197], v[86:89]
	v_mfma_i32_16x16x64_i8 v[78:81], v[170:173], v[202:205], v[78:81]
	v_mfma_i32_16x16x64_i8 v[74:77], v[178:181], v[202:205], v[74:77]
	v_mfma_i32_16x16x64_i8 v[70:73], v[170:173], v[210:213], v[70:73]
	v_mfma_i32_16x16x64_i8 v[66:69], v[178:181], v[210:213], v[66:69]
	v_mfma_i32_16x16x64_i8 v[110:113], v[174:177], v[190:193], v[110:113]
	v_mfma_i32_16x16x64_i8 v[102:105], v[182:185], v[190:193], v[102:105]
	v_mfma_i32_16x16x64_i8 v[94:97], v[174:177], v[198:201], v[94:97]
	v_mfma_i32_16x16x64_i8 v[86:89], v[182:185], v[198:201], v[86:89]
	v_mfma_i32_16x16x64_i8 v[78:81], v[174:177], v[206:209], v[78:81]
	v_mfma_i32_16x16x64_i8 v[74:77], v[182:185], v[206:209], v[74:77]
	v_mfma_i32_16x16x64_i8 v[70:73], v[174:177], v[214:217], v[70:73]
	v_mfma_i32_16x16x64_i8 v[66:69], v[182:185], v[214:217], v[66:69]
	s_setprio 0
	s_barrier
	s_add_i32 s69, s58, s42
	v_lshl_add_u64 v[158:159], s[70:71], 0, v[132:133]
	s_mov_b32 m0, s69
	ds_read_b128 v[186:189], v161 offset:16384
	ds_read_b128 v[190:193], v161 offset:17408
	ds_read_b128 v[194:197], v161 offset:18432
	ds_read_b128 v[198:201], v161 offset:19456
	ds_read_b128 v[202:205], v161 offset:20480
	ds_read_b128 v[206:209], v161 offset:21504
	ds_read_b128 v[210:213], v161 offset:22528
	ds_read_b128 v[214:217], v161 offset:23552
	global_load_lds_dwordx4 v[158:159], off
	s_add_i32 m0, s69, 0x2000
	v_lshl_add_u64 v[166:167], s[70:71], 0, v[136:137]
	s_add_u32 s70, s70, s4
	s_addc_u32 s71, s71, s5
	s_add_i32 s69, s59, s42
	global_load_lds_dwordx4 v[166:167], off
	v_lshl_add_u64 v[218:219], s[70:71], 0, v[132:133]
	s_mov_b32 m0, s69
	v_lshl_add_u64 v[220:221], s[70:71], 0, v[136:137]
	global_load_lds_dwordx4 v[218:219], off
	s_add_i32 m0, s69, 0x2000
	v_lshl_add_u64 v[222:223], s[38:39], 0, v[130:131]
	global_load_lds_dwordx4 v[220:221], off
	s_mov_b32 m0, s43
	v_lshl_add_u64 v[224:225], s[38:39], 0, v[134:135]
	global_load_lds_dwordx4 v[222:223], off
	s_mov_b32 m0, s44
	s_nop 0
	global_load_lds_dwordx4 v[224:225], off
	s_waitcnt vmcnt(8)
	s_waitcnt lgkmcnt(0)
	s_barrier
	s_setprio 1
	v_mfma_i32_16x16x64_i8 v[62:65], v[146:149], v[186:189], v[62:65]
	v_mfma_i32_16x16x64_i8 v[58:61], v[154:157], v[186:189], v[58:61]
	v_mfma_i32_16x16x64_i8 v[54:57], v[146:149], v[194:197], v[54:57]
	v_mfma_i32_16x16x64_i8 v[50:53], v[154:157], v[194:197], v[50:53]
	v_mfma_i32_16x16x64_i8 v[42:45], v[146:149], v[202:205], v[42:45]
	v_mfma_i32_16x16x64_i8 v[34:37], v[154:157], v[202:205], v[34:37]
	v_mfma_i32_16x16x64_i8 v[26:29], v[146:149], v[210:213], v[26:29]
	v_mfma_i32_16x16x64_i8 v[18:21], v[154:157], v[210:213], v[18:21]
	v_mfma_i32_16x16x64_i8 v[62:65], v[150:153], v[190:193], v[62:65]
	v_mfma_i32_16x16x64_i8 v[58:61], v[162:165], v[190:193], v[58:61]
	v_mfma_i32_16x16x64_i8 v[54:57], v[150:153], v[198:201], v[54:57]
	v_mfma_i32_16x16x64_i8 v[50:53], v[162:165], v[198:201], v[50:53]
	v_mfma_i32_16x16x64_i8 v[42:45], v[150:153], v[206:209], v[42:45]
	v_mfma_i32_16x16x64_i8 v[34:37], v[162:165], v[206:209], v[34:37]
	v_mfma_i32_16x16x64_i8 v[26:29], v[150:153], v[214:217], v[26:29]
	v_mfma_i32_16x16x64_i8 v[18:21], v[162:165], v[214:217], v[18:21]
	v_mfma_i32_16x16x64_i8 v[46:49], v[170:173], v[186:189], v[46:49]
	v_mfma_i32_16x16x64_i8 v[38:41], v[178:181], v[186:189], v[38:41]
	v_mfma_i32_16x16x64_i8 v[30:33], v[170:173], v[194:197], v[30:33]
	v_mfma_i32_16x16x64_i8 v[22:25], v[178:181], v[194:197], v[22:25]
	v_mfma_i32_16x16x64_i8 v[14:17], v[170:173], v[202:205], v[14:17]
	v_mfma_i32_16x16x64_i8 v[10:13], v[178:181], v[202:205], v[10:13]
	v_mfma_i32_16x16x64_i8 v[6:9], v[170:173], v[210:213], v[6:9]
	v_mfma_i32_16x16x64_i8 v[2:5], v[178:181], v[210:213], v[2:5]
	v_mfma_i32_16x16x64_i8 v[46:49], v[174:177], v[190:193], v[46:49]
	v_mfma_i32_16x16x64_i8 v[38:41], v[182:185], v[190:193], v[38:41]
	v_mfma_i32_16x16x64_i8 v[30:33], v[174:177], v[198:201], v[30:33]
	v_mfma_i32_16x16x64_i8 v[22:25], v[182:185], v[198:201], v[22:25]
	v_mfma_i32_16x16x64_i8 v[14:17], v[174:177], v[206:209], v[14:17]
	v_mfma_i32_16x16x64_i8 v[10:13], v[182:185], v[206:209], v[10:13]
	v_mfma_i32_16x16x64_i8 v[6:9], v[174:177], v[214:217], v[6:9]
	v_mfma_i32_16x16x64_i8 v[2:5], v[182:185], v[214:217], v[2:5]
	s_setprio 0
	s_barrier
	s_add_i32 s69, 0, 0x18000
	v_add_u32_e32 v160, s69, v1
	s_add_i32 s70, 0, 0x1c000
	ds_read_b128 v[146:149], v160
	ds_read_b128 v[150:153], v160 offset:1024
	ds_read_b128 v[154:157], v160 offset:2048
	ds_read_b128 v[162:165], v160 offset:3072
	v_add_u32_e32 v160, s70, v1
	ds_read_b128 v[170:173], v160
	ds_read_b128 v[174:177], v160 offset:1024
	ds_read_b128 v[178:181], v160 offset:2048
	ds_read_b128 v[182:185], v160 offset:3072
	s_add_u32 s38, s38, s4
	s_addc_u32 s39, s39, s5
	s_mov_b32 m0, s45
	v_lshl_add_u64 v[226:227], s[38:39], 0, v[130:131]
	ds_read_b128 v[186:189], v161 offset:32768
	ds_read_b128 v[190:193], v161 offset:33792
	ds_read_b128 v[194:197], v161 offset:34816
	ds_read_b128 v[198:201], v161 offset:35840
	ds_read_b128 v[202:205], v161 offset:36864
	ds_read_b128 v[206:209], v161 offset:37888
	ds_read_b128 v[210:213], v161 offset:38912
	ds_read_b128 v[214:217], v161 offset:39936
	global_load_lds_dwordx4 v[226:227], off
	v_lshl_add_u64 v[226:227], s[38:39], 0, v[134:135]
	s_mov_b32 m0, s46
	s_nop 0
	global_load_lds_dwordx4 v[226:227], off
	s_waitcnt vmcnt(8)
	s_waitcnt lgkmcnt(0)
	s_barrier
	s_setprio 1
	v_mfma_i32_16x16x64_i8 v[126:129], v[146:149], v[186:189], v[126:129]
	v_mfma_i32_16x16x64_i8 v[122:125], v[154:157], v[186:189], v[122:125]
	v_mfma_i32_16x16x64_i8 v[118:121], v[146:149], v[194:197], v[118:121]
	v_mfma_i32_16x16x64_i8 v[114:117], v[154:157], v[194:197], v[114:117]
	v_mfma_i32_16x16x64_i8 v[106:109], v[146:149], v[202:205], v[106:109]
	v_mfma_i32_16x16x64_i8 v[98:101], v[154:157], v[202:205], v[98:101]
	v_mfma_i32_16x16x64_i8 v[90:93], v[146:149], v[210:213], v[90:93]
	v_mfma_i32_16x16x64_i8 v[82:85], v[154:157], v[210:213], v[82:85]
	v_mfma_i32_16x16x64_i8 v[126:129], v[150:153], v[190:193], v[126:129]
	v_mfma_i32_16x16x64_i8 v[122:125], v[162:165], v[190:193], v[122:125]
	v_mfma_i32_16x16x64_i8 v[118:121], v[150:153], v[198:201], v[118:121]
	v_mfma_i32_16x16x64_i8 v[114:117], v[162:165], v[198:201], v[114:117]
	v_mfma_i32_16x16x64_i8 v[106:109], v[150:153], v[206:209], v[106:109]
	v_mfma_i32_16x16x64_i8 v[98:101], v[162:165], v[206:209], v[98:101]
	v_mfma_i32_16x16x64_i8 v[90:93], v[150:153], v[214:217], v[90:93]
	v_mfma_i32_16x16x64_i8 v[82:85], v[162:165], v[214:217], v[82:85]
	v_mfma_i32_16x16x64_i8 v[110:113], v[170:173], v[186:189], v[110:113]
	v_mfma_i32_16x16x64_i8 v[102:105], v[178:181], v[186:189], v[102:105]
	v_mfma_i32_16x16x64_i8 v[94:97], v[170:173], v[194:197], v[94:97]
	v_mfma_i32_16x16x64_i8 v[86:89], v[178:181], v[194:197], v[86:89]
	v_mfma_i32_16x16x64_i8 v[78:81], v[170:173], v[202:205], v[78:81]
	v_mfma_i32_16x16x64_i8 v[74:77], v[178:181], v[202:205], v[74:77]
	v_mfma_i32_16x16x64_i8 v[70:73], v[170:173], v[210:213], v[70:73]
	v_mfma_i32_16x16x64_i8 v[66:69], v[178:181], v[210:213], v[66:69]
	v_mfma_i32_16x16x64_i8 v[110:113], v[174:177], v[190:193], v[110:113]
	v_mfma_i32_16x16x64_i8 v[102:105], v[182:185], v[190:193], v[102:105]
	v_mfma_i32_16x16x64_i8 v[94:97], v[174:177], v[198:201], v[94:97]
	v_mfma_i32_16x16x64_i8 v[86:89], v[182:185], v[198:201], v[86:89]
	v_mfma_i32_16x16x64_i8 v[78:81], v[174:177], v[206:209], v[78:81]
	v_mfma_i32_16x16x64_i8 v[74:77], v[182:185], v[206:209], v[74:77]
	v_mfma_i32_16x16x64_i8 v[70:73], v[174:177], v[214:217], v[70:73]
	v_mfma_i32_16x16x64_i8 v[66:69], v[182:185], v[214:217], v[66:69]
	s_setprio 0
	s_barrier
	s_add_i32 s38, s69, s42
	v_lshl_add_u64 v[158:159], v[158:159], 0, s[24:25]
	s_mov_b32 m0, s38
	ds_read_b128 v[186:189], v161 offset:49152
	ds_read_b128 v[190:193], v161 offset:50176
	ds_read_b128 v[194:197], v161 offset:51200
	ds_read_b128 v[198:201], v161 offset:52224
	ds_read_b128 v[202:205], v161 offset:53248
	ds_read_b128 v[206:209], v161 offset:54272
	ds_read_b128 v[210:213], v161 offset:55296
	ds_read_b128 v[214:217], v161 offset:56320
	global_load_lds_dwordx4 v[158:159], off
	v_lshl_add_u64 v[158:159], v[166:167], 0, s[24:25]
	s_add_i32 m0, s38, 0x2000
	s_add_i32 s38, s70, s42
	global_load_lds_dwordx4 v[158:159], off
	v_lshl_add_u64 v[158:159], v[218:219], 0, s[24:25]
	s_mov_b32 m0, s38
	s_nop 0
	global_load_lds_dwordx4 v[158:159], off
	v_lshl_add_u64 v[158:159], v[220:221], 0, s[24:25]
	s_add_i32 m0, s38, 0x2000
	s_nop 0
	global_load_lds_dwordx4 v[158:159], off
	v_lshl_add_u64 v[158:159], v[222:223], 0, s[24:25]
	s_mov_b32 m0, s50
	s_nop 0
	global_load_lds_dwordx4 v[158:159], off
	v_lshl_add_u64 v[158:159], v[224:225], 0, s[24:25]
	s_mov_b32 m0, s51
	s_nop 0
	global_load_lds_dwordx4 v[158:159], off
	s_waitcnt vmcnt(8)
	s_waitcnt lgkmcnt(0)
	s_barrier
	s_setprio 1
	v_mfma_i32_16x16x64_i8 v[62:65], v[146:149], v[186:189], v[62:65]
	v_mfma_i32_16x16x64_i8 v[58:61], v[154:157], v[186:189], v[58:61]
	v_mfma_i32_16x16x64_i8 v[54:57], v[146:149], v[194:197], v[54:57]
	v_mfma_i32_16x16x64_i8 v[50:53], v[154:157], v[194:197], v[50:53]
	v_mfma_i32_16x16x64_i8 v[42:45], v[146:149], v[202:205], v[42:45]
	v_mfma_i32_16x16x64_i8 v[34:37], v[154:157], v[202:205], v[34:37]
	v_mfma_i32_16x16x64_i8 v[26:29], v[146:149], v[210:213], v[26:29]
	v_mfma_i32_16x16x64_i8 v[18:21], v[154:157], v[210:213], v[18:21]
	v_mfma_i32_16x16x64_i8 v[62:65], v[150:153], v[190:193], v[62:65]
	v_mfma_i32_16x16x64_i8 v[58:61], v[162:165], v[190:193], v[58:61]
	v_mfma_i32_16x16x64_i8 v[54:57], v[150:153], v[198:201], v[54:57]
	v_mfma_i32_16x16x64_i8 v[50:53], v[162:165], v[198:201], v[50:53]
	v_mfma_i32_16x16x64_i8 v[42:45], v[150:153], v[206:209], v[42:45]
	v_mfma_i32_16x16x64_i8 v[34:37], v[162:165], v[206:209], v[34:37]
	v_mfma_i32_16x16x64_i8 v[26:29], v[150:153], v[214:217], v[26:29]
	v_mfma_i32_16x16x64_i8 v[18:21], v[162:165], v[214:217], v[18:21]
	v_mfma_i32_16x16x64_i8 v[46:49], v[170:173], v[186:189], v[46:49]
	v_mfma_i32_16x16x64_i8 v[38:41], v[178:181], v[186:189], v[38:41]
	v_mfma_i32_16x16x64_i8 v[30:33], v[170:173], v[194:197], v[30:33]
	v_mfma_i32_16x16x64_i8 v[22:25], v[178:181], v[194:197], v[22:25]
	v_mfma_i32_16x16x64_i8 v[14:17], v[170:173], v[202:205], v[14:17]
	v_mfma_i32_16x16x64_i8 v[10:13], v[178:181], v[202:205], v[10:13]
	v_mfma_i32_16x16x64_i8 v[6:9], v[170:173], v[210:213], v[6:9]
	v_mfma_i32_16x16x64_i8 v[2:5], v[178:181], v[210:213], v[2:5]
	v_mfma_i32_16x16x64_i8 v[46:49], v[174:177], v[190:193], v[46:49]
	v_mfma_i32_16x16x64_i8 v[38:41], v[182:185], v[190:193], v[38:41]
	v_mfma_i32_16x16x64_i8 v[30:33], v[174:177], v[198:201], v[30:33]
	v_mfma_i32_16x16x64_i8 v[22:25], v[182:185], v[198:201], v[22:25]
	v_mfma_i32_16x16x64_i8 v[14:17], v[174:177], v[206:209], v[14:17]
	v_mfma_i32_16x16x64_i8 v[10:13], v[182:185], v[206:209], v[10:13]
	v_mfma_i32_16x16x64_i8 v[6:9], v[174:177], v[214:217], v[6:9]
	v_mfma_i32_16x16x64_i8 v[2:5], v[182:185], v[214:217], v[2:5]
	s_setprio 0
	s_barrier
	s_add_u32 s36, s36, 0x100
	s_addc_u32 s37, s37, 0
	s_add_u32 s66, s66, 0x100
	s_addc_u32 s67, s67, 0
	s_cmp_ge_i32 s68, s52
	s_mov_b32 s38, s68
	s_cbranch_scc0 .LBB0_1751
	v_cvt_f32_i32_e32 v176, v126
	v_cvt_f32_i32_e32 v177, v127
	v_cvt_f32_i32_e32 v174, v128
	v_cvt_f32_i32_e32 v175, v129
	v_cvt_f32_i32_e32 v178, v122
	v_cvt_f32_i32_e32 v179, v123
	v_cvt_f32_i32_e32 v180, v124
	v_cvt_f32_i32_e32 v181, v125
	v_cvt_f32_i32_e32 v162, v110
	v_cvt_f32_i32_e32 v163, v111
	v_cvt_f32_i32_e32 v164, v112
	v_cvt_f32_i32_e32 v165, v113
	v_cvt_f32_i32_e32 v166, v102
	v_cvt_f32_i32_e32 v167, v103
	v_cvt_f32_i32_e32 v170, v104
	v_cvt_f32_i32_e32 v171, v105
	v_cvt_f32_i32_e32 v152, v118
	v_cvt_f32_i32_e32 v153, v119
	v_cvt_f32_i32_e32 v154, v120
	v_cvt_f32_i32_e32 v155, v121
	v_cvt_f32_i32_e32 v156, v114
	v_cvt_f32_i32_e32 v157, v115
	v_cvt_f32_i32_e32 v158, v116
	v_cvt_f32_i32_e32 v159, v117
	v_cvt_f32_i32_e32 v126, v94
	v_cvt_f32_i32_e32 v127, v95
	v_cvt_f32_i32_e32 v128, v96
	v_cvt_f32_i32_e32 v129, v97
	v_cvt_f32_i32_e32 v146, v86
	v_cvt_f32_i32_e32 v147, v87
	v_cvt_f32_i32_e32 v148, v88
	v_cvt_f32_i32_e32 v149, v89
	v_cvt_f32_i32_e32 v118, v106
	v_cvt_f32_i32_e32 v119, v107
	v_cvt_f32_i32_e32 v120, v108
	v_cvt_f32_i32_e32 v121, v109
	v_cvt_f32_i32_e32 v122, v98
	v_cvt_f32_i32_e32 v123, v99
	v_cvt_f32_i32_e32 v124, v100
	v_cvt_f32_i32_e32 v125, v101
	v_cvt_f32_i32_e32 v108, v78
	v_cvt_f32_i32_e32 v109, v79
	v_cvt_f32_i32_e32 v110, v80
	v_cvt_f32_i32_e32 v111, v81
	v_cvt_f32_i32_e32 v112, v74
	v_cvt_f32_i32_e32 v113, v75
	v_cvt_f32_i32_e32 v114, v76
	v_cvt_f32_i32_e32 v115, v77
	v_cvt_f32_i32_e32 v100, v90
	v_cvt_f32_i32_e32 v101, v91
	v_cvt_f32_i32_e32 v102, v92
	v_cvt_f32_i32_e32 v103, v93
	v_cvt_f32_i32_e32 v104, v82
	v_cvt_f32_i32_e32 v105, v83
	v_cvt_f32_i32_e32 v106, v84
	v_cvt_f32_i32_e32 v107, v85
	v_cvt_f32_i32_e32 v90, v70
	v_cvt_f32_i32_e32 v91, v71
	v_cvt_f32_i32_e32 v92, v72
	v_cvt_f32_i32_e32 v93, v73
	v_cvt_f32_i32_e32 v94, v66
	v_cvt_f32_i32_e32 v95, v67
	v_cvt_f32_i32_e32 v96, v68
	v_cvt_f32_i32_e32 v97, v69
	v_cvt_f32_i32_e32 v82, v62
	v_cvt_f32_i32_e32 v83, v63
	v_cvt_f32_i32_e32 v84, v64
	v_cvt_f32_i32_e32 v85, v65
	v_cvt_f32_i32_e32 v86, v58
	v_cvt_f32_i32_e32 v87, v59
	v_cvt_f32_i32_e32 v88, v60
	v_cvt_f32_i32_e32 v89, v61
	v_cvt_f32_i32_e32 v74, v46
	v_cvt_f32_i32_e32 v75, v47
	v_cvt_f32_i32_e32 v76, v48
	v_cvt_f32_i32_e32 v77, v49
	v_cvt_f32_i32_e32 v78, v38
	v_cvt_f32_i32_e32 v79, v39
	v_cvt_f32_i32_e32 v80, v40
	v_cvt_f32_i32_e32 v81, v41
	v_cvt_f32_i32_e32 v54, v54
	v_cvt_f32_i32_e32 v55, v55
	v_cvt_f32_i32_e32 v56, v56
	v_cvt_f32_i32_e32 v57, v57
	v_cvt_f32_i32_e32 v58, v50
	v_cvt_f32_i32_e32 v59, v51
	v_cvt_f32_i32_e32 v60, v52
	v_cvt_f32_i32_e32 v61, v53
	v_cvt_f32_i32_e32 v46, v30
	v_cvt_f32_i32_e32 v47, v31
	v_cvt_f32_i32_e32 v48, v32
	v_cvt_f32_i32_e32 v49, v33
	v_cvt_f32_i32_e32 v50, v22
	v_cvt_f32_i32_e32 v51, v23
	v_cvt_f32_i32_e32 v52, v24
	v_cvt_f32_i32_e32 v53, v25
	v_cvt_f32_i32_e32 v38, v42
	v_cvt_f32_i32_e32 v39, v43
	v_cvt_f32_i32_e32 v40, v44
	v_cvt_f32_i32_e32 v41, v45
	v_cvt_f32_i32_e32 v34, v34
	v_cvt_f32_i32_e32 v35, v35
	v_cvt_f32_i32_e32 v36, v36
	v_cvt_f32_i32_e32 v37, v37
	v_cvt_f32_i32_e32 v22, v14
	v_cvt_f32_i32_e32 v23, v15
	v_cvt_f32_i32_e32 v24, v16
	v_cvt_f32_i32_e32 v25, v17
	v_cvt_f32_i32_e32 v30, v10
	v_cvt_f32_i32_e32 v31, v11
	v_cvt_f32_i32_e32 v32, v12
	v_cvt_f32_i32_e32 v33, v13
	v_cvt_f32_i32_e32 v10, v26
	v_cvt_f32_i32_e32 v11, v27
	v_cvt_f32_i32_e32 v12, v28
	v_cvt_f32_i32_e32 v13, v29
	v_cvt_f32_i32_e32 v14, v18
	v_cvt_f32_i32_e32 v15, v19
	v_cvt_f32_i32_e32 v16, v20
	v_cvt_f32_i32_e32 v17, v21
	v_cvt_f32_i32_e32 v6, v6
	v_cvt_f32_i32_e32 v7, v7
	v_cvt_f32_i32_e32 v8, v8
	v_cvt_f32_i32_e32 v9, v9
	v_cvt_f32_i32_e32 v2, v2
	v_cvt_f32_i32_e32 v3, v3
	v_cvt_f32_i32_e32 v4, v4
	v_cvt_f32_i32_e32 v5, v5

.LBB0_1896:
	v_add_u32_e32 v150, s67, v1
	ds_read_b128 v[146:149], v150
	ds_read_b128 v[152:155], v150 offset:1024
	ds_read_b128 v[156:159], v150 offset:2048
	ds_read_b128 v[160:163], v150 offset:3072
	v_add_u32_e32 v150, s68, v1
	ds_read_b128 v[164:167], v150
	ds_read_b128 v[170:173], v150 offset:1024
	ds_read_b128 v[174:177], v150 offset:2048
	ds_read_b128 v[178:181], v150 offset:3072
	s_add_i32 s73, s38, 2
	s_add_u32 s74, s36, 0x80
	s_addc_u32 s39, s37, 0
	s_cmp_eq_u32 s63, s38
	s_cselect_b32 s38, s2, s74
	s_cselect_b32 s39, s3, s39
	s_cselect_b32 s75, s35, s72
	s_cselect_b32 s74, s34, s71
	v_lshl_add_u64 v[214:215], s[36:37], 0, v[138:139]
	s_add_i32 m0, s90, 0xc000
	ds_read_b128 v[182:185], v151
	ds_read_b128 v[186:189], v151 offset:1024
	ds_read_b128 v[190:193], v151 offset:2048
	ds_read_b128 v[194:197], v151 offset:3072
	ds_read_b128 v[198:201], v151 offset:4096
	ds_read_b128 v[202:205], v151 offset:5120
	ds_read_b128 v[206:209], v151 offset:6144
	ds_read_b128 v[210:213], v151 offset:7168
	global_load_lds_dwordx4 v[214:215], off
	v_lshl_add_u64 v[214:215], s[36:37], 0, v[140:141]
	s_add_i32 m0, s90, 0xe000
	s_nop 0
	global_load_lds_dwordx4 v[214:215], off
	s_waitcnt vmcnt(8)
	s_waitcnt lgkmcnt(0)
	s_barrier
	s_setprio 1
	v_mfma_i32_16x16x64_i8 v[126:129], v[146:149], v[182:185], v[126:129]
	v_mfma_i32_16x16x64_i8 v[122:125], v[156:159], v[182:185], v[122:125]
	v_mfma_i32_16x16x64_i8 v[118:121], v[146:149], v[190:193], v[118:121]
	v_mfma_i32_16x16x64_i8 v[114:117], v[156:159], v[190:193], v[114:117]
	v_mfma_i32_16x16x64_i8 v[106:109], v[146:149], v[198:201], v[106:109]
	v_mfma_i32_16x16x64_i8 v[98:101], v[156:159], v[198:201], v[98:101]
	v_mfma_i32_16x16x64_i8 v[90:93], v[146:149], v[206:209], v[90:93]
	v_mfma_i32_16x16x64_i8 v[82:85], v[156:159], v[206:209], v[82:85]
	v_mfma_i32_16x16x64_i8 v[126:129], v[152:155], v[186:189], v[126:129]
	v_mfma_i32_16x16x64_i8 v[122:125], v[160:163], v[186:189], v[122:125]
	v_mfma_i32_16x16x64_i8 v[118:121], v[152:155], v[194:197], v[118:121]
	v_mfma_i32_16x16x64_i8 v[114:117], v[160:163], v[194:197], v[114:117]
	v_mfma_i32_16x16x64_i8 v[106:109], v[152:155], v[202:205], v[106:109]
	v_mfma_i32_16x16x64_i8 v[98:101], v[160:163], v[202:205], v[98:101]
	v_mfma_i32_16x16x64_i8 v[90:93], v[152:155], v[210:213], v[90:93]
	v_mfma_i32_16x16x64_i8 v[82:85], v[160:163], v[210:213], v[82:85]
	v_mfma_i32_16x16x64_i8 v[110:113], v[164:167], v[182:185], v[110:113]
	v_mfma_i32_16x16x64_i8 v[102:105], v[174:177], v[182:185], v[102:105]
	v_mfma_i32_16x16x64_i8 v[94:97], v[164:167], v[190:193], v[94:97]
	v_mfma_i32_16x16x64_i8 v[86:89], v[174:177], v[190:193], v[86:89]
	v_mfma_i32_16x16x64_i8 v[78:81], v[164:167], v[198:201], v[78:81]
	v_mfma_i32_16x16x64_i8 v[74:77], v[174:177], v[198:201], v[74:77]
	v_mfma_i32_16x16x64_i8 v[70:73], v[164:167], v[206:209], v[70:73]
	v_mfma_i32_16x16x64_i8 v[66:69], v[174:177], v[206:209], v[66:69]
	v_mfma_i32_16x16x64_i8 v[110:113], v[170:173], v[186:189], v[110:113]
	v_mfma_i32_16x16x64_i8 v[102:105], v[178:181], v[186:189], v[102:105]
	v_mfma_i32_16x16x64_i8 v[94:97], v[170:173], v[194:197], v[94:97]
	v_mfma_i32_16x16x64_i8 v[86:89], v[178:181], v[194:197], v[86:89]
	v_mfma_i32_16x16x64_i8 v[78:81], v[170:173], v[202:205], v[78:81]
	v_mfma_i32_16x16x64_i8 v[74:77], v[178:181], v[202:205], v[74:77]
	v_mfma_i32_16x16x64_i8 v[70:73], v[170:173], v[210:213], v[70:73]
	v_mfma_i32_16x16x64_i8 v[66:69], v[178:181], v[210:213], v[66:69]
	s_setprio 0
	s_barrier
	s_add_i32 s76, s67, s85
	v_lshl_add_u64 v[214:215], s[74:75], 0, v[134:135]
	s_mov_b32 m0, s76
	ds_read_b128 v[182:185], v151 offset:16384
	ds_read_b128 v[186:189], v151 offset:17408
	ds_read_b128 v[190:193], v151 offset:18432
	ds_read_b128 v[194:197], v151 offset:19456
	ds_read_b128 v[198:201], v151 offset:20480
	ds_read_b128 v[202:205], v151 offset:21504
	ds_read_b128 v[206:209], v151 offset:22528
	ds_read_b128 v[210:213], v151 offset:23552
	global_load_lds_dwordx4 v[214:215], off
	s_add_i32 m0, s76, 0x2000
	v_lshl_add_u64 v[216:217], s[74:75], 0, v[130:131]
	s_add_u32 s74, s74, s6
	s_addc_u32 s75, s75, s7
	s_add_i32 s76, s68, s85
	global_load_lds_dwordx4 v[216:217], off
	v_lshl_add_u64 v[218:219], s[74:75], 0, v[134:135]
	s_mov_b32 m0, s76
	v_lshl_add_u64 v[220:221], s[74:75], 0, v[130:131]
	global_load_lds_dwordx4 v[218:219], off
	s_add_i32 m0, s76, 0x2000
	v_lshl_add_u64 v[222:223], s[38:39], 0, v[136:137]
	global_load_lds_dwordx4 v[220:221], off
	s_mov_b32 m0, s90
	v_lshl_add_u64 v[224:225], s[38:39], 0, v[132:133]
	global_load_lds_dwordx4 v[222:223], off
	s_mov_b32 m0, s91
	s_nop 0
	global_load_lds_dwordx4 v[224:225], off
	s_waitcnt vmcnt(8)
	s_waitcnt lgkmcnt(0)
	s_barrier
	s_setprio 1
	v_mfma_i32_16x16x64_i8 v[62:65], v[146:149], v[182:185], v[62:65]
	v_mfma_i32_16x16x64_i8 v[58:61], v[156:159], v[182:185], v[58:61]
	v_mfma_i32_16x16x64_i8 v[54:57], v[146:149], v[190:193], v[54:57]
	v_mfma_i32_16x16x64_i8 v[50:53], v[156:159], v[190:193], v[50:53]
	v_mfma_i32_16x16x64_i8 v[42:45], v[146:149], v[198:201], v[42:45]
	v_mfma_i32_16x16x64_i8 v[34:37], v[156:159], v[198:201], v[34:37]
	v_mfma_i32_16x16x64_i8 v[26:29], v[146:149], v[206:209], v[26:29]
	v_mfma_i32_16x16x64_i8 v[18:21], v[156:159], v[206:209], v[18:21]
	v_mfma_i32_16x16x64_i8 v[62:65], v[152:155], v[186:189], v[62:65]
	v_mfma_i32_16x16x64_i8 v[58:61], v[160:163], v[186:189], v[58:61]
	v_mfma_i32_16x16x64_i8 v[54:57], v[152:155], v[194:197], v[54:57]
	v_mfma_i32_16x16x64_i8 v[50:53], v[160:163], v[194:197], v[50:53]
	v_mfma_i32_16x16x64_i8 v[42:45], v[152:155], v[202:205], v[42:45]
	v_mfma_i32_16x16x64_i8 v[34:37], v[160:163], v[202:205], v[34:37]
	v_mfma_i32_16x16x64_i8 v[26:29], v[152:155], v[210:213], v[26:29]
	v_mfma_i32_16x16x64_i8 v[18:21], v[160:163], v[210:213], v[18:21]
	v_mfma_i32_16x16x64_i8 v[46:49], v[164:167], v[182:185], v[46:49]
	v_mfma_i32_16x16x64_i8 v[38:41], v[174:177], v[182:185], v[38:41]
	v_mfma_i32_16x16x64_i8 v[30:33], v[164:167], v[190:193], v[30:33]
	v_mfma_i32_16x16x64_i8 v[22:25], v[174:177], v[190:193], v[22:25]
	v_mfma_i32_16x16x64_i8 v[14:17], v[164:167], v[198:201], v[14:17]
	v_mfma_i32_16x16x64_i8 v[10:13], v[174:177], v[198:201], v[10:13]
	v_mfma_i32_16x16x64_i8 v[6:9], v[164:167], v[206:209], v[6:9]
	v_mfma_i32_16x16x64_i8 v[2:5], v[174:177], v[206:209], v[2:5]
	v_mfma_i32_16x16x64_i8 v[46:49], v[170:173], v[186:189], v[46:49]
	v_mfma_i32_16x16x64_i8 v[38:41], v[178:181], v[186:189], v[38:41]
	v_mfma_i32_16x16x64_i8 v[30:33], v[170:173], v[194:197], v[30:33]
	v_mfma_i32_16x16x64_i8 v[22:25], v[178:181], v[194:197], v[22:25]
	v_mfma_i32_16x16x64_i8 v[14:17], v[170:173], v[202:205], v[14:17]
	v_mfma_i32_16x16x64_i8 v[10:13], v[178:181], v[202:205], v[10:13]
	v_mfma_i32_16x16x64_i8 v[6:9], v[170:173], v[210:213], v[6:9]
	v_mfma_i32_16x16x64_i8 v[2:5], v[178:181], v[210:213], v[2:5]
	s_setprio 0
	s_barrier
	s_add_i32 s74, 0, 0x18000
	v_add_u32_e32 v150, s74, v1
	s_add_i32 s75, 0, 0x1c000
	ds_read_b128 v[146:149], v150
	ds_read_b128 v[152:155], v150 offset:1024
	ds_read_b128 v[156:159], v150 offset:2048
	ds_read_b128 v[160:163], v150 offset:3072
	v_add_u32_e32 v150, s75, v1
	ds_read_b128 v[164:167], v150
	ds_read_b128 v[170:173], v150 offset:1024
	ds_read_b128 v[174:177], v150 offset:2048
	ds_read_b128 v[178:181], v150 offset:3072
	s_add_u32 s38, s38, s6
	s_addc_u32 s39, s39, s7
	s_mov_b32 m0, s96
	v_lshl_add_u64 v[226:227], s[38:39], 0, v[136:137]
	ds_read_b128 v[182:185], v151 offset:32768
	ds_read_b128 v[186:189], v151 offset:33792
	ds_read_b128 v[190:193], v151 offset:34816
	ds_read_b128 v[194:197], v151 offset:35840
	ds_read_b128 v[198:201], v151 offset:36864
	ds_read_b128 v[202:205], v151 offset:37888
	ds_read_b128 v[206:209], v151 offset:38912
	ds_read_b128 v[210:213], v151 offset:39936
	global_load_lds_dwordx4 v[226:227], off
	v_lshl_add_u64 v[226:227], s[38:39], 0, v[132:133]
	s_mov_b32 m0, s52
	s_nop 0
	global_load_lds_dwordx4 v[226:227], off
	s_waitcnt vmcnt(8)
	s_waitcnt lgkmcnt(0)
	s_barrier
	s_setprio 1
	v_mfma_i32_16x16x64_i8 v[126:129], v[146:149], v[182:185], v[126:129]
	v_mfma_i32_16x16x64_i8 v[122:125], v[156:159], v[182:185], v[122:125]
	v_mfma_i32_16x16x64_i8 v[118:121], v[146:149], v[190:193], v[118:121]
	v_mfma_i32_16x16x64_i8 v[114:117], v[156:159], v[190:193], v[114:117]
	v_mfma_i32_16x16x64_i8 v[106:109], v[146:149], v[198:201], v[106:109]
	v_mfma_i32_16x16x64_i8 v[98:101], v[156:159], v[198:201], v[98:101]
	v_mfma_i32_16x16x64_i8 v[90:93], v[146:149], v[206:209], v[90:93]
	v_mfma_i32_16x16x64_i8 v[82:85], v[156:159], v[206:209], v[82:85]
	v_mfma_i32_16x16x64_i8 v[126:129], v[152:155], v[186:189], v[126:129]
	v_mfma_i32_16x16x64_i8 v[122:125], v[160:163], v[186:189], v[122:125]
	v_mfma_i32_16x16x64_i8 v[118:121], v[152:155], v[194:197], v[118:121]
	v_mfma_i32_16x16x64_i8 v[114:117], v[160:163], v[194:197], v[114:117]
	v_mfma_i32_16x16x64_i8 v[106:109], v[152:155], v[202:205], v[106:109]
	v_mfma_i32_16x16x64_i8 v[98:101], v[160:163], v[202:205], v[98:101]
	v_mfma_i32_16x16x64_i8 v[90:93], v[152:155], v[210:213], v[90:93]
	v_mfma_i32_16x16x64_i8 v[82:85], v[160:163], v[210:213], v[82:85]
	v_mfma_i32_16x16x64_i8 v[110:113], v[164:167], v[182:185], v[110:113]
	v_mfma_i32_16x16x64_i8 v[102:105], v[174:177], v[182:185], v[102:105]
	v_mfma_i32_16x16x64_i8 v[94:97], v[164:167], v[190:193], v[94:97]
	v_mfma_i32_16x16x64_i8 v[86:89], v[174:177], v[190:193], v[86:89]
	v_mfma_i32_16x16x64_i8 v[78:81], v[164:167], v[198:201], v[78:81]
	v_mfma_i32_16x16x64_i8 v[74:77], v[174:177], v[198:201], v[74:77]
	v_mfma_i32_16x16x64_i8 v[70:73], v[164:167], v[206:209], v[70:73]
	v_mfma_i32_16x16x64_i8 v[66:69], v[174:177], v[206:209], v[66:69]
	v_mfma_i32_16x16x64_i8 v[110:113], v[170:173], v[186:189], v[110:113]
	v_mfma_i32_16x16x64_i8 v[102:105], v[178:181], v[186:189], v[102:105]
	v_mfma_i32_16x16x64_i8 v[94:97], v[170:173], v[194:197], v[94:97]
	v_mfma_i32_16x16x64_i8 v[86:89], v[178:181], v[194:197], v[86:89]
	v_mfma_i32_16x16x64_i8 v[78:81], v[170:173], v[202:205], v[78:81]
	v_mfma_i32_16x16x64_i8 v[74:77], v[178:181], v[202:205], v[74:77]
	v_mfma_i32_16x16x64_i8 v[70:73], v[170:173], v[210:213], v[70:73]
	v_mfma_i32_16x16x64_i8 v[66:69], v[178:181], v[210:213], v[66:69]
	s_setprio 0
	s_barrier
	s_add_i32 s38, s74, s85
	v_lshl_add_u64 v[214:215], v[214:215], 0, s[16:17]
	s_mov_b32 m0, s38
	ds_read_b128 v[182:185], v151 offset:49152
	ds_read_b128 v[186:189], v151 offset:50176
	ds_read_b128 v[190:193], v151 offset:51200
	ds_read_b128 v[194:197], v151 offset:52224
	ds_read_b128 v[198:201], v151 offset:53248
	ds_read_b128 v[202:205], v151 offset:54272
	ds_read_b128 v[206:209], v151 offset:55296
	ds_read_b128 v[210:213], v151 offset:56320
	global_load_lds_dwordx4 v[214:215], off
	v_lshl_add_u64 v[214:215], v[216:217], 0, s[16:17]
	s_add_i32 m0, s38, 0x2000
	s_add_i32 s38, s75, s85
	global_load_lds_dwordx4 v[214:215], off
	v_lshl_add_u64 v[214:215], v[218:219], 0, s[16:17]
	s_mov_b32 m0, s38
	s_nop 0
	global_load_lds_dwordx4 v[214:215], off
	v_lshl_add_u64 v[214:215], v[220:221], 0, s[16:17]
	s_add_i32 m0, s38, 0x2000
	s_nop 0
	global_load_lds_dwordx4 v[214:215], off
	v_lshl_add_u64 v[214:215], v[222:223], 0, s[16:17]
	s_mov_b32 m0, s57
	s_nop 0
	global_load_lds_dwordx4 v[214:215], off
	v_lshl_add_u64 v[214:215], v[224:225], 0, s[16:17]
	s_mov_b32 m0, s58
	s_nop 0
	global_load_lds_dwordx4 v[214:215], off
	s_waitcnt vmcnt(8)
	s_waitcnt lgkmcnt(0)
	s_barrier
	s_setprio 1
	v_mfma_i32_16x16x64_i8 v[62:65], v[146:149], v[182:185], v[62:65]
	v_mfma_i32_16x16x64_i8 v[58:61], v[156:159], v[182:185], v[58:61]
	v_mfma_i32_16x16x64_i8 v[54:57], v[146:149], v[190:193], v[54:57]
	v_mfma_i32_16x16x64_i8 v[50:53], v[156:159], v[190:193], v[50:53]
	v_mfma_i32_16x16x64_i8 v[42:45], v[146:149], v[198:201], v[42:45]
	v_mfma_i32_16x16x64_i8 v[34:37], v[156:159], v[198:201], v[34:37]
	v_mfma_i32_16x16x64_i8 v[26:29], v[146:149], v[206:209], v[26:29]
	v_mfma_i32_16x16x64_i8 v[18:21], v[156:159], v[206:209], v[18:21]
	v_mfma_i32_16x16x64_i8 v[62:65], v[152:155], v[186:189], v[62:65]
	v_mfma_i32_16x16x64_i8 v[58:61], v[160:163], v[186:189], v[58:61]
	v_mfma_i32_16x16x64_i8 v[54:57], v[152:155], v[194:197], v[54:57]
	v_mfma_i32_16x16x64_i8 v[50:53], v[160:163], v[194:197], v[50:53]
	v_mfma_i32_16x16x64_i8 v[42:45], v[152:155], v[202:205], v[42:45]
	v_mfma_i32_16x16x64_i8 v[34:37], v[160:163], v[202:205], v[34:37]
	v_mfma_i32_16x16x64_i8 v[26:29], v[152:155], v[210:213], v[26:29]
	v_mfma_i32_16x16x64_i8 v[18:21], v[160:163], v[210:213], v[18:21]
	v_mfma_i32_16x16x64_i8 v[46:49], v[164:167], v[182:185], v[46:49]
	v_mfma_i32_16x16x64_i8 v[38:41], v[174:177], v[182:185], v[38:41]
	v_mfma_i32_16x16x64_i8 v[30:33], v[164:167], v[190:193], v[30:33]
	v_mfma_i32_16x16x64_i8 v[22:25], v[174:177], v[190:193], v[22:25]
	v_mfma_i32_16x16x64_i8 v[14:17], v[164:167], v[198:201], v[14:17]
	v_mfma_i32_16x16x64_i8 v[10:13], v[174:177], v[198:201], v[10:13]
	v_mfma_i32_16x16x64_i8 v[6:9], v[164:167], v[206:209], v[6:9]
	v_mfma_i32_16x16x64_i8 v[2:5], v[174:177], v[206:209], v[2:5]
	v_mfma_i32_16x16x64_i8 v[46:49], v[170:173], v[186:189], v[46:49]
	v_mfma_i32_16x16x64_i8 v[38:41], v[178:181], v[186:189], v[38:41]
	v_mfma_i32_16x16x64_i8 v[30:33], v[170:173], v[194:197], v[30:33]
	v_mfma_i32_16x16x64_i8 v[22:25], v[178:181], v[194:197], v[22:25]
	v_mfma_i32_16x16x64_i8 v[14:17], v[170:173], v[202:205], v[14:17]
	v_mfma_i32_16x16x64_i8 v[10:13], v[178:181], v[202:205], v[10:13]
	v_mfma_i32_16x16x64_i8 v[6:9], v[170:173], v[210:213], v[6:9]
	v_mfma_i32_16x16x64_i8 v[2:5], v[178:181], v[210:213], v[2:5]
	s_setprio 0
	s_barrier
	s_add_u32 s36, s36, 0x100
	s_addc_u32 s37, s37, 0
	s_add_u32 s71, s71, 0x100
	s_addc_u32 s72, s72, 0
	s_cmp_ge_i32 s73, s59
	s_mov_b32 s38, s73
	s_cbranch_scc0 .LBB0_1896
	v_cvt_f32_i32_e32 v154, v126
	v_cvt_f32_i32_e32 v155, v127
	v_cvt_f32_i32_e32 v152, v128
	v_cvt_f32_i32_e32 v153, v129
	v_cvt_f32_i32_e32 v158, v122
	v_cvt_f32_i32_e32 v159, v123
	v_cvt_f32_i32_e32 v156, v124
	v_cvt_f32_i32_e32 v157, v125
	v_cvt_f32_i32_e32 v128, v110
	v_cvt_f32_i32_e32 v129, v111
	v_cvt_f32_i32_e32 v126, v112
	v_cvt_f32_i32_e32 v127, v113
	v_cvt_f32_i32_e32 v148, v102
	v_cvt_f32_i32_e32 v149, v103
	v_cvt_f32_i32_e32 v146, v104
	v_cvt_f32_i32_e32 v147, v105
	v_cvt_f32_i32_e32 v122, v118
	v_cvt_f32_i32_e32 v123, v119
	v_cvt_f32_i32_e32 v118, v120
	v_cvt_f32_i32_e32 v119, v121
	v_cvt_f32_i32_e32 v124, v114
	v_cvt_f32_i32_e32 v125, v115
	v_cvt_f32_i32_e32 v120, v116
	v_cvt_f32_i32_e32 v121, v117
	v_cvt_f32_i32_e32 v112, v94
	v_cvt_f32_i32_e32 v113, v95
	v_cvt_f32_i32_e32 v110, v96
	v_cvt_f32_i32_e32 v111, v97
	v_cvt_f32_i32_e32 v116, v86
	v_cvt_f32_i32_e32 v117, v87
	v_cvt_f32_i32_e32 v114, v88
	v_cvt_f32_i32_e32 v115, v89
	v_cvt_f32_i32_e32 v104, v106
	v_cvt_f32_i32_e32 v105, v107
	v_cvt_f32_i32_e32 v102, v108
	v_cvt_f32_i32_e32 v103, v109
	v_cvt_f32_i32_e32 v108, v98
	v_cvt_f32_i32_e32 v109, v99
	v_cvt_f32_i32_e32 v106, v100
	v_cvt_f32_i32_e32 v107, v101
	v_cvt_f32_i32_e32 v96, v78
	v_cvt_f32_i32_e32 v97, v79
	v_cvt_f32_i32_e32 v94, v80
	v_cvt_f32_i32_e32 v95, v81
	v_cvt_f32_i32_e32 v100, v74
	v_cvt_f32_i32_e32 v101, v75
	v_cvt_f32_i32_e32 v98, v76
	v_cvt_f32_i32_e32 v99, v77
	v_cvt_f32_i32_e32 v88, v90
	v_cvt_f32_i32_e32 v89, v91
	v_cvt_f32_i32_e32 v86, v92
	v_cvt_f32_i32_e32 v87, v93
	v_cvt_f32_i32_e32 v92, v82
	v_cvt_f32_i32_e32 v93, v83
	v_cvt_f32_i32_e32 v90, v84
	v_cvt_f32_i32_e32 v91, v85
	v_cvt_f32_i32_e32 v80, v70
	v_cvt_f32_i32_e32 v81, v71
	v_cvt_f32_i32_e32 v78, v72
	v_cvt_f32_i32_e32 v79, v73
	v_cvt_f32_i32_e32 v84, v66
	v_cvt_f32_i32_e32 v85, v67
	v_cvt_f32_i32_e32 v82, v68
	v_cvt_f32_i32_e32 v83, v69
	v_cvt_f32_i32_e32 v72, v62
	v_cvt_f32_i32_e32 v73, v63
	v_cvt_f32_i32_e32 v70, v64
	v_cvt_f32_i32_e32 v71, v65
	v_cvt_f32_i32_e32 v76, v58
	v_cvt_f32_i32_e32 v77, v59
	v_cvt_f32_i32_e32 v74, v60
	v_cvt_f32_i32_e32 v75, v61
	v_cvt_f32_i32_e32 v64, v46
	v_cvt_f32_i32_e32 v65, v47
	v_cvt_f32_i32_e32 v62, v48
	v_cvt_f32_i32_e32 v63, v49
	v_cvt_f32_i32_e32 v68, v38
	v_cvt_f32_i32_e32 v69, v39
	v_cvt_f32_i32_e32 v66, v40
	v_cvt_f32_i32_e32 v67, v41
	v_cvt_f32_i32_e32 v58, v54
	v_cvt_f32_i32_e32 v59, v55
	v_cvt_f32_i32_e32 v54, v56
	v_cvt_f32_i32_e32 v55, v57
	v_cvt_f32_i32_e32 v60, v50
	v_cvt_f32_i32_e32 v61, v51
	v_cvt_f32_i32_e32 v56, v52
	v_cvt_f32_i32_e32 v57, v53
	v_cvt_f32_i32_e32 v48, v30
	v_cvt_f32_i32_e32 v49, v31
	v_cvt_f32_i32_e32 v46, v32
	v_cvt_f32_i32_e32 v47, v33
	v_cvt_f32_i32_e32 v52, v22
	v_cvt_f32_i32_e32 v53, v23
	v_cvt_f32_i32_e32 v50, v24
	v_cvt_f32_i32_e32 v51, v25
	v_cvt_f32_i32_e32 v40, v42
	v_cvt_f32_i32_e32 v41, v43
	v_cvt_f32_i32_e32 v38, v44
	v_cvt_f32_i32_e32 v39, v45
	v_cvt_f32_i32_e32 v42, v34
	v_cvt_f32_i32_e32 v43, v35
	v_cvt_f32_i32_e32 v34, v36
	v_cvt_f32_i32_e32 v35, v37
	v_cvt_f32_i32_e32 v24, v14
	v_cvt_f32_i32_e32 v25, v15
	v_cvt_f32_i32_e32 v22, v16
	v_cvt_f32_i32_e32 v23, v17
	v_cvt_f32_i32_e32 v32, v10
	v_cvt_f32_i32_e32 v33, v11
	v_cvt_f32_i32_e32 v30, v12
	v_cvt_f32_i32_e32 v31, v13
	v_cvt_f32_i32_e32 v14, v26
	v_cvt_f32_i32_e32 v15, v27
	v_cvt_f32_i32_e32 v12, v28
	v_cvt_f32_i32_e32 v13, v29
	v_cvt_f32_i32_e32 v18, v18
	v_cvt_f32_i32_e32 v19, v19
	v_cvt_f32_i32_e32 v16, v20
	v_cvt_f32_i32_e32 v17, v21
	v_cvt_f32_i32_e32 v10, v6
	v_cvt_f32_i32_e32 v11, v7
	v_cvt_f32_i32_e32 v6, v8
	v_cvt_f32_i32_e32 v7, v9
	v_cvt_f32_i32_e32 v8, v2
	v_cvt_f32_i32_e32 v9, v3
	v_cvt_f32_i32_e32 v2, v4
	v_cvt_f32_i32_e32 v3, v5

.LBB0_2025:
	v_add_u32_e32 v138, s56, v1
	ds_read_b128 v[148:151], v138
	ds_read_b128 v[156:159], v138 offset:1024
	ds_read_b128 v[160:163], v138 offset:2048
	ds_read_b128 v[164:167], v138 offset:3072
	v_add_u32_e32 v138, s57, v1
	ds_read_b128 v[168:171], v138
	ds_read_b128 v[172:175], v138 offset:1024
	ds_read_b128 v[176:179], v138 offset:2048
	ds_read_b128 v[180:183], v138 offset:3072
	s_add_i32 s65, s30, 2
	s_add_u32 s66, s28, 0x80
	s_addc_u32 s31, s29, 0
	s_cmp_eq_u32 s54, s30
	s_cselect_b32 s30, s2, s66
	s_cselect_b32 s31, s3, s31
	s_cselect_b32 s67, s27, s64
	s_cselect_b32 s66, s26, s63
	v_lshl_add_u64 v[152:153], s[28:29], 0, v[140:141]
	s_add_i32 m0, s41, 0xc000
	ds_read_b128 v[184:187], v155
	ds_read_b128 v[188:191], v155 offset:1024
	ds_read_b128 v[192:195], v155 offset:2048
	ds_read_b128 v[196:199], v155 offset:3072
	ds_read_b128 v[200:203], v155 offset:4096
	ds_read_b128 v[204:207], v155 offset:5120
	ds_read_b128 v[208:211], v155 offset:6144
	ds_read_b128 v[212:215], v155 offset:7168
	global_load_lds_dwordx4 v[152:153], off
	v_lshl_add_u64 v[152:153], s[28:29], 0, v[142:143]
	s_add_i32 m0, s41, 0xe000
	s_nop 0
	global_load_lds_dwordx4 v[152:153], off
	s_waitcnt vmcnt(8)
	s_waitcnt lgkmcnt(0)
	s_barrier
	s_setprio 1
	v_mfma_i32_16x16x64_i8 v[126:129], v[148:151], v[184:187], v[126:129]
	v_mfma_i32_16x16x64_i8 v[122:125], v[160:163], v[184:187], v[122:125]
	v_mfma_i32_16x16x64_i8 v[118:121], v[148:151], v[192:195], v[118:121]
	v_mfma_i32_16x16x64_i8 v[114:117], v[160:163], v[192:195], v[114:117]
	v_mfma_i32_16x16x64_i8 v[106:109], v[148:151], v[200:203], v[106:109]
	v_mfma_i32_16x16x64_i8 v[98:101], v[160:163], v[200:203], v[98:101]
	v_mfma_i32_16x16x64_i8 v[90:93], v[148:151], v[208:211], v[90:93]
	v_mfma_i32_16x16x64_i8 v[82:85], v[160:163], v[208:211], v[82:85]
	v_mfma_i32_16x16x64_i8 v[126:129], v[156:159], v[188:191], v[126:129]
	v_mfma_i32_16x16x64_i8 v[122:125], v[164:167], v[188:191], v[122:125]
	v_mfma_i32_16x16x64_i8 v[118:121], v[156:159], v[196:199], v[118:121]
	v_mfma_i32_16x16x64_i8 v[114:117], v[164:167], v[196:199], v[114:117]
	v_mfma_i32_16x16x64_i8 v[106:109], v[156:159], v[204:207], v[106:109]
	v_mfma_i32_16x16x64_i8 v[98:101], v[164:167], v[204:207], v[98:101]
	v_mfma_i32_16x16x64_i8 v[90:93], v[156:159], v[212:215], v[90:93]
	v_mfma_i32_16x16x64_i8 v[82:85], v[164:167], v[212:215], v[82:85]
	v_mfma_i32_16x16x64_i8 v[110:113], v[168:171], v[184:187], v[110:113]
	v_mfma_i32_16x16x64_i8 v[102:105], v[176:179], v[184:187], v[102:105]
	v_mfma_i32_16x16x64_i8 v[94:97], v[168:171], v[192:195], v[94:97]
	v_mfma_i32_16x16x64_i8 v[86:89], v[176:179], v[192:195], v[86:89]
	v_mfma_i32_16x16x64_i8 v[78:81], v[168:171], v[200:203], v[78:81]
	v_mfma_i32_16x16x64_i8 v[74:77], v[176:179], v[200:203], v[74:77]
	v_mfma_i32_16x16x64_i8 v[70:73], v[168:171], v[208:211], v[70:73]
	v_mfma_i32_16x16x64_i8 v[66:69], v[176:179], v[208:211], v[66:69]
	v_mfma_i32_16x16x64_i8 v[110:113], v[172:175], v[188:191], v[110:113]
	v_mfma_i32_16x16x64_i8 v[102:105], v[180:183], v[188:191], v[102:105]
	v_mfma_i32_16x16x64_i8 v[94:97], v[172:175], v[196:199], v[94:97]
	v_mfma_i32_16x16x64_i8 v[86:89], v[180:183], v[196:199], v[86:89]
	v_mfma_i32_16x16x64_i8 v[78:81], v[172:175], v[204:207], v[78:81]
	v_mfma_i32_16x16x64_i8 v[74:77], v[180:183], v[204:207], v[74:77]
	v_mfma_i32_16x16x64_i8 v[70:73], v[172:175], v[212:215], v[70:73]
	v_mfma_i32_16x16x64_i8 v[66:69], v[180:183], v[212:215], v[66:69]
	s_setprio 0
	s_barrier
	s_add_i32 s68, s56, s38
	v_lshl_add_u64 v[152:153], s[66:67], 0, v[134:135]
	s_mov_b32 m0, s68
	ds_read_b128 v[184:187], v155 offset:16384
	ds_read_b128 v[188:191], v155 offset:17408
	ds_read_b128 v[192:195], v155 offset:18432
	ds_read_b128 v[196:199], v155 offset:19456
	ds_read_b128 v[200:203], v155 offset:20480
	ds_read_b128 v[204:207], v155 offset:21504
	ds_read_b128 v[208:211], v155 offset:22528
	ds_read_b128 v[212:215], v155 offset:23552
	global_load_lds_dwordx4 v[152:153], off
	s_add_i32 m0, s68, 0x2000
	v_lshl_add_u64 v[216:217], s[66:67], 0, v[130:131]
	s_add_u32 s66, s66, s6
	s_addc_u32 s67, s67, s7
	s_add_i32 s68, s57, s38
	global_load_lds_dwordx4 v[216:217], off
	v_lshl_add_u64 v[218:219], s[66:67], 0, v[134:135]
	s_mov_b32 m0, s68
	v_lshl_add_u64 v[220:221], s[66:67], 0, v[130:131]
	global_load_lds_dwordx4 v[218:219], off
	s_add_i32 m0, s68, 0x2000
	v_lshl_add_u64 v[222:223], s[30:31], 0, v[136:137]
	global_load_lds_dwordx4 v[220:221], off
	s_mov_b32 m0, s41
	v_lshl_add_u64 v[224:225], s[30:31], 0, v[132:133]
	global_load_lds_dwordx4 v[222:223], off
	s_mov_b32 m0, s42
	s_nop 0
	global_load_lds_dwordx4 v[224:225], off
	s_waitcnt vmcnt(8)
	s_waitcnt lgkmcnt(0)
	s_barrier
	s_setprio 1
	v_mfma_i32_16x16x64_i8 v[62:65], v[148:151], v[184:187], v[62:65]
	v_mfma_i32_16x16x64_i8 v[58:61], v[160:163], v[184:187], v[58:61]
	v_mfma_i32_16x16x64_i8 v[54:57], v[148:151], v[192:195], v[54:57]
	v_mfma_i32_16x16x64_i8 v[50:53], v[160:163], v[192:195], v[50:53]
	v_mfma_i32_16x16x64_i8 v[42:45], v[148:151], v[200:203], v[42:45]
	v_mfma_i32_16x16x64_i8 v[34:37], v[160:163], v[200:203], v[34:37]
	v_mfma_i32_16x16x64_i8 v[26:29], v[148:151], v[208:211], v[26:29]
	v_mfma_i32_16x16x64_i8 v[18:21], v[160:163], v[208:211], v[18:21]
	v_mfma_i32_16x16x64_i8 v[62:65], v[156:159], v[188:191], v[62:65]
	v_mfma_i32_16x16x64_i8 v[58:61], v[164:167], v[188:191], v[58:61]
	v_mfma_i32_16x16x64_i8 v[54:57], v[156:159], v[196:199], v[54:57]
	v_mfma_i32_16x16x64_i8 v[50:53], v[164:167], v[196:199], v[50:53]
	v_mfma_i32_16x16x64_i8 v[42:45], v[156:159], v[204:207], v[42:45]
	v_mfma_i32_16x16x64_i8 v[34:37], v[164:167], v[204:207], v[34:37]
	v_mfma_i32_16x16x64_i8 v[26:29], v[156:159], v[212:215], v[26:29]
	v_mfma_i32_16x16x64_i8 v[18:21], v[164:167], v[212:215], v[18:21]
	v_mfma_i32_16x16x64_i8 v[46:49], v[168:171], v[184:187], v[46:49]
	v_mfma_i32_16x16x64_i8 v[38:41], v[176:179], v[184:187], v[38:41]
	v_mfma_i32_16x16x64_i8 v[30:33], v[168:171], v[192:195], v[30:33]
	v_mfma_i32_16x16x64_i8 v[22:25], v[176:179], v[192:195], v[22:25]
	v_mfma_i32_16x16x64_i8 v[14:17], v[168:171], v[200:203], v[14:17]
	v_mfma_i32_16x16x64_i8 v[10:13], v[176:179], v[200:203], v[10:13]
	v_mfma_i32_16x16x64_i8 v[6:9], v[168:171], v[208:211], v[6:9]
	v_mfma_i32_16x16x64_i8 v[2:5], v[176:179], v[208:211], v[2:5]
	v_mfma_i32_16x16x64_i8 v[46:49], v[172:175], v[188:191], v[46:49]
	v_mfma_i32_16x16x64_i8 v[38:41], v[180:183], v[188:191], v[38:41]
	v_mfma_i32_16x16x64_i8 v[30:33], v[172:175], v[196:199], v[30:33]
	v_mfma_i32_16x16x64_i8 v[22:25], v[180:183], v[196:199], v[22:25]
	v_mfma_i32_16x16x64_i8 v[14:17], v[172:175], v[204:207], v[14:17]
	v_mfma_i32_16x16x64_i8 v[10:13], v[180:183], v[204:207], v[10:13]
	v_mfma_i32_16x16x64_i8 v[6:9], v[172:175], v[212:215], v[6:9]
	v_mfma_i32_16x16x64_i8 v[2:5], v[180:183], v[212:215], v[2:5]
	s_setprio 0
	s_barrier
	s_add_i32 s66, 0, 0x18000
	v_add_u32_e32 v138, s66, v1
	s_add_i32 s67, 0, 0x1c000
	ds_read_b128 v[148:151], v138
	ds_read_b128 v[156:159], v138 offset:1024
	ds_read_b128 v[160:163], v138 offset:2048
	ds_read_b128 v[164:167], v138 offset:3072
	v_add_u32_e32 v138, s67, v1
	ds_read_b128 v[168:171], v138
	ds_read_b128 v[172:175], v138 offset:1024
	ds_read_b128 v[176:179], v138 offset:2048
	ds_read_b128 v[180:183], v138 offset:3072
	s_add_u32 s30, s30, s6
	s_addc_u32 s31, s31, s7
	s_mov_b32 m0, s43
	v_lshl_add_u64 v[226:227], s[30:31], 0, v[136:137]
	ds_read_b128 v[184:187], v155 offset:32768
	ds_read_b128 v[188:191], v155 offset:33792
	ds_read_b128 v[192:195], v155 offset:34816
	ds_read_b128 v[196:199], v155 offset:35840
	ds_read_b128 v[200:203], v155 offset:36864
	ds_read_b128 v[204:207], v155 offset:37888
	ds_read_b128 v[208:211], v155 offset:38912
	ds_read_b128 v[212:215], v155 offset:39936
	global_load_lds_dwordx4 v[226:227], off
	v_lshl_add_u64 v[226:227], s[30:31], 0, v[132:133]
	s_mov_b32 m0, s44
	s_nop 0
	global_load_lds_dwordx4 v[226:227], off
	s_waitcnt vmcnt(8)
	s_waitcnt lgkmcnt(0)
	s_barrier
	s_setprio 1
	v_mfma_i32_16x16x64_i8 v[126:129], v[148:151], v[184:187], v[126:129]
	v_mfma_i32_16x16x64_i8 v[122:125], v[160:163], v[184:187], v[122:125]
	v_mfma_i32_16x16x64_i8 v[118:121], v[148:151], v[192:195], v[118:121]
	v_mfma_i32_16x16x64_i8 v[114:117], v[160:163], v[192:195], v[114:117]
	v_mfma_i32_16x16x64_i8 v[106:109], v[148:151], v[200:203], v[106:109]
	v_mfma_i32_16x16x64_i8 v[98:101], v[160:163], v[200:203], v[98:101]
	v_mfma_i32_16x16x64_i8 v[90:93], v[148:151], v[208:211], v[90:93]
	v_mfma_i32_16x16x64_i8 v[82:85], v[160:163], v[208:211], v[82:85]
	v_mfma_i32_16x16x64_i8 v[126:129], v[156:159], v[188:191], v[126:129]
	v_mfma_i32_16x16x64_i8 v[122:125], v[164:167], v[188:191], v[122:125]
	v_mfma_i32_16x16x64_i8 v[118:121], v[156:159], v[196:199], v[118:121]
	v_mfma_i32_16x16x64_i8 v[114:117], v[164:167], v[196:199], v[114:117]
	v_mfma_i32_16x16x64_i8 v[106:109], v[156:159], v[204:207], v[106:109]
	v_mfma_i32_16x16x64_i8 v[98:101], v[164:167], v[204:207], v[98:101]
	v_mfma_i32_16x16x64_i8 v[90:93], v[156:159], v[212:215], v[90:93]
	v_mfma_i32_16x16x64_i8 v[82:85], v[164:167], v[212:215], v[82:85]
	v_mfma_i32_16x16x64_i8 v[110:113], v[168:171], v[184:187], v[110:113]
	v_mfma_i32_16x16x64_i8 v[102:105], v[176:179], v[184:187], v[102:105]
	v_mfma_i32_16x16x64_i8 v[94:97], v[168:171], v[192:195], v[94:97]
	v_mfma_i32_16x16x64_i8 v[86:89], v[176:179], v[192:195], v[86:89]
	v_mfma_i32_16x16x64_i8 v[78:81], v[168:171], v[200:203], v[78:81]
	v_mfma_i32_16x16x64_i8 v[74:77], v[176:179], v[200:203], v[74:77]
	v_mfma_i32_16x16x64_i8 v[70:73], v[168:171], v[208:211], v[70:73]
	v_mfma_i32_16x16x64_i8 v[66:69], v[176:179], v[208:211], v[66:69]
	v_mfma_i32_16x16x64_i8 v[110:113], v[172:175], v[188:191], v[110:113]
	v_mfma_i32_16x16x64_i8 v[102:105], v[180:183], v[188:191], v[102:105]
	v_mfma_i32_16x16x64_i8 v[94:97], v[172:175], v[196:199], v[94:97]
	v_mfma_i32_16x16x64_i8 v[86:89], v[180:183], v[196:199], v[86:89]
	v_mfma_i32_16x16x64_i8 v[78:81], v[172:175], v[204:207], v[78:81]
	v_mfma_i32_16x16x64_i8 v[74:77], v[180:183], v[204:207], v[74:77]
	v_mfma_i32_16x16x64_i8 v[70:73], v[172:175], v[212:215], v[70:73]
	v_mfma_i32_16x16x64_i8 v[66:69], v[180:183], v[212:215], v[66:69]
	s_setprio 0
	s_barrier
	s_add_i32 s30, s66, s38
	v_lshl_add_u64 v[152:153], v[152:153], 0, s[16:17]
	s_mov_b32 m0, s30
	ds_read_b128 v[184:187], v155 offset:49152
	ds_read_b128 v[188:191], v155 offset:50176
	ds_read_b128 v[192:195], v155 offset:51200
	ds_read_b128 v[196:199], v155 offset:52224
	ds_read_b128 v[200:203], v155 offset:53248
	ds_read_b128 v[204:207], v155 offset:54272
	ds_read_b128 v[208:211], v155 offset:55296
	ds_read_b128 v[212:215], v155 offset:56320
	global_load_lds_dwordx4 v[152:153], off
	v_lshl_add_u64 v[152:153], v[216:217], 0, s[16:17]
	s_add_i32 m0, s30, 0x2000
	s_add_i32 s30, s67, s38
	global_load_lds_dwordx4 v[152:153], off
	v_lshl_add_u64 v[152:153], v[218:219], 0, s[16:17]
	s_mov_b32 m0, s30
	s_nop 0
	global_load_lds_dwordx4 v[152:153], off
	v_lshl_add_u64 v[152:153], v[220:221], 0, s[16:17]
	s_add_i32 m0, s30, 0x2000
	s_nop 0
	global_load_lds_dwordx4 v[152:153], off
	v_lshl_add_u64 v[152:153], v[222:223], 0, s[16:17]
	s_mov_b32 m0, s47
	s_nop 0
	global_load_lds_dwordx4 v[152:153], off
	v_lshl_add_u64 v[152:153], v[224:225], 0, s[16:17]
	s_mov_b32 m0, s48
	s_nop 0
	global_load_lds_dwordx4 v[152:153], off
	s_waitcnt vmcnt(8)
	s_waitcnt lgkmcnt(0)
	s_barrier
	s_setprio 1
	v_mfma_i32_16x16x64_i8 v[62:65], v[148:151], v[184:187], v[62:65]
	v_mfma_i32_16x16x64_i8 v[58:61], v[160:163], v[184:187], v[58:61]
	v_mfma_i32_16x16x64_i8 v[54:57], v[148:151], v[192:195], v[54:57]
	v_mfma_i32_16x16x64_i8 v[50:53], v[160:163], v[192:195], v[50:53]
	v_mfma_i32_16x16x64_i8 v[42:45], v[148:151], v[200:203], v[42:45]
	v_mfma_i32_16x16x64_i8 v[34:37], v[160:163], v[200:203], v[34:37]
	v_mfma_i32_16x16x64_i8 v[26:29], v[148:151], v[208:211], v[26:29]
	v_mfma_i32_16x16x64_i8 v[18:21], v[160:163], v[208:211], v[18:21]
	v_mfma_i32_16x16x64_i8 v[62:65], v[156:159], v[188:191], v[62:65]
	v_mfma_i32_16x16x64_i8 v[58:61], v[164:167], v[188:191], v[58:61]
	v_mfma_i32_16x16x64_i8 v[54:57], v[156:159], v[196:199], v[54:57]
	v_mfma_i32_16x16x64_i8 v[50:53], v[164:167], v[196:199], v[50:53]
	v_mfma_i32_16x16x64_i8 v[42:45], v[156:159], v[204:207], v[42:45]
	v_mfma_i32_16x16x64_i8 v[34:37], v[164:167], v[204:207], v[34:37]
	v_mfma_i32_16x16x64_i8 v[26:29], v[156:159], v[212:215], v[26:29]
	v_mfma_i32_16x16x64_i8 v[18:21], v[164:167], v[212:215], v[18:21]
	v_mfma_i32_16x16x64_i8 v[46:49], v[168:171], v[184:187], v[46:49]
	v_mfma_i32_16x16x64_i8 v[38:41], v[176:179], v[184:187], v[38:41]
	v_mfma_i32_16x16x64_i8 v[30:33], v[168:171], v[192:195], v[30:33]
	v_mfma_i32_16x16x64_i8 v[22:25], v[176:179], v[192:195], v[22:25]
	v_mfma_i32_16x16x64_i8 v[14:17], v[168:171], v[200:203], v[14:17]
	v_mfma_i32_16x16x64_i8 v[10:13], v[176:179], v[200:203], v[10:13]
	v_mfma_i32_16x16x64_i8 v[6:9], v[168:171], v[208:211], v[6:9]
	v_mfma_i32_16x16x64_i8 v[2:5], v[176:179], v[208:211], v[2:5]
	v_mfma_i32_16x16x64_i8 v[46:49], v[172:175], v[188:191], v[46:49]
	v_mfma_i32_16x16x64_i8 v[38:41], v[180:183], v[188:191], v[38:41]
	v_mfma_i32_16x16x64_i8 v[30:33], v[172:175], v[196:199], v[30:33]
	v_mfma_i32_16x16x64_i8 v[22:25], v[180:183], v[196:199], v[22:25]
	v_mfma_i32_16x16x64_i8 v[14:17], v[172:175], v[204:207], v[14:17]
	v_mfma_i32_16x16x64_i8 v[10:13], v[180:183], v[204:207], v[10:13]
	v_mfma_i32_16x16x64_i8 v[6:9], v[172:175], v[212:215], v[6:9]
	v_mfma_i32_16x16x64_i8 v[2:5], v[180:183], v[212:215], v[2:5]
	s_setprio 0
	s_barrier
	s_add_u32 s28, s28, 0x100
	s_addc_u32 s29, s29, 0
	s_add_u32 s63, s63, 0x100
	s_addc_u32 s64, s64, 0
	s_cmp_ge_i32 s65, s49
	s_mov_b32 s30, s65
	s_cbranch_scc0 .LBB0_2025
	v_cvt_f32_i32_e32 v158, v126
	v_cvt_f32_i32_e32 v159, v127
	v_cvt_f32_i32_e32 v160, v128
	v_cvt_f32_i32_e32 v161, v129
	v_cvt_f32_i32_e32 v156, v122
	v_cvt_f32_i32_e32 v157, v123
	v_cvt_f32_i32_e32 v162, v124
	v_cvt_f32_i32_e32 v163, v125
	v_cvt_f32_i32_e32 v166, v110
	v_cvt_f32_i32_e32 v167, v111
	v_cvt_f32_i32_e32 v170, v112
	v_cvt_f32_i32_e32 v171, v113
	v_cvt_f32_i32_e32 v164, v102
	v_cvt_f32_i32_e32 v165, v103
	v_cvt_f32_i32_e32 v168, v104
	v_cvt_f32_i32_e32 v169, v105
	v_cvt_f32_i32_e32 v122, v118
	v_cvt_f32_i32_e32 v123, v119
	v_cvt_f32_i32_e32 v126, v120
	v_cvt_f32_i32_e32 v127, v121
	v_cvt_f32_i32_e32 v120, v114
	v_cvt_f32_i32_e32 v121, v115
	v_cvt_f32_i32_e32 v124, v116
	v_cvt_f32_i32_e32 v125, v117
	v_cvt_f32_i32_e32 v148, v94
	v_cvt_f32_i32_e32 v149, v95
	v_cvt_f32_i32_e32 v152, v96
	v_cvt_f32_i32_e32 v153, v97
	v_cvt_f32_i32_e32 v128, v86
	v_cvt_f32_i32_e32 v129, v87
	v_cvt_f32_i32_e32 v150, v88
	v_cvt_f32_i32_e32 v151, v89
	v_cvt_f32_i32_e32 v96, v106
	v_cvt_f32_i32_e32 v97, v107
	v_cvt_f32_i32_e32 v102, v108
	v_cvt_f32_i32_e32 v103, v109
	v_cvt_f32_i32_e32 v94, v98
	v_cvt_f32_i32_e32 v95, v99
	v_cvt_f32_i32_e32 v98, v100
	v_cvt_f32_i32_e32 v99, v101
	v_cvt_f32_i32_e32 v110, v78
	v_cvt_f32_i32_e32 v111, v79
	v_cvt_f32_i32_e32 v114, v80
	v_cvt_f32_i32_e32 v115, v81
	v_cvt_f32_i32_e32 v108, v74
	v_cvt_f32_i32_e32 v109, v75
	v_cvt_f32_i32_e32 v112, v76
	v_cvt_f32_i32_e32 v113, v77
	v_cvt_f32_i32_e32 v80, v90
	v_cvt_f32_i32_e32 v81, v91
	v_cvt_f32_i32_e32 v86, v92
	v_cvt_f32_i32_e32 v87, v93
	v_cvt_f32_i32_e32 v78, v82
	v_cvt_f32_i32_e32 v79, v83
	v_cvt_f32_i32_e32 v82, v84
	v_cvt_f32_i32_e32 v83, v85
	v_cvt_f32_i32_e32 v88, v70
	v_cvt_f32_i32_e32 v89, v71
	v_cvt_f32_i32_e32 v92, v72
	v_cvt_f32_i32_e32 v93, v73
	v_cvt_f32_i32_e32 v84, v66
	v_cvt_f32_i32_e32 v85, v67
	v_cvt_f32_i32_e32 v90, v68
	v_cvt_f32_i32_e32 v91, v69
	v_cvt_f32_i32_e32 v66, v62
	v_cvt_f32_i32_e32 v67, v63
	v_cvt_f32_i32_e32 v68, v64
	v_cvt_f32_i32_e32 v69, v65
	v_cvt_f32_i32_e32 v62, v58
	v_cvt_f32_i32_e32 v63, v59
	v_cvt_f32_i32_e32 v64, v60
	v_cvt_f32_i32_e32 v65, v61
	v_cvt_f32_i32_e32 v72, v46
	v_cvt_f32_i32_e32 v73, v47
	v_cvt_f32_i32_e32 v76, v48
	v_cvt_f32_i32_e32 v77, v49
	v_cvt_f32_i32_e32 v70, v38
	v_cvt_f32_i32_e32 v71, v39
	v_cvt_f32_i32_e32 v74, v40
	v_cvt_f32_i32_e32 v75, v41
	v_cvt_f32_i32_e32 v48, v54
	v_cvt_f32_i32_e32 v49, v55
	v_cvt_f32_i32_e32 v54, v56
	v_cvt_f32_i32_e32 v55, v57
	v_cvt_f32_i32_e32 v46, v50
	v_cvt_f32_i32_e32 v47, v51
	v_cvt_f32_i32_e32 v50, v52
	v_cvt_f32_i32_e32 v51, v53
	v_cvt_f32_i32_e32 v56, v30
	v_cvt_f32_i32_e32 v57, v31
	v_cvt_f32_i32_e32 v60, v32
	v_cvt_f32_i32_e32 v61, v33
	v_cvt_f32_i32_e32 v52, v22
	v_cvt_f32_i32_e32 v53, v23
	v_cvt_f32_i32_e32 v58, v24
	v_cvt_f32_i32_e32 v59, v25
	v_cvt_f32_i32_e32 v24, v42
	v_cvt_f32_i32_e32 v25, v43
	v_cvt_f32_i32_e32 v32, v44
	v_cvt_f32_i32_e32 v33, v45
	v_cvt_f32_i32_e32 v22, v34
	v_cvt_f32_i32_e32 v23, v35
	v_cvt_f32_i32_e32 v30, v36
	v_cvt_f32_i32_e32 v31, v37
	v_cvt_f32_i32_e32 v36, v14
	v_cvt_f32_i32_e32 v37, v15
	v_cvt_f32_i32_e32 v40, v16
	v_cvt_f32_i32_e32 v41, v17
	v_cvt_f32_i32_e32 v34, v10
	v_cvt_f32_i32_e32 v35, v11
	v_cvt_f32_i32_e32 v38, v12
	v_cvt_f32_i32_e32 v39, v13
	v_cvt_f32_i32_e32 v12, v26
	v_cvt_f32_i32_e32 v13, v27
	v_cvt_f32_i32_e32 v16, v28
	v_cvt_f32_i32_e32 v17, v29
	v_cvt_f32_i32_e32 v10, v18
	v_cvt_f32_i32_e32 v11, v19
	v_cvt_f32_i32_e32 v14, v20
	v_cvt_f32_i32_e32 v15, v21
	v_cvt_f32_i32_e32 v6, v6
	v_cvt_f32_i32_e32 v7, v7
	v_cvt_f32_i32_e32 v8, v8
	v_cvt_f32_i32_e32 v9, v9
	v_cvt_f32_i32_e32 v2, v2
	v_cvt_f32_i32_e32 v3, v3
	v_cvt_f32_i32_e32 v4, v4
	v_cvt_f32_i32_e32 v5, v5

.LBB0_2098:
	ds_read_b128 v[18:21], v190
	ds_read_b128 v[22:25], v190 offset:1024
	ds_read_b128 v[26:29], v190 offset:2048
	ds_read_b128 v[30:33], v190 offset:3072
	ds_read_b128 v[2:5], v191
	ds_read_b128 v[6:9], v191 offset:1024
	ds_read_b128 v[10:13], v191 offset:2048
	ds_read_b128 v[14:17], v191 offset:3072
	s_add_i32 s67, s34, 2
	s_add_u32 s36, s30, 0x80
	s_addc_u32 s35, s31, 0
	s_cmp_eq_u32 s57, s34
	s_cselect_b32 s34, s2, s36
	s_cselect_b32 s35, s3, s35
	s_cselect_b32 s37, s29, s66
	s_cselect_b32 s36, s28, s65
	v_lshl_add_u64 v[186:187], s[30:31], 0, v[170:171]
	s_add_i32 m0, s45, 0xc000
	ds_read_b128 v[178:181], v192
	ds_read_b128 v[182:185], v192 offset:1024
	ds_read_b128 v[194:197], v192 offset:2048
	ds_read_b128 v[198:201], v192 offset:3072
	ds_read_b128 v[202:205], v192 offset:4096
	ds_read_b128 v[206:209], v192 offset:5120
	ds_read_b128 v[210:213], v192 offset:6144
	ds_read_b128 v[214:217], v192 offset:7168
	global_load_lds_dwordx4 v[186:187], off
	v_lshl_add_u64 v[186:187], s[30:31], 0, v[172:173]
	s_add_i32 m0, s45, 0xe000
	s_nop 0
	global_load_lds_dwordx4 v[186:187], off
	s_waitcnt vmcnt(8)
	s_waitcnt lgkmcnt(0)
	s_barrier
	s_setprio 1
	v_mfma_scale_f32_16x16x128_f8f6f4 v[154:157], v[18:25], v[178:185], v[154:157], v193, v193 op_sel_hi:[0,0,0]
	v_mfma_scale_f32_16x16x128_f8f6f4 v[158:161], v[26:33], v[178:185], v[158:161], v193, v193 op_sel_hi:[0,0,0]
	v_mfma_scale_f32_16x16x128_f8f6f4 v[142:145], v[18:25], v[194:201], v[142:145], v193, v193 op_sel_hi:[0,0,0]
	v_mfma_scale_f32_16x16x128_f8f6f4 v[138:141], v[26:33], v[194:201], v[138:141], v193, v193 op_sel_hi:[0,0,0]
	v_mfma_scale_f32_16x16x128_f8f6f4 v[126:129], v[18:25], v[202:209], v[126:129], v193, v193 op_sel_hi:[0,0,0]
	v_mfma_scale_f32_16x16x128_f8f6f4 v[122:125], v[26:33], v[202:209], v[122:125], v193, v193 op_sel_hi:[0,0,0]
	v_mfma_scale_f32_16x16x128_f8f6f4 v[110:113], v[18:25], v[210:217], v[110:113], v193, v193 op_sel_hi:[0,0,0]
	v_mfma_scale_f32_16x16x128_f8f6f4 v[106:109], v[26:33], v[210:217], v[106:109], v193, v193 op_sel_hi:[0,0,0]
	v_mfma_scale_f32_16x16x128_f8f6f4 v[150:153], v[2:9], v[178:185], v[150:153], v193, v193 op_sel_hi:[0,0,0]
	v_mfma_scale_f32_16x16x128_f8f6f4 v[146:149], v[10:17], v[178:185], v[146:149], v193, v193 op_sel_hi:[0,0,0]
	v_mfma_scale_f32_16x16x128_f8f6f4 v[134:137], v[2:9], v[194:201], v[134:137], v193, v193 op_sel_hi:[0,0,0]
	v_mfma_scale_f32_16x16x128_f8f6f4 v[130:133], v[10:17], v[194:201], v[130:133], v193, v193 op_sel_hi:[0,0,0]
	v_mfma_scale_f32_16x16x128_f8f6f4 v[118:121], v[2:9], v[202:209], v[118:121], v193, v193 op_sel_hi:[0,0,0]
	v_mfma_scale_f32_16x16x128_f8f6f4 v[114:117], v[10:17], v[202:209], v[114:117], v193, v193 op_sel_hi:[0,0,0]
	v_mfma_scale_f32_16x16x128_f8f6f4 v[102:105], v[2:9], v[210:217], v[102:105], v193, v193 op_sel_hi:[0,0,0]
	v_mfma_scale_f32_16x16x128_f8f6f4 v[98:101], v[10:17], v[210:217], v[98:101], v193, v193 op_sel_hi:[0,0,0]
	s_setprio 0
	s_barrier
	s_add_i32 s68, s59, s42
	v_lshl_add_u64 v[178:179], s[36:37], 0, v[166:167]
	s_mov_b32 m0, s68
	ds_read_b128 v[194:197], v192 offset:16384
	ds_read_b128 v[198:201], v192 offset:17408
	ds_read_b128 v[202:205], v192 offset:18432
	ds_read_b128 v[206:209], v192 offset:19456
	ds_read_b128 v[210:213], v192 offset:20480
	ds_read_b128 v[214:217], v192 offset:21504
	ds_read_b128 v[218:221], v192 offset:22528
	ds_read_b128 v[222:225], v192 offset:23552
	global_load_lds_dwordx4 v[178:179], off
	s_add_i32 m0, s68, 0x2000
	v_lshl_add_u64 v[180:181], s[36:37], 0, v[162:163]
	s_add_u32 s36, s36, s4
	s_addc_u32 s37, s37, s5
	s_add_i32 s68, s60, s42
	global_load_lds_dwordx4 v[180:181], off
	v_lshl_add_u64 v[182:183], s[36:37], 0, v[166:167]
	s_mov_b32 m0, s68
	v_lshl_add_u64 v[184:185], s[36:37], 0, v[162:163]
	global_load_lds_dwordx4 v[182:183], off
	s_add_i32 m0, s68, 0x2000
	v_lshl_add_u64 v[186:187], s[34:35], 0, v[168:169]
	global_load_lds_dwordx4 v[184:185], off
	s_mov_b32 m0, s45
	v_lshl_add_u64 v[188:189], s[34:35], 0, v[164:165]
	global_load_lds_dwordx4 v[186:187], off
	s_mov_b32 m0, s46
	s_nop 0
	global_load_lds_dwordx4 v[188:189], off
	s_waitcnt vmcnt(8)
	s_waitcnt lgkmcnt(0)
	s_barrier
	s_setprio 1
	v_mfma_scale_f32_16x16x128_f8f6f4 v[94:97], v[18:25], v[194:201], v[94:97], v193, v193 op_sel_hi:[0,0,0]
	v_mfma_scale_f32_16x16x128_f8f6f4 v[90:93], v[26:33], v[194:201], v[90:93], v193, v193 op_sel_hi:[0,0,0]
	v_mfma_scale_f32_16x16x128_f8f6f4 v[78:81], v[18:25], v[202:209], v[78:81], v193, v193 op_sel_hi:[0,0,0]
	v_mfma_scale_f32_16x16x128_f8f6f4 v[74:77], v[26:33], v[202:209], v[74:77], v193, v193 op_sel_hi:[0,0,0]
	v_mfma_scale_f32_16x16x128_f8f6f4 v[62:65], v[18:25], v[210:217], v[62:65], v193, v193 op_sel_hi:[0,0,0]
	v_mfma_scale_f32_16x16x128_f8f6f4 v[58:61], v[26:33], v[210:217], v[58:61], v193, v193 op_sel_hi:[0,0,0]
	v_mfma_scale_f32_16x16x128_f8f6f4 v[46:49], v[18:25], v[218:225], v[46:49], v193, v193 op_sel_hi:[0,0,0]
	v_mfma_scale_f32_16x16x128_f8f6f4 v[42:45], v[26:33], v[218:225], v[42:45], v193, v193 op_sel_hi:[0,0,0]
	v_mfma_scale_f32_16x16x128_f8f6f4 v[86:89], v[2:9], v[194:201], v[86:89], v193, v193 op_sel_hi:[0,0,0]
	v_mfma_scale_f32_16x16x128_f8f6f4 v[82:85], v[10:17], v[194:201], v[82:85], v193, v193 op_sel_hi:[0,0,0]
	v_mfma_scale_f32_16x16x128_f8f6f4 v[70:73], v[2:9], v[202:209], v[70:73], v193, v193 op_sel_hi:[0,0,0]
	v_mfma_scale_f32_16x16x128_f8f6f4 v[66:69], v[10:17], v[202:209], v[66:69], v193, v193 op_sel_hi:[0,0,0]
	v_mfma_scale_f32_16x16x128_f8f6f4 v[54:57], v[2:9], v[210:217], v[54:57], v193, v193 op_sel_hi:[0,0,0]
	v_mfma_scale_f32_16x16x128_f8f6f4 v[50:53], v[10:17], v[210:217], v[50:53], v193, v193 op_sel_hi:[0,0,0]
	v_mfma_scale_f32_16x16x128_f8f6f4 v[38:41], v[2:9], v[218:225], v[38:41], v193, v193 op_sel_hi:[0,0,0]
	v_mfma_scale_f32_16x16x128_f8f6f4 v[34:37], v[10:17], v[218:225], v[34:37], v193, v193 op_sel_hi:[0,0,0]
	s_setprio 0
	s_barrier
	s_add_i32 s36, 0, 0x18000
	s_add_i32 s37, 0, 0x1c000
	v_add_u32_e32 v14, s36, v1
	v_add_u32_e32 v30, s37, v1
	ds_read_b128 v[2:5], v14
	ds_read_b128 v[6:9], v14 offset:1024
	ds_read_b128 v[10:13], v14 offset:2048
	ds_read_b128 v[14:17], v14 offset:3072
	ds_read_b128 v[18:21], v30
	ds_read_b128 v[22:25], v30 offset:1024
	ds_read_b128 v[26:29], v30 offset:2048
	ds_read_b128 v[30:33], v30 offset:3072
	s_add_u32 s34, s34, s4
	s_addc_u32 s35, s35, s5
	s_mov_b32 m0, s47
	v_lshl_add_u64 v[226:227], s[34:35], 0, v[168:169]
	ds_read_b128 v[194:197], v192 offset:32768
	ds_read_b128 v[198:201], v192 offset:33792
	ds_read_b128 v[202:205], v192 offset:34816
	ds_read_b128 v[206:209], v192 offset:35840
	ds_read_b128 v[210:213], v192 offset:36864
	ds_read_b128 v[214:217], v192 offset:37888
	ds_read_b128 v[218:221], v192 offset:38912
	ds_read_b128 v[222:225], v192 offset:39936
	global_load_lds_dwordx4 v[226:227], off
	v_lshl_add_u64 v[226:227], s[34:35], 0, v[164:165]
	s_mov_b32 m0, s48
	s_nop 0
	global_load_lds_dwordx4 v[226:227], off
	s_waitcnt vmcnt(8)
	s_waitcnt lgkmcnt(0)
	s_barrier
	s_setprio 1
	v_mfma_scale_f32_16x16x128_f8f6f4 v[154:157], v[2:9], v[194:201], v[154:157], v193, v193 op_sel_hi:[0,0,0]
	v_mfma_scale_f32_16x16x128_f8f6f4 v[158:161], v[10:17], v[194:201], v[158:161], v193, v193 op_sel_hi:[0,0,0]
	v_mfma_scale_f32_16x16x128_f8f6f4 v[142:145], v[2:9], v[202:209], v[142:145], v193, v193 op_sel_hi:[0,0,0]
	v_mfma_scale_f32_16x16x128_f8f6f4 v[138:141], v[10:17], v[202:209], v[138:141], v193, v193 op_sel_hi:[0,0,0]
	v_mfma_scale_f32_16x16x128_f8f6f4 v[126:129], v[2:9], v[210:217], v[126:129], v193, v193 op_sel_hi:[0,0,0]
	v_mfma_scale_f32_16x16x128_f8f6f4 v[122:125], v[10:17], v[210:217], v[122:125], v193, v193 op_sel_hi:[0,0,0]
	v_mfma_scale_f32_16x16x128_f8f6f4 v[110:113], v[2:9], v[218:225], v[110:113], v193, v193 op_sel_hi:[0,0,0]
	v_mfma_scale_f32_16x16x128_f8f6f4 v[106:109], v[10:17], v[218:225], v[106:109], v193, v193 op_sel_hi:[0,0,0]
	v_mfma_scale_f32_16x16x128_f8f6f4 v[150:153], v[18:25], v[194:201], v[150:153], v193, v193 op_sel_hi:[0,0,0]
	v_mfma_scale_f32_16x16x128_f8f6f4 v[146:149], v[26:33], v[194:201], v[146:149], v193, v193 op_sel_hi:[0,0,0]
	v_mfma_scale_f32_16x16x128_f8f6f4 v[134:137], v[18:25], v[202:209], v[134:137], v193, v193 op_sel_hi:[0,0,0]
	v_mfma_scale_f32_16x16x128_f8f6f4 v[130:133], v[26:33], v[202:209], v[130:133], v193, v193 op_sel_hi:[0,0,0]
	v_mfma_scale_f32_16x16x128_f8f6f4 v[118:121], v[18:25], v[210:217], v[118:121], v193, v193 op_sel_hi:[0,0,0]
	v_mfma_scale_f32_16x16x128_f8f6f4 v[114:117], v[26:33], v[210:217], v[114:117], v193, v193 op_sel_hi:[0,0,0]
	v_mfma_scale_f32_16x16x128_f8f6f4 v[102:105], v[18:25], v[218:225], v[102:105], v193, v193 op_sel_hi:[0,0,0]
	v_mfma_scale_f32_16x16x128_f8f6f4 v[98:101], v[26:33], v[218:225], v[98:101], v193, v193 op_sel_hi:[0,0,0]
	s_setprio 0
	s_barrier
	s_add_i32 s34, s36, s42
	v_lshl_add_u64 v[178:179], v[178:179], 0, s[12:13]
	s_mov_b32 m0, s34
	ds_read_b128 v[194:197], v192 offset:49152
	ds_read_b128 v[198:201], v192 offset:50176
	ds_read_b128 v[202:205], v192 offset:51200
	ds_read_b128 v[206:209], v192 offset:52224
	ds_read_b128 v[210:213], v192 offset:53248
	ds_read_b128 v[214:217], v192 offset:54272
	ds_read_b128 v[218:221], v192 offset:55296
	ds_read_b128 v[222:225], v192 offset:56320
	global_load_lds_dwordx4 v[178:179], off
	v_lshl_add_u64 v[178:179], v[180:181], 0, s[12:13]
	s_add_i32 m0, s34, 0x2000
	s_add_i32 s34, s37, s42
	global_load_lds_dwordx4 v[178:179], off
	v_lshl_add_u64 v[178:179], v[182:183], 0, s[12:13]
	s_mov_b32 m0, s34
	s_nop 0
	global_load_lds_dwordx4 v[178:179], off
	v_lshl_add_u64 v[178:179], v[184:185], 0, s[12:13]
	s_add_i32 m0, s34, 0x2000
	s_nop 0
	global_load_lds_dwordx4 v[178:179], off
	v_lshl_add_u64 v[178:179], v[186:187], 0, s[12:13]
	s_mov_b32 m0, s51
	s_nop 0
	global_load_lds_dwordx4 v[178:179], off
	v_lshl_add_u64 v[178:179], v[188:189], 0, s[12:13]
	s_mov_b32 m0, s52
	s_nop 0
	global_load_lds_dwordx4 v[178:179], off
	s_waitcnt vmcnt(8)
	s_waitcnt lgkmcnt(0)
	s_barrier
	s_setprio 1
	v_mfma_scale_f32_16x16x128_f8f6f4 v[94:97], v[2:9], v[194:201], v[94:97], v193, v193 op_sel_hi:[0,0,0]
	v_mfma_scale_f32_16x16x128_f8f6f4 v[90:93], v[10:17], v[194:201], v[90:93], v193, v193 op_sel_hi:[0,0,0]
	v_mfma_scale_f32_16x16x128_f8f6f4 v[78:81], v[2:9], v[202:209], v[78:81], v193, v193 op_sel_hi:[0,0,0]
	v_mfma_scale_f32_16x16x128_f8f6f4 v[74:77], v[10:17], v[202:209], v[74:77], v193, v193 op_sel_hi:[0,0,0]
	v_mfma_scale_f32_16x16x128_f8f6f4 v[62:65], v[2:9], v[210:217], v[62:65], v193, v193 op_sel_hi:[0,0,0]
	v_mfma_scale_f32_16x16x128_f8f6f4 v[58:61], v[10:17], v[210:217], v[58:61], v193, v193 op_sel_hi:[0,0,0]
	v_mfma_scale_f32_16x16x128_f8f6f4 v[46:49], v[2:9], v[218:225], v[46:49], v193, v193 op_sel_hi:[0,0,0]
	v_mfma_scale_f32_16x16x128_f8f6f4 v[42:45], v[10:17], v[218:225], v[42:45], v193, v193 op_sel_hi:[0,0,0]
	v_mfma_scale_f32_16x16x128_f8f6f4 v[86:89], v[18:25], v[194:201], v[86:89], v193, v193 op_sel_hi:[0,0,0]
	v_mfma_scale_f32_16x16x128_f8f6f4 v[82:85], v[26:33], v[194:201], v[82:85], v193, v193 op_sel_hi:[0,0,0]
	v_mfma_scale_f32_16x16x128_f8f6f4 v[70:73], v[18:25], v[202:209], v[70:73], v193, v193 op_sel_hi:[0,0,0]
	v_mfma_scale_f32_16x16x128_f8f6f4 v[66:69], v[26:33], v[202:209], v[66:69], v193, v193 op_sel_hi:[0,0,0]
	v_mfma_scale_f32_16x16x128_f8f6f4 v[54:57], v[18:25], v[210:217], v[54:57], v193, v193 op_sel_hi:[0,0,0]
	v_mfma_scale_f32_16x16x128_f8f6f4 v[50:53], v[26:33], v[210:217], v[50:53], v193, v193 op_sel_hi:[0,0,0]
	v_mfma_scale_f32_16x16x128_f8f6f4 v[38:41], v[18:25], v[218:225], v[38:41], v193, v193 op_sel_hi:[0,0,0]
	v_mfma_scale_f32_16x16x128_f8f6f4 v[34:37], v[26:33], v[218:225], v[34:37], v193, v193 op_sel_hi:[0,0,0]
	s_setprio 0
	s_barrier
	s_add_u32 s30, s30, 0x100
	s_addc_u32 s31, s31, 0
	s_add_u32 s65, s65, 0x100
	s_addc_u32 s66, s66, 0
	s_cmp_ge_i32 s67, s53
	s_mov_b32 s34, s67
	s_cbranch_scc0 .LBB0_2098
